# rstd_prologue: rowsq loads of up to 6 units batched before consuming (plus merge+in_proj epilogues)
# speedup vs baseline: 1.0181x; 1.0073x over previous
; #define LAS __attribute__((address_space(3)))
;     __device__ bool next(int i, Unit& u) const { Unit b; if (!so.next(i >> 2, b)) return false; const int sub = i & 3; u.pm = b.pm; u.pn = sub * 4 + b.pn; u.acol = sub * 512; u.ord = i; return true; }
;     __device__ bool next(int i, Unit& u) const {
;         const long L = (long)i * G + c; if (L >= nwg) return false;
;         int wgid = (int)L; { const int q = nwg / NXCD, r = nwg % NXCD, xcd = wgid % NXCD, off = wgid / NXCD; wgid = (xcd < r ? xcd * (q + 1) : r * (q + 1) + (xcd - r) * q) + off; }
;         const int nig = WGM * nN, gid = wgid / nig, fm = gid * WGM, gsz = (nM - fm) < WGM ? (nM - fm) : WGM;
;         u.pm = fm + ((wgid % nig) % gsz); u.pn = (wgid % nig) / gsz; u.acol = 0; u.ord = i; return true;
; template <class Sched> __device__ __forceinline__ void rstd_prologue(const Sched& S, const float* rowsq, LAS float* rst) {
;     int t_ = threadIdx.x; asm volatile("" : "+v"(t_));
;     pg8::Unit u;
;     for (int i = 0; i < 12 && S.next(i, u); ++i) if (t_ < 256) rst[i * 256 + t_] = pg8::row_rstd(rowsq, (size_t)u.pm * 256 + t_);
.LBB0_186:
	s_ashr_i32 s34, s94, 31
	s_ashr_i32 s48, s71, 31
	s_cmpk_lt_i32 s71, 0x580
	v_mov_b32_e32 v2, v216
	s_cselect_b64 s[24:25], -1, 0
	s_cmpk_gt_i32 s71, 0x57f
	s_cbranch_scc1 .LBB0_222
	v_readlane_b32 s2, v253, 37
	v_ashrrev_i32_e32 v3, 31, v2
	v_readlane_b32 s26, v251, 40
	v_lshl_add_u32 v0, v2, 2, s2
	v_cmp_gt_i32_e64 s[2:3], s91, v2
	v_lshlrev_b64 v[2:3], 6, v[2:3]
	v_readlane_b32 s27, v251, 41
	s_nop 1
	v_lshl_add_u64 v[2:3], s[26:27], 0, v[2:3]
	s_and_saveexec_b64 s[26:27], s[2:3]
	s_cbranch_execz .LBB0_189
	s_lshr_b32 s28, s48, 29
	s_add_i32 s28, s71, s28
	s_and_b32 s29, s28, -8
	s_sub_i32 s29, s71, s29
	s_cmp_lt_i32 s29, 0
	s_movk_i32 s30, 0xb1
	s_cselect_b32 s30, s30, 0xb0
	s_mul_i32 s29, s29, s30
	s_ashr_i32 s28, s28, 3
	s_add_i32 s29, s29, s28
	s_mul_hi_i32 s28, s29, 0x2e8ba2e9
	s_lshr_b32 s30, s28, 31
	s_ashr_i32 s28, s28, 5
	s_add_i32 s28, s28, s30
	s_lshl_b32 s30, s28, 3
	s_sub_i32 s31, 64, s30
	s_min_i32 s31, s31, 8
	s_abs_i32 s31, s31
	v_cvt_f32_u32_e32 v24, s31
	s_sub_i32 s36, 0, s31
	s_mulk_i32 s28, 0xb0
	s_sub_i32 s28, s29, s28
	v_rcp_iflag_f32_e32 v24, v24
	s_ashr_i32 s29, s28, 31
	s_abs_i32 s28, s28
	v_mul_f32_e32 v24, 0x4f7ffffe, v24
	v_cvt_u32_f32_e32 v24, v24
	s_nop 0
	v_readfirstlane_b32 s37, v24
	s_mul_i32 s36, s36, s37
	s_mul_hi_u32 s36, s37, s36
	s_add_i32 s37, s37, s36
	s_mul_hi_u32 s36, s28, s37
	s_mul_i32 s36, s36, s31
	s_sub_i32 s28, s28, s36
	s_sub_i32 s36, s28, s31
	s_cmp_ge_u32 s28, s31
	s_cselect_b32 s28, s36, s28
	s_sub_i32 s36, s28, s31
	s_cmp_ge_u32 s28, s31
	s_cselect_b32 s28, s36, s28
	s_xor_b32 s28, s28, s29
	s_sub_i32 s28, s28, s29
	s_add_i32 s28, s28, s30
	s_ashr_i32 s29, s28, 31
	s_lshl_b64 s[28:29], s[28:29], 14
	v_lshl_add_u64 v[36:37], v[2:3], 0, s[28:29]
	global_load_dwordx4 v[24:27], v[36:37], off
	global_load_dwordx4 v[28:31], v[36:37], off offset:16
	global_load_dwordx4 v[32:35], v[36:37], off offset:32
	s_nop 0
	global_load_dwordx4 v[36:39], v[36:37], off offset:48
.LBB0_189:
	s_or_b64 exec, exec, s[26:27]
	s_add_u32 s26, s94, s71
	s_addc_u32 s27, s34, s48
	v_cmp_gt_i64_e32 vcc, s[26:27], v[184:185]
	s_cbranch_vccnz .Lmy_rsa_0_c1
	s_and_saveexec_b64 s[28:29], s[2:3]
	s_cbranch_execz .LBB0_192
	s_ashr_i32 s30, s26, 31
	s_lshr_b32 s30, s30, 29
	s_add_i32 s30, s26, s30
	s_ashr_i32 s31, s30, 3
	s_and_b32 s30, s30, -8
	s_sub_i32 s30, s26, s30
	s_cmp_lt_i32 s30, 0
	s_movk_i32 s36, 0xb1
	s_cselect_b32 s36, s36, 0xb0
	s_mul_i32 s30, s30, s36
	s_add_i32 s30, s30, s31
	s_mul_hi_i32 s31, s30, 0x2e8ba2e9
	s_lshr_b32 s36, s31, 31
	s_ashr_i32 s31, s31, 5
	s_add_i32 s31, s31, s36
	s_lshl_b32 s36, s31, 3
	s_sub_i32 s37, 64, s36
	s_min_i32 s37, s37, 8
	s_abs_i32 s37, s37
	v_cvt_f32_u32_e32 v40, s37
	s_sub_i32 s38, 0, s37
	s_mulk_i32 s31, 0xb0
	s_sub_i32 s30, s30, s31
	v_rcp_iflag_f32_e32 v40, v40
	s_ashr_i32 s31, s30, 31
	s_abs_i32 s30, s30
	v_mul_f32_e32 v40, 0x4f7ffffe, v40
	v_cvt_u32_f32_e32 v40, v40
	s_nop 0
	v_readfirstlane_b32 s39, v40
	s_mul_i32 s38, s38, s39
	s_mul_hi_u32 s38, s39, s38
	s_add_i32 s39, s39, s38
	s_mul_hi_u32 s38, s30, s39
	s_mul_i32 s38, s38, s37
	s_sub_i32 s30, s30, s38
	s_sub_i32 s38, s30, s37
	s_cmp_ge_u32 s30, s37
	s_cselect_b32 s30, s38, s30
	s_sub_i32 s38, s30, s37
	s_cmp_ge_u32 s30, s37
	s_cselect_b32 s30, s38, s30
	s_xor_b32 s30, s30, s31
	s_sub_i32 s30, s30, s31
	s_add_i32 s30, s30, s36
	s_ashr_i32 s31, s30, 31
	s_lshl_b64 s[30:31], s[30:31], 14
	v_lshl_add_u64 v[52:53], v[2:3], 0, s[30:31]
	global_load_dwordx4 v[40:43], v[52:53], off
	global_load_dwordx4 v[44:47], v[52:53], off offset:16
	global_load_dwordx4 v[48:51], v[52:53], off offset:32
	s_nop 0
	global_load_dwordx4 v[52:55], v[52:53], off offset:48
.LBB0_192:
	s_or_b64 exec, exec, s[28:29]
	s_add_u32 s26, s26, s94
	s_addc_u32 s27, s27, s34
	v_cmp_gt_i64_e32 vcc, s[26:27], v[184:185]
	s_cbranch_vccnz .Lmy_rsa_0_c2
	s_and_saveexec_b64 s[28:29], s[2:3]
	s_cbranch_execz .LBB0_195
	s_ashr_i32 s30, s26, 31
	s_lshr_b32 s30, s30, 29
	s_add_i32 s30, s26, s30
	s_ashr_i32 s31, s30, 3
	s_and_b32 s30, s30, -8
	s_sub_i32 s30, s26, s30
	s_cmp_lt_i32 s30, 0
	s_movk_i32 s36, 0xb1
	s_cselect_b32 s36, s36, 0xb0
	s_mul_i32 s30, s30, s36
	s_add_i32 s30, s30, s31
	s_mul_hi_i32 s31, s30, 0x2e8ba2e9
	s_lshr_b32 s36, s31, 31
	s_ashr_i32 s31, s31, 5
	s_add_i32 s31, s31, s36
	s_lshl_b32 s36, s31, 3
	s_sub_i32 s37, 64, s36
	s_min_i32 s37, s37, 8
	s_abs_i32 s37, s37
	v_cvt_f32_u32_e32 v56, s37
	s_sub_i32 s38, 0, s37
	s_mulk_i32 s31, 0xb0
	s_sub_i32 s30, s30, s31
	v_rcp_iflag_f32_e32 v56, v56
	s_ashr_i32 s31, s30, 31
	s_abs_i32 s30, s30
	v_mul_f32_e32 v56, 0x4f7ffffe, v56
	v_cvt_u32_f32_e32 v56, v56
	s_nop 0
	v_readfirstlane_b32 s39, v56
	s_mul_i32 s38, s38, s39
	s_mul_hi_u32 s38, s39, s38
	s_add_i32 s39, s39, s38
	s_mul_hi_u32 s38, s30, s39
	s_mul_i32 s38, s38, s37
	s_sub_i32 s30, s30, s38
	s_sub_i32 s38, s30, s37
	s_cmp_ge_u32 s30, s37
	s_cselect_b32 s30, s38, s30
	s_sub_i32 s38, s30, s37
	s_cmp_ge_u32 s30, s37
	s_cselect_b32 s30, s38, s30
	s_xor_b32 s30, s30, s31
	s_sub_i32 s30, s30, s31
	s_add_i32 s30, s30, s36
	s_ashr_i32 s31, s30, 31
	s_lshl_b64 s[30:31], s[30:31], 14
	v_lshl_add_u64 v[68:69], v[2:3], 0, s[30:31]
	global_load_dwordx4 v[56:59], v[68:69], off
	global_load_dwordx4 v[60:63], v[68:69], off offset:16
	global_load_dwordx4 v[64:67], v[68:69], off offset:32
	s_nop 0
	global_load_dwordx4 v[68:71], v[68:69], off offset:48
;     __device__ bool next(int i, Unit& u) const { Unit b; if (!so.next(i >> 2, b)) return false; const int sub = i & 3; u.pm = b.pm; u.pn = sub * 4 + b.pn; u.acol = sub * 512; u.ord = i; return true; }
;     __device__ bool next(int i, Unit& u) const {
;         const long L = (long)i * G + c; if (L >= nwg) return false;
;         int wgid = (int)L; { const int q = nwg / NXCD, r = nwg % NXCD, xcd = wgid % NXCD, off = wgid / NXCD; wgid = (xcd < r ? xcd * (q + 1) : r * (q + 1) + (xcd - r) * q) + off; }
;         const int nig = WGM * nN, gid = wgid / nig, fm = gid * WGM, gsz = (nM - fm) < WGM ? (nM - fm) : WGM;
;         u.pm = fm + ((wgid % nig) % gsz); u.pn = (wgid % nig) / gsz; u.acol = 0; u.ord = i; return true;
; __device__ __forceinline__ float row_rstd(const float* rowsq, size_t row) {
;     const f32x4* q = (const f32x4*)(rowsq + row * 16); const f32x4 a = q[0], b = q[1], c = q[2], d = q[3];
;     const float s = ((a[0] + a[1]) + (a[2] + a[3])) + ((b[0] + b[1]) + (b[2] + b[3])) + ((c[0] + c[1]) + (c[2] + c[3])) + ((d[0] + d[1]) + (d[2] + d[3]));
;     return rsqrtf(s * (1.f / DM) + EPS);
.LBB0_195:
	s_or_b64 exec, exec, s[28:29]
	s_add_u32 s26, s26, s94
	s_addc_u32 s27, s27, s34
	v_cmp_gt_i64_e32 vcc, s[26:27], v[184:185]
	s_cbranch_vccnz .Lmy_rsa_0_c3
	s_and_saveexec_b64 s[28:29], s[2:3]
	s_cbranch_execz .LBB0_198
	s_ashr_i32 s30, s26, 31
	s_lshr_b32 s30, s30, 29
	s_add_i32 s30, s26, s30
	s_ashr_i32 s31, s30, 3
	s_and_b32 s30, s30, -8
	s_sub_i32 s30, s26, s30
	s_cmp_lt_i32 s30, 0
	s_movk_i32 s36, 0xb1
	s_cselect_b32 s36, s36, 0xb0
	s_mul_i32 s30, s30, s36
	s_add_i32 s30, s30, s31
	s_mul_hi_i32 s31, s30, 0x2e8ba2e9
	s_lshr_b32 s36, s31, 31
	s_ashr_i32 s31, s31, 5
	s_add_i32 s31, s31, s36
	s_lshl_b32 s36, s31, 3
	s_sub_i32 s37, 64, s36
	s_min_i32 s37, s37, 8
	s_abs_i32 s37, s37
	v_cvt_f32_u32_e32 v72, s37
	s_sub_i32 s38, 0, s37
	s_mulk_i32 s31, 0xb0
	s_sub_i32 s30, s30, s31
	v_rcp_iflag_f32_e32 v72, v72
	s_ashr_i32 s31, s30, 31
	s_abs_i32 s30, s30
	v_mul_f32_e32 v72, 0x4f7ffffe, v72
	v_cvt_u32_f32_e32 v72, v72
	s_nop 0
	v_readfirstlane_b32 s39, v72
	s_mul_i32 s38, s38, s39
	s_mul_hi_u32 s38, s39, s38
	s_add_i32 s39, s39, s38
	s_mul_hi_u32 s38, s30, s39
	s_mul_i32 s38, s38, s37
	s_sub_i32 s30, s30, s38
	s_sub_i32 s38, s30, s37
	s_cmp_ge_u32 s30, s37
	s_cselect_b32 s30, s38, s30
	s_sub_i32 s38, s30, s37
	s_cmp_ge_u32 s30, s37
	s_cselect_b32 s30, s38, s30
	s_xor_b32 s30, s30, s31
	s_sub_i32 s30, s30, s31
	s_add_i32 s30, s30, s36
	s_ashr_i32 s31, s30, 31
	s_lshl_b64 s[30:31], s[30:31], 14
	v_lshl_add_u64 v[84:85], v[2:3], 0, s[30:31]
	global_load_dwordx4 v[72:75], v[84:85], off
	global_load_dwordx4 v[76:79], v[84:85], off offset:16
	global_load_dwordx4 v[80:83], v[84:85], off offset:32
	s_nop 0
	global_load_dwordx4 v[84:87], v[84:85], off offset:48
.LBB0_198:
	s_or_b64 exec, exec, s[28:29]
	s_add_u32 s26, s26, s94
	s_addc_u32 s27, s27, s34
	v_cmp_gt_i64_e32 vcc, s[26:27], v[184:185]
	s_cbranch_vccnz .Lmy_rsa_0_c4
	s_and_saveexec_b64 s[28:29], s[2:3]
	s_cbranch_execz .LBB0_201
	s_ashr_i32 s30, s26, 31
	s_lshr_b32 s30, s30, 29
	s_add_i32 s30, s26, s30
	s_ashr_i32 s31, s30, 3
	s_and_b32 s30, s30, -8
	s_sub_i32 s30, s26, s30
	s_cmp_lt_i32 s30, 0
	s_movk_i32 s36, 0xb1
	s_cselect_b32 s36, s36, 0xb0
	s_mul_i32 s30, s30, s36
	s_add_i32 s30, s30, s31
	s_mul_hi_i32 s31, s30, 0x2e8ba2e9
	s_lshr_b32 s36, s31, 31
	s_ashr_i32 s31, s31, 5
	s_add_i32 s31, s31, s36
	s_lshl_b32 s36, s31, 3
	s_sub_i32 s37, 64, s36
	s_min_i32 s37, s37, 8
	s_abs_i32 s37, s37
	v_cvt_f32_u32_e32 v88, s37
	s_sub_i32 s38, 0, s37
	s_mulk_i32 s31, 0xb0
	s_sub_i32 s30, s30, s31
	v_rcp_iflag_f32_e32 v88, v88
	s_ashr_i32 s31, s30, 31
	s_abs_i32 s30, s30
	v_mul_f32_e32 v88, 0x4f7ffffe, v88
	v_cvt_u32_f32_e32 v88, v88
	s_nop 0
	v_readfirstlane_b32 s39, v88
	s_mul_i32 s38, s38, s39
	s_mul_hi_u32 s38, s39, s38
	s_add_i32 s39, s39, s38
	s_mul_hi_u32 s38, s30, s39
	s_mul_i32 s38, s38, s37
	s_sub_i32 s30, s30, s38
	s_sub_i32 s38, s30, s37
	s_cmp_ge_u32 s30, s37
	s_cselect_b32 s30, s38, s30
	s_sub_i32 s38, s30, s37
	s_cmp_ge_u32 s30, s37
	s_cselect_b32 s30, s38, s30
	s_xor_b32 s30, s30, s31
	s_sub_i32 s30, s30, s31
	s_add_i32 s30, s30, s36
	s_ashr_i32 s31, s30, 31
	s_lshl_b64 s[30:31], s[30:31], 14
	v_lshl_add_u64 v[100:101], v[2:3], 0, s[30:31]
	global_load_dwordx4 v[88:91], v[100:101], off
	global_load_dwordx4 v[92:95], v[100:101], off offset:16
	global_load_dwordx4 v[96:99], v[100:101], off offset:32
	s_nop 0
	global_load_dwordx4 v[100:103], v[100:101], off offset:48
.LBB0_201:
	s_or_b64 exec, exec, s[28:29]
	s_add_u32 s26, s26, s94
	s_addc_u32 s27, s27, s34
	v_cmp_gt_i64_e32 vcc, s[26:27], v[184:185]
	s_cbranch_vccnz .Lmy_rsa_0_c5
	s_and_saveexec_b64 s[28:29], s[2:3]
	s_cbranch_execz .LBB0_204
	s_ashr_i32 s30, s26, 31
	s_lshr_b32 s30, s30, 29
	s_add_i32 s30, s26, s30
	s_ashr_i32 s31, s30, 3
	s_and_b32 s30, s30, -8
	s_sub_i32 s30, s26, s30
	s_cmp_lt_i32 s30, 0
	s_movk_i32 s36, 0xb1
	s_cselect_b32 s36, s36, 0xb0
	s_mul_i32 s30, s30, s36
	s_add_i32 s30, s30, s31
	s_mul_hi_i32 s31, s30, 0x2e8ba2e9
	s_lshr_b32 s36, s31, 31
	s_ashr_i32 s31, s31, 5
	s_add_i32 s31, s31, s36
	s_lshl_b32 s36, s31, 3
	s_sub_i32 s37, 64, s36
	s_min_i32 s37, s37, 8
	s_abs_i32 s37, s37
	v_cvt_f32_u32_e32 v104, s37
	s_sub_i32 s38, 0, s37
	s_mulk_i32 s31, 0xb0
	s_sub_i32 s30, s30, s31
	v_rcp_iflag_f32_e32 v104, v104
	s_ashr_i32 s31, s30, 31
	s_abs_i32 s30, s30
	v_mul_f32_e32 v104, 0x4f7ffffe, v104
	v_cvt_u32_f32_e32 v104, v104
	s_nop 0
	v_readfirstlane_b32 s39, v104
	s_mul_i32 s38, s38, s39
	s_mul_hi_u32 s38, s39, s38
	s_add_i32 s39, s39, s38
	s_mul_hi_u32 s38, s30, s39
	s_mul_i32 s38, s38, s37
	s_sub_i32 s30, s30, s38
	s_sub_i32 s38, s30, s37
	s_cmp_ge_u32 s30, s37
	s_cselect_b32 s30, s38, s30
	s_sub_i32 s38, s30, s37
	s_cmp_ge_u32 s30, s37
	s_cselect_b32 s30, s38, s30
	s_xor_b32 s30, s30, s31
	s_sub_i32 s30, s30, s31
	s_add_i32 s30, s30, s36
	s_ashr_i32 s31, s30, 31
	s_lshl_b64 s[30:31], s[30:31], 14
	v_lshl_add_u64 v[116:117], v[2:3], 0, s[30:31]
	global_load_dwordx4 v[104:107], v[116:117], off
	global_load_dwordx4 v[108:111], v[116:117], off offset:16
	global_load_dwordx4 v[112:115], v[116:117], off offset:32
	s_nop 0
	global_load_dwordx4 v[116:119], v[116:117], off offset:48
	s_or_b64 exec, exec, s[28:29]
.Lmy_rsa_0_c6:
	s_and_saveexec_b64 s[28:29], s[2:3]
	s_cbranch_execz .Lmy_rsa_0_s5
	s_mov_b32 s30, 0x800000
	s_waitcnt vmcnt(3)
	v_mov_b32_e32 v20, v105
	v_mov_b32_e32 v21, v106
	v_mov_b32_e32 v105, v107
	s_waitcnt vmcnt(2)
	v_mov_b32_e32 v106, v109
	v_mov_b32_e32 v107, v110
	v_mov_b32_e32 v109, v111
	v_pk_add_f32 v[104:105], v[20:21], v[104:105]
	v_pk_add_f32 v[106:107], v[106:107], v[108:109]
	v_pk_add_f32 v[104:105], v[104:105], v[104:105] op_sel:[0,1] op_sel_hi:[1,0]
	v_pk_add_f32 v[106:107], v[106:107], v[106:107] op_sel:[0,1] op_sel_hi:[1,0]
	s_waitcnt vmcnt(1)
	v_add_f32_e32 v110, v112, v113
	v_add_f32_e32 v112, v114, v115
	s_waitcnt vmcnt(0)
	v_mov_b32_e32 v111, v118
	v_mov_b32_e32 v113, v119
	v_mov_b32_e32 v105, v116
	v_mov_b32_e32 v107, v117
	v_pk_add_f32 v[108:109], v[110:111], v[112:113]
	v_pk_add_f32 v[104:105], v[104:105], v[106:107]
	s_nop 0
	v_pk_add_f32 v[104:105], v[104:105], v[108:109]
	s_nop 0
	v_add_f32_e32 v104, v104, v105
	v_fmamk_f32 v104, v104, 0x3a800000, v218
	v_mul_f32_e32 v105, 0x4b800000, v104
	v_cmp_gt_f32_e32 vcc, s30, v104
	s_nop 1
	v_cndmask_b32_e32 v104, v104, v105, vcc
	v_rsq_f32_e32 v104, v104
	s_nop 0
	v_mul_f32_e32 v105, 0x45800000, v104
	v_cndmask_b32_e32 v104, v104, v105, vcc
	ds_write_b32 v0, v104 offset:5120

;     __device__ bool next(int i, Unit& u) const { Unit b; if (!so.next(i >> 2, b)) return false; const int sub = i & 3; u.pm = b.pm; u.pn = sub * 4 + b.pn; u.acol = sub * 512; u.ord = i; return true; }
; __device__ __forceinline__ float row_rstd(const float* rowsq, size_t row) {
;     const f32x4* q = (const f32x4*)(rowsq + row * 16); const f32x4 a = q[0], b = q[1], c = q[2], d = q[3];
;     const float s = ((a[0] + a[1]) + (a[2] + a[3])) + ((b[0] + b[1]) + (b[2] + b[3])) + ((c[0] + c[1]) + (c[2] + c[3])) + ((d[0] + d[1]) + (d[2] + d[3]));
;     return rsqrtf(s * (1.f / DM) + EPS);
; template <class Sched> __device__ __forceinline__ void rstd_prologue(const Sched& S, const float* rowsq, LAS float* rst) {
;     ...
;     for (int i = 0; i < 12 && S.next(i, u); ++i) if (t_ < 256) rst[i * 256 + t_] = pg8::row_rstd(rowsq, (size_t)u.pm * 256 + t_);
.Lmy_rsa_0_c5:
	s_and_saveexec_b64 s[28:29], s[2:3]
	s_cbranch_execz .Lmy_rsa_0_s4
	s_mov_b32 s30, 0x800000
	s_waitcnt vmcnt(3)
	v_mov_b32_e32 v20, v89
	v_mov_b32_e32 v21, v90
	v_mov_b32_e32 v89, v91
	s_waitcnt vmcnt(2)
	v_mov_b32_e32 v90, v93
	v_mov_b32_e32 v91, v94
	v_mov_b32_e32 v93, v95
	v_pk_add_f32 v[88:89], v[20:21], v[88:89]
	v_pk_add_f32 v[90:91], v[90:91], v[92:93]
	v_pk_add_f32 v[88:89], v[88:89], v[88:89] op_sel:[0,1] op_sel_hi:[1,0]
	v_pk_add_f32 v[90:91], v[90:91], v[90:91] op_sel:[0,1] op_sel_hi:[1,0]
	s_waitcnt vmcnt(1)
	v_add_f32_e32 v94, v96, v97
	v_add_f32_e32 v96, v98, v99
	s_waitcnt vmcnt(0)
	v_mov_b32_e32 v95, v102
	v_mov_b32_e32 v97, v103
	v_mov_b32_e32 v89, v100
	v_mov_b32_e32 v91, v101
	v_pk_add_f32 v[92:93], v[94:95], v[96:97]
	v_pk_add_f32 v[88:89], v[88:89], v[90:91]
	s_nop 0
	v_pk_add_f32 v[88:89], v[88:89], v[92:93]
	s_nop 0
	v_add_f32_e32 v88, v88, v89
	v_fmamk_f32 v88, v88, 0x3a800000, v218
	v_mul_f32_e32 v89, 0x4b800000, v88
	v_cmp_gt_f32_e32 vcc, s30, v88
	s_nop 1
	v_cndmask_b32_e32 v88, v88, v89, vcc
	v_rsq_f32_e32 v88, v88
	s_nop 0
	v_mul_f32_e32 v89, 0x45800000, v88
	v_cndmask_b32_e32 v88, v88, v89, vcc
	ds_write_b32 v0, v88 offset:4096

;     __device__ bool next(int i, Unit& u) const { Unit b; if (!so.next(i >> 2, b)) return false; const int sub = i & 3; u.pm = b.pm; u.pn = sub * 4 + b.pn; u.acol = sub * 512; u.ord = i; return true; }
; __device__ __forceinline__ float row_rstd(const float* rowsq, size_t row) {
;     const f32x4* q = (const f32x4*)(rowsq + row * 16); const f32x4 a = q[0], b = q[1], c = q[2], d = q[3];
;     const float s = ((a[0] + a[1]) + (a[2] + a[3])) + ((b[0] + b[1]) + (b[2] + b[3])) + ((c[0] + c[1]) + (c[2] + c[3])) + ((d[0] + d[1]) + (d[2] + d[3]));
;     return rsqrtf(s * (1.f / DM) + EPS);
; template <class Sched> __device__ __forceinline__ void rstd_prologue(const Sched& S, const float* rowsq, LAS float* rst) {
;     ...
;     for (int i = 0; i < 12 && S.next(i, u); ++i) if (t_ < 256) rst[i * 256 + t_] = pg8::row_rstd(rowsq, (size_t)u.pm * 256 + t_);
.Lmy_rsa_0_c4:
	s_and_saveexec_b64 s[28:29], s[2:3]
	s_cbranch_execz .Lmy_rsa_0_s3
	s_mov_b32 s30, 0x800000
	s_waitcnt vmcnt(3)
	v_mov_b32_e32 v20, v73
	v_mov_b32_e32 v21, v74
	v_mov_b32_e32 v73, v75
	s_waitcnt vmcnt(2)
	v_mov_b32_e32 v74, v77
	v_mov_b32_e32 v75, v78
	v_mov_b32_e32 v77, v79
	v_pk_add_f32 v[72:73], v[20:21], v[72:73]
	v_pk_add_f32 v[74:75], v[74:75], v[76:77]
	v_pk_add_f32 v[72:73], v[72:73], v[72:73] op_sel:[0,1] op_sel_hi:[1,0]
	v_pk_add_f32 v[74:75], v[74:75], v[74:75] op_sel:[0,1] op_sel_hi:[1,0]
	s_waitcnt vmcnt(1)
	v_add_f32_e32 v78, v80, v81
	v_add_f32_e32 v80, v82, v83
	s_waitcnt vmcnt(0)
	v_mov_b32_e32 v79, v86
	v_mov_b32_e32 v81, v87
	v_mov_b32_e32 v73, v84
	v_mov_b32_e32 v75, v85
	v_pk_add_f32 v[76:77], v[78:79], v[80:81]
	v_pk_add_f32 v[72:73], v[72:73], v[74:75]
	s_nop 0
	v_pk_add_f32 v[72:73], v[72:73], v[76:77]
	s_nop 0
	v_add_f32_e32 v72, v72, v73
	v_fmamk_f32 v72, v72, 0x3a800000, v218
	v_mul_f32_e32 v73, 0x4b800000, v72
	v_cmp_gt_f32_e32 vcc, s30, v72
	s_nop 1
	v_cndmask_b32_e32 v72, v72, v73, vcc
	v_rsq_f32_e32 v72, v72
	s_nop 0
	v_mul_f32_e32 v73, 0x45800000, v72
	v_cndmask_b32_e32 v72, v72, v73, vcc
	ds_write_b32 v0, v72 offset:3072

;     __device__ bool next(int i, Unit& u) const { Unit b; if (!so.next(i >> 2, b)) return false; const int sub = i & 3; u.pm = b.pm; u.pn = sub * 4 + b.pn; u.acol = sub * 512; u.ord = i; return true; }
; __device__ __forceinline__ float row_rstd(const float* rowsq, size_t row) {
;     const f32x4* q = (const f32x4*)(rowsq + row * 16); const f32x4 a = q[0], b = q[1], c = q[2], d = q[3];
;     const float s = ((a[0] + a[1]) + (a[2] + a[3])) + ((b[0] + b[1]) + (b[2] + b[3])) + ((c[0] + c[1]) + (c[2] + c[3])) + ((d[0] + d[1]) + (d[2] + d[3]));
;     return rsqrtf(s * (1.f / DM) + EPS);
; template <class Sched> __device__ __forceinline__ void rstd_prologue(const Sched& S, const float* rowsq, LAS float* rst) {
;     ...
;     for (int i = 0; i < 12 && S.next(i, u); ++i) if (t_ < 256) rst[i * 256 + t_] = pg8::row_rstd(rowsq, (size_t)u.pm * 256 + t_);
.Lmy_rsa_0_c3:
	s_and_saveexec_b64 s[28:29], s[2:3]
	s_cbranch_execz .Lmy_rsa_0_s2
	s_mov_b32 s30, 0x800000
	s_waitcnt vmcnt(3)
	v_mov_b32_e32 v20, v57
	v_mov_b32_e32 v21, v58
	v_mov_b32_e32 v57, v59
	s_waitcnt vmcnt(2)
	v_mov_b32_e32 v58, v61
	v_mov_b32_e32 v59, v62
	v_mov_b32_e32 v61, v63
	v_pk_add_f32 v[56:57], v[20:21], v[56:57]
	v_pk_add_f32 v[58:59], v[58:59], v[60:61]
	v_pk_add_f32 v[56:57], v[56:57], v[56:57] op_sel:[0,1] op_sel_hi:[1,0]
	v_pk_add_f32 v[58:59], v[58:59], v[58:59] op_sel:[0,1] op_sel_hi:[1,0]
	s_waitcnt vmcnt(1)
	v_add_f32_e32 v62, v64, v65
	v_add_f32_e32 v64, v66, v67
	s_waitcnt vmcnt(0)
	v_mov_b32_e32 v63, v70
	v_mov_b32_e32 v65, v71
	v_mov_b32_e32 v57, v68
	v_mov_b32_e32 v59, v69
	v_pk_add_f32 v[60:61], v[62:63], v[64:65]
	v_pk_add_f32 v[56:57], v[56:57], v[58:59]
	s_nop 0
	v_pk_add_f32 v[56:57], v[56:57], v[60:61]
	s_nop 0
	v_add_f32_e32 v56, v56, v57
	v_fmamk_f32 v56, v56, 0x3a800000, v218
	v_mul_f32_e32 v57, 0x4b800000, v56
	v_cmp_gt_f32_e32 vcc, s30, v56
	s_nop 1
	v_cndmask_b32_e32 v56, v56, v57, vcc
	v_rsq_f32_e32 v56, v56
	s_nop 0
	v_mul_f32_e32 v57, 0x45800000, v56
	v_cndmask_b32_e32 v56, v56, v57, vcc
	ds_write_b32 v0, v56 offset:2048

;     __device__ bool next(int i, Unit& u) const { Unit b; if (!so.next(i >> 2, b)) return false; const int sub = i & 3; u.pm = b.pm; u.pn = sub * 4 + b.pn; u.acol = sub * 512; u.ord = i; return true; }
; __device__ __forceinline__ float row_rstd(const float* rowsq, size_t row) {
;     const f32x4* q = (const f32x4*)(rowsq + row * 16); const f32x4 a = q[0], b = q[1], c = q[2], d = q[3];
;     const float s = ((a[0] + a[1]) + (a[2] + a[3])) + ((b[0] + b[1]) + (b[2] + b[3])) + ((c[0] + c[1]) + (c[2] + c[3])) + ((d[0] + d[1]) + (d[2] + d[3]));
;     return rsqrtf(s * (1.f / DM) + EPS);
; template <class Sched> __device__ __forceinline__ void rstd_prologue(const Sched& S, const float* rowsq, LAS float* rst) {
;     ...
;     for (int i = 0; i < 12 && S.next(i, u); ++i) if (t_ < 256) rst[i * 256 + t_] = pg8::row_rstd(rowsq, (size_t)u.pm * 256 + t_);
.Lmy_rsa_0_c2:
	s_and_saveexec_b64 s[28:29], s[2:3]
	s_cbranch_execz .Lmy_rsa_0_s1
	s_mov_b32 s30, 0x800000
	s_waitcnt vmcnt(3)
	v_mov_b32_e32 v20, v41
	v_mov_b32_e32 v21, v42
	v_mov_b32_e32 v41, v43
	s_waitcnt vmcnt(2)
	v_mov_b32_e32 v42, v45
	v_mov_b32_e32 v43, v46
	v_mov_b32_e32 v45, v47
	v_pk_add_f32 v[40:41], v[20:21], v[40:41]
	v_pk_add_f32 v[42:43], v[42:43], v[44:45]
	v_pk_add_f32 v[40:41], v[40:41], v[40:41] op_sel:[0,1] op_sel_hi:[1,0]
	v_pk_add_f32 v[42:43], v[42:43], v[42:43] op_sel:[0,1] op_sel_hi:[1,0]
	s_waitcnt vmcnt(1)
	v_add_f32_e32 v46, v48, v49
	v_add_f32_e32 v48, v50, v51
	s_waitcnt vmcnt(0)
	v_mov_b32_e32 v47, v54
	v_mov_b32_e32 v49, v55
	v_mov_b32_e32 v41, v52
	v_mov_b32_e32 v43, v53
	v_pk_add_f32 v[44:45], v[46:47], v[48:49]
	v_pk_add_f32 v[40:41], v[40:41], v[42:43]
	s_nop 0
	v_pk_add_f32 v[40:41], v[40:41], v[44:45]
	s_nop 0
	v_add_f32_e32 v40, v40, v41
	v_fmamk_f32 v40, v40, 0x3a800000, v218
	v_mul_f32_e32 v41, 0x4b800000, v40
	v_cmp_gt_f32_e32 vcc, s30, v40
	s_nop 1
	v_cndmask_b32_e32 v40, v40, v41, vcc
	v_rsq_f32_e32 v40, v40
	s_nop 0
	v_mul_f32_e32 v41, 0x45800000, v40
	v_cndmask_b32_e32 v40, v40, v41, vcc
	ds_write_b32 v0, v40 offset:1024

;     __device__ bool next(int i, Unit& u) const { Unit b; if (!so.next(i >> 2, b)) return false; const int sub = i & 3; u.pm = b.pm; u.pn = sub * 4 + b.pn; u.acol = sub * 512; u.ord = i; return true; }
; __device__ __forceinline__ float row_rstd(const float* rowsq, size_t row) {
;     const f32x4* q = (const f32x4*)(rowsq + row * 16); const f32x4 a = q[0], b = q[1], c = q[2], d = q[3];
;     const float s = ((a[0] + a[1]) + (a[2] + a[3])) + ((b[0] + b[1]) + (b[2] + b[3])) + ((c[0] + c[1]) + (c[2] + c[3])) + ((d[0] + d[1]) + (d[2] + d[3]));
;     return rsqrtf(s * (1.f / DM) + EPS);
; template <class Sched> __device__ __forceinline__ void rstd_prologue(const Sched& S, const float* rowsq, LAS float* rst) {
;     ...
;     for (int i = 0; i < 12 && S.next(i, u); ++i) if (t_ < 256) rst[i * 256 + t_] = pg8::row_rstd(rowsq, (size_t)u.pm * 256 + t_);
.Lmy_rsa_0_c1:
	s_and_saveexec_b64 s[28:29], s[2:3]
	s_cbranch_execz .Lmy_rsa_0_s0
	s_mov_b32 s28, 0x800000
	s_waitcnt vmcnt(3)
	v_mov_b32_e32 v20, v25
	v_mov_b32_e32 v21, v26
	v_mov_b32_e32 v25, v27
	s_waitcnt vmcnt(2)
	v_mov_b32_e32 v26, v29
	v_mov_b32_e32 v27, v30
	v_mov_b32_e32 v29, v31
	v_pk_add_f32 v[24:25], v[20:21], v[24:25]
	v_pk_add_f32 v[26:27], v[26:27], v[28:29]
	v_pk_add_f32 v[24:25], v[24:25], v[24:25] op_sel:[0,1] op_sel_hi:[1,0]
	v_pk_add_f32 v[26:27], v[26:27], v[26:27] op_sel:[0,1] op_sel_hi:[1,0]
	s_waitcnt vmcnt(1)
	v_add_f32_e32 v30, v32, v33
	v_add_f32_e32 v32, v34, v35
	s_waitcnt vmcnt(0)
	v_mov_b32_e32 v31, v38
	v_mov_b32_e32 v33, v39
	v_mov_b32_e32 v25, v36
	v_mov_b32_e32 v27, v37
	v_pk_add_f32 v[28:29], v[30:31], v[32:33]
	v_pk_add_f32 v[24:25], v[24:25], v[26:27]
	s_nop 0
	v_pk_add_f32 v[24:25], v[24:25], v[28:29]
	s_nop 0
	v_add_f32_e32 v24, v24, v25
	v_fmamk_f32 v24, v24, 0x3a800000, v218
	v_mul_f32_e32 v25, 0x4b800000, v24
	v_cmp_gt_f32_e32 vcc, s28, v24
	s_nop 1
	v_cndmask_b32_e32 v24, v24, v25, vcc
	v_rsq_f32_e32 v24, v24
	s_nop 0
	v_mul_f32_e32 v25, 0x45800000, v24
	v_cndmask_b32_e32 v24, v24, v25, vcc
	ds_write_b32 v0, v24
.Lmy_rsa_0_s0:
	s_or_b64 exec, exec, s[28:29]
.LBB0_204:
	s_or_b64 exec, exec, s[28:29]
	s_add_u32 s26, s26, s94
	s_addc_u32 s27, s27, s34
	v_cmp_gt_i64_e32 vcc, s[26:27], v[184:185]
	s_cbranch_vccnz .LBB0_222
	s_and_saveexec_b64 s[28:29], s[2:3]
	s_cbranch_execz .LBB0_207
	s_ashr_i32 s30, s26, 31
	s_lshr_b32 s30, s30, 29
	s_add_i32 s30, s26, s30
	s_ashr_i32 s31, s30, 3
	s_and_b32 s30, s30, -8
	s_sub_i32 s30, s26, s30
	s_cmp_lt_i32 s30, 0
	s_movk_i32 s36, 0xb1
	s_cselect_b32 s36, s36, 0xb0
	s_mul_i32 s30, s30, s36
	s_add_i32 s30, s30, s31
	s_mul_hi_i32 s31, s30, 0x2e8ba2e9
	s_lshr_b32 s36, s31, 31
	s_ashr_i32 s31, s31, 5
	s_add_i32 s31, s31, s36
	s_lshl_b32 s36, s31, 3
	s_sub_i32 s37, 64, s36
	s_min_i32 s37, s37, 8
	s_abs_i32 s37, s37
	v_cvt_f32_u32_e32 v4, s37
	s_sub_i32 s38, 0, s37
	s_mulk_i32 s31, 0xb0
	s_sub_i32 s30, s30, s31
	v_rcp_iflag_f32_e32 v4, v4
	s_ashr_i32 s31, s30, 31
	s_abs_i32 s30, s30
	v_mul_f32_e32 v4, 0x4f7ffffe, v4
	v_cvt_u32_f32_e32 v4, v4
	s_nop 0
	v_readfirstlane_b32 s39, v4
	s_mul_i32 s38, s38, s39
	s_mul_hi_u32 s38, s39, s38
	s_add_i32 s39, s39, s38
	s_mul_hi_u32 s38, s30, s39
	s_mul_i32 s38, s38, s37
	s_sub_i32 s30, s30, s38
	s_sub_i32 s38, s30, s37
	s_cmp_ge_u32 s30, s37
	s_cselect_b32 s30, s38, s30
	s_sub_i32 s38, s30, s37
	s_cmp_ge_u32 s30, s37
	s_cselect_b32 s30, s38, s30
	s_xor_b32 s30, s30, s31
	s_sub_i32 s30, s30, s31
	s_add_i32 s30, s30, s36
	s_ashr_i32 s31, s30, 31
	s_lshl_b64 s[30:31], s[30:31], 14
	v_lshl_add_u64 v[16:17], v[2:3], 0, s[30:31]
	global_load_dwordx4 v[4:7], v[16:17], off
	global_load_dwordx4 v[8:11], v[16:17], off offset:16
	global_load_dwordx4 v[12:15], v[16:17], off offset:32
	s_nop 0
	global_load_dwordx4 v[16:19], v[16:17], off offset:48
	s_mov_b32 s30, 0x800000
	s_waitcnt vmcnt(3)
	v_mov_b32_e32 v20, v5
	v_mov_b32_e32 v21, v6
	v_mov_b32_e32 v5, v7
	s_waitcnt vmcnt(2)
	v_mov_b32_e32 v6, v9
	v_mov_b32_e32 v7, v10
	v_mov_b32_e32 v9, v11
	v_pk_add_f32 v[4:5], v[20:21], v[4:5]
	v_pk_add_f32 v[6:7], v[6:7], v[8:9]
	v_pk_add_f32 v[4:5], v[4:5], v[4:5] op_sel:[0,1] op_sel_hi:[1,0]
	v_pk_add_f32 v[6:7], v[6:7], v[6:7] op_sel:[0,1] op_sel_hi:[1,0]
	s_waitcnt vmcnt(1)
	v_add_f32_e32 v10, v12, v13
	v_add_f32_e32 v12, v14, v15
	s_waitcnt vmcnt(0)
	v_mov_b32_e32 v11, v18
	v_mov_b32_e32 v13, v19
	v_mov_b32_e32 v5, v16
	v_mov_b32_e32 v7, v17
	v_pk_add_f32 v[8:9], v[10:11], v[12:13]
	v_pk_add_f32 v[4:5], v[4:5], v[6:7]
	s_nop 0
	v_pk_add_f32 v[4:5], v[4:5], v[8:9]
	s_nop 0
	v_add_f32_e32 v4, v4, v5
	v_fmamk_f32 v4, v4, 0x3a800000, v218
	v_mul_f32_e32 v5, 0x4b800000, v4
	v_cmp_gt_f32_e32 vcc, s30, v4
	s_nop 1
	v_cndmask_b32_e32 v4, v4, v5, vcc
	v_rsq_f32_e32 v4, v4
	s_nop 0
	v_mul_f32_e32 v5, 0x45800000, v4
	v_cndmask_b32_e32 v4, v4, v5, vcc
	ds_write_b32 v0, v4 offset:6144

;     __device__ bool next(int i, Unit& u) const { Unit b; if (!so.next(i >> 2, b)) return false; const int sub = i & 3; u.pm = b.pm; u.pn = sub * 4 + b.pn; u.acol = sub * 512; u.ord = i; return true; }
;     __device__ bool next(int i, Unit& u) const {
;         const long L = (long)i * G + c; if (L >= nwg) return false;
;         int wgid = (int)L; { const int q = nwg / NXCD, r = nwg % NXCD, xcd = wgid % NXCD, off = wgid / NXCD; wgid = (xcd < r ? xcd * (q + 1) : r * (q + 1) + (xcd - r) * q) + off; }
;         const int nig = WGM * nN, gid = wgid / nig, fm = gid * WGM, gsz = (nM - fm) < WGM ? (nM - fm) : WGM;
;         u.pm = fm + ((wgid % nig) % gsz); u.pn = (wgid % nig) / gsz; u.acol = 0; u.ord = i; return true;
; __device__ __forceinline__ float row_rstd(const float* rowsq, size_t row) {
;     const f32x4* q = (const f32x4*)(rowsq + row * 16); const f32x4 a = q[0], b = q[1], c = q[2], d = q[3];
;     const float s = ((a[0] + a[1]) + (a[2] + a[3])) + ((b[0] + b[1]) + (b[2] + b[3])) + ((c[0] + c[1]) + (c[2] + c[3])) + ((d[0] + d[1]) + (d[2] + d[3]));
;     return rsqrtf(s * (1.f / DM) + EPS);
.LBB0_388:
	s_or_b64 exec, exec, s[0:1]
	v_readlane_b32 s0, v254, 5
	s_waitcnt lgkmcnt(0)
	s_barrier
	v_readlane_b32 s1, v254, 6
	s_ashr_i32 s34, s94, 31
	s_ashr_i32 s48, s71, 31
	v_writelane_b32 v254, s0, 5
	s_cmpk_lt_i32 s71, 0x900
	v_mov_b32_e32 v2, v216
	v_writelane_b32 v254, s1, 6
	s_cselect_b64 s[0:1], -1, 0
	s_cmpk_gt_i32 s71, 0x8ff
	s_cbranch_scc1 .LBB0_424
	v_readlane_b32 s2, v253, 37
	v_ashrrev_i32_e32 v3, 31, v2
	v_cmp_gt_i32_e64 s[36:37], s91, v2
	v_lshl_add_u32 v0, v2, 2, s2
	v_readlane_b32 s2, v251, 42
	v_lshlrev_b64 v[2:3], 6, v[2:3]
	v_readlane_b32 s3, v251, 43
	s_nop 1
	v_lshl_add_u64 v[2:3], s[2:3], 0, v[2:3]
	s_and_saveexec_b64 s[2:3], s[36:37]
	s_cbranch_execz .LBB0_391
	s_lshr_b32 s24, s48, 29
	s_add_i32 s24, s71, s24
	s_and_b32 s25, s24, -8
	s_sub_i32 s25, s71, s25
	s_cmp_lt_i32 s25, 0
	s_movk_i32 s26, 0x121
	s_cselect_b32 s26, s26, 0x120
	s_mul_i32 s25, s25, s26
	s_ashr_i32 s24, s24, 3
	s_add_i32 s25, s25, s24
	s_mul_hi_i32 s24, s25, 0x38e38e39
	s_lshr_b32 s26, s24, 31
	s_ashr_i32 s24, s24, 6
	s_add_i32 s24, s24, s26
	s_mul_i32 s26, s24, 0x120
	s_lshl_b32 s24, s24, 3
	s_sub_i32 s25, s25, s26
	s_sub_i32 s26, 64, s24
	s_min_i32 s26, s26, 8
	s_abs_i32 s26, s26
	v_cvt_f32_u32_e32 v24, s26
	s_sub_i32 s28, 0, s26
	s_ashr_i32 s27, s25, 31
	s_abs_i32 s25, s25
	v_rcp_iflag_f32_e32 v24, v24
	s_nop 0
	v_mul_f32_e32 v24, 0x4f7ffffe, v24
	v_cvt_u32_f32_e32 v24, v24
	s_nop 0
	v_readfirstlane_b32 s29, v24
	s_mul_i32 s28, s28, s29
	s_mul_hi_u32 s28, s29, s28
	s_add_i32 s29, s29, s28
	s_mul_hi_u32 s28, s25, s29
	s_mul_i32 s28, s28, s26
	s_sub_i32 s25, s25, s28
	s_sub_i32 s28, s25, s26
	s_cmp_ge_u32 s25, s26
	s_cselect_b32 s25, s28, s25
	s_sub_i32 s28, s25, s26
	s_cmp_ge_u32 s25, s26
	s_cselect_b32 s25, s28, s25
	s_xor_b32 s25, s25, s27
	s_sub_i32 s25, s25, s27
	s_add_i32 s24, s25, s24
	s_ashr_i32 s25, s24, 31
	s_lshl_b64 s[24:25], s[24:25], 14
	v_lshl_add_u64 v[36:37], v[2:3], 0, s[24:25]
	global_load_dwordx4 v[24:27], v[36:37], off offset:48
	global_load_dwordx4 v[28:31], v[36:37], off offset:32
	global_load_dwordx4 v[32:35], v[36:37], off offset:16
	s_nop 0
	global_load_dwordx4 v[36:39], v[36:37], off
.LBB0_391:
	s_or_b64 exec, exec, s[2:3]
	s_add_u32 s2, s94, s71
	s_addc_u32 s3, s34, s48
	v_cmp_gt_i64_e32 vcc, s[2:3], v[192:193]
	s_cbranch_vccnz .Lmy_rsb_0_c1
	s_and_saveexec_b64 s[24:25], s[36:37]
	s_cbranch_execz .LBB0_394
	s_ashr_i32 s26, s2, 31
	s_lshr_b32 s26, s26, 29
	s_add_i32 s26, s2, s26
	s_ashr_i32 s27, s26, 3
	s_and_b32 s26, s26, -8
	s_sub_i32 s26, s2, s26
	s_cmp_lt_i32 s26, 0
	s_movk_i32 s28, 0x121
	s_cselect_b32 s28, s28, 0x120
	s_mul_i32 s26, s26, s28
	s_add_i32 s26, s26, s27
	s_mul_hi_i32 s27, s26, 0x38e38e39
	s_lshr_b32 s28, s27, 31
	s_ashr_i32 s27, s27, 6
	s_add_i32 s27, s27, s28
	s_mul_i32 s28, s27, 0x120
	s_lshl_b32 s27, s27, 3
	s_sub_i32 s26, s26, s28
	s_sub_i32 s28, 64, s27
	s_min_i32 s28, s28, 8
	s_abs_i32 s28, s28
	v_cvt_f32_u32_e32 v40, s28
	s_sub_i32 s30, 0, s28
	s_ashr_i32 s29, s26, 31
	s_abs_i32 s26, s26
	v_rcp_iflag_f32_e32 v40, v40
	s_nop 0
	v_mul_f32_e32 v40, 0x4f7ffffe, v40
	v_cvt_u32_f32_e32 v40, v40
	s_nop 0
	v_readfirstlane_b32 s31, v40
	s_mul_i32 s30, s30, s31
	s_mul_hi_u32 s30, s31, s30
	s_add_i32 s31, s31, s30
	s_mul_hi_u32 s30, s26, s31
	s_mul_i32 s30, s30, s28
	s_sub_i32 s26, s26, s30
	s_sub_i32 s30, s26, s28
	s_cmp_ge_u32 s26, s28
	s_cselect_b32 s26, s30, s26
	s_sub_i32 s30, s26, s28
	s_cmp_ge_u32 s26, s28
	s_cselect_b32 s26, s30, s26
	s_xor_b32 s26, s26, s29
	s_sub_i32 s26, s26, s29
	s_add_i32 s26, s26, s27
	s_ashr_i32 s27, s26, 31
	s_lshl_b64 s[26:27], s[26:27], 14
	v_lshl_add_u64 v[52:53], v[2:3], 0, s[26:27]
	global_load_dwordx4 v[40:43], v[52:53], off offset:48
	global_load_dwordx4 v[44:47], v[52:53], off offset:32
	global_load_dwordx4 v[48:51], v[52:53], off offset:16
	s_nop 0
	global_load_dwordx4 v[52:55], v[52:53], off
.LBB0_394:
	s_or_b64 exec, exec, s[24:25]
	s_add_u32 s2, s2, s94
	s_addc_u32 s3, s3, s34
	v_cmp_gt_i64_e32 vcc, s[2:3], v[192:193]
	s_cbranch_vccnz .Lmy_rsb_0_c2
	s_and_saveexec_b64 s[24:25], s[36:37]
	s_cbranch_execz .LBB0_397
	s_ashr_i32 s26, s2, 31
	s_lshr_b32 s26, s26, 29
	s_add_i32 s26, s2, s26
	s_ashr_i32 s27, s26, 3
	s_and_b32 s26, s26, -8
	s_sub_i32 s26, s2, s26
	s_cmp_lt_i32 s26, 0
	s_movk_i32 s28, 0x121
	s_cselect_b32 s28, s28, 0x120
	s_mul_i32 s26, s26, s28
	s_add_i32 s26, s26, s27
	s_mul_hi_i32 s27, s26, 0x38e38e39
	s_lshr_b32 s28, s27, 31
	s_ashr_i32 s27, s27, 6
	s_add_i32 s27, s27, s28
	s_mul_i32 s28, s27, 0x120
	s_lshl_b32 s27, s27, 3
	s_sub_i32 s26, s26, s28
	s_sub_i32 s28, 64, s27
	s_min_i32 s28, s28, 8
	s_abs_i32 s28, s28
	v_cvt_f32_u32_e32 v56, s28
	s_sub_i32 s30, 0, s28
	s_ashr_i32 s29, s26, 31
	s_abs_i32 s26, s26
	v_rcp_iflag_f32_e32 v56, v56
	s_nop 0
	v_mul_f32_e32 v56, 0x4f7ffffe, v56
	v_cvt_u32_f32_e32 v56, v56
	s_nop 0
	v_readfirstlane_b32 s31, v56
	s_mul_i32 s30, s30, s31
	s_mul_hi_u32 s30, s31, s30
	s_add_i32 s31, s31, s30
	s_mul_hi_u32 s30, s26, s31
	s_mul_i32 s30, s30, s28
	s_sub_i32 s26, s26, s30
	s_sub_i32 s30, s26, s28
	s_cmp_ge_u32 s26, s28
	s_cselect_b32 s26, s30, s26
	s_sub_i32 s30, s26, s28
	s_cmp_ge_u32 s26, s28
	s_cselect_b32 s26, s30, s26
	s_xor_b32 s26, s26, s29
	s_sub_i32 s26, s26, s29
	s_add_i32 s26, s26, s27
	s_ashr_i32 s27, s26, 31
	s_lshl_b64 s[26:27], s[26:27], 14
	v_lshl_add_u64 v[68:69], v[2:3], 0, s[26:27]
	global_load_dwordx4 v[56:59], v[68:69], off offset:48
	global_load_dwordx4 v[60:63], v[68:69], off offset:32
	global_load_dwordx4 v[64:67], v[68:69], off offset:16
	s_nop 0
	global_load_dwordx4 v[68:71], v[68:69], off
;     __device__ bool next(int i, Unit& u) const { Unit b; if (!so.next(i >> 2, b)) return false; const int sub = i & 3; u.pm = b.pm; u.pn = sub * 4 + b.pn; u.acol = sub * 512; u.ord = i; return true; }
;     __device__ bool next(int i, Unit& u) const {
;         const long L = (long)i * G + c; if (L >= nwg) return false;
;         int wgid = (int)L; { const int q = nwg / NXCD, r = nwg % NXCD, xcd = wgid % NXCD, off = wgid / NXCD; wgid = (xcd < r ? xcd * (q + 1) : r * (q + 1) + (xcd - r) * q) + off; }
;         const int nig = WGM * nN, gid = wgid / nig, fm = gid * WGM, gsz = (nM - fm) < WGM ? (nM - fm) : WGM;
;         u.pm = fm + ((wgid % nig) % gsz); u.pn = (wgid % nig) / gsz; u.acol = 0; u.ord = i; return true;
; __device__ __forceinline__ float row_rstd(const float* rowsq, size_t row) {
;     const f32x4* q = (const f32x4*)(rowsq + row * 16); const f32x4 a = q[0], b = q[1], c = q[2], d = q[3];
;     const float s = ((a[0] + a[1]) + (a[2] + a[3])) + ((b[0] + b[1]) + (b[2] + b[3])) + ((c[0] + c[1]) + (c[2] + c[3])) + ((d[0] + d[1]) + (d[2] + d[3]));
;     return rsqrtf(s * (1.f / DM) + EPS);
.LBB0_397:
	s_or_b64 exec, exec, s[24:25]
	s_add_u32 s2, s2, s94
	s_addc_u32 s3, s3, s34
	v_cmp_gt_i64_e32 vcc, s[2:3], v[192:193]
	s_cbranch_vccnz .Lmy_rsb_0_c3
	s_and_saveexec_b64 s[24:25], s[36:37]
	s_cbranch_execz .LBB0_400
	s_ashr_i32 s26, s2, 31
	s_lshr_b32 s26, s26, 29
	s_add_i32 s26, s2, s26
	s_ashr_i32 s27, s26, 3
	s_and_b32 s26, s26, -8
	s_sub_i32 s26, s2, s26
	s_cmp_lt_i32 s26, 0
	s_movk_i32 s28, 0x121
	s_cselect_b32 s28, s28, 0x120
	s_mul_i32 s26, s26, s28
	s_add_i32 s26, s26, s27
	s_mul_hi_i32 s27, s26, 0x38e38e39
	s_lshr_b32 s28, s27, 31
	s_ashr_i32 s27, s27, 6
	s_add_i32 s27, s27, s28
	s_mul_i32 s28, s27, 0x120
	s_lshl_b32 s27, s27, 3
	s_sub_i32 s26, s26, s28
	s_sub_i32 s28, 64, s27
	s_min_i32 s28, s28, 8
	s_abs_i32 s28, s28
	v_cvt_f32_u32_e32 v72, s28
	s_sub_i32 s30, 0, s28
	s_ashr_i32 s29, s26, 31
	s_abs_i32 s26, s26
	v_rcp_iflag_f32_e32 v72, v72
	s_nop 0
	v_mul_f32_e32 v72, 0x4f7ffffe, v72
	v_cvt_u32_f32_e32 v72, v72
	s_nop 0
	v_readfirstlane_b32 s31, v72
	s_mul_i32 s30, s30, s31
	s_mul_hi_u32 s30, s31, s30
	s_add_i32 s31, s31, s30
	s_mul_hi_u32 s30, s26, s31
	s_mul_i32 s30, s30, s28
	s_sub_i32 s26, s26, s30
	s_sub_i32 s30, s26, s28
	s_cmp_ge_u32 s26, s28
	s_cselect_b32 s26, s30, s26
	s_sub_i32 s30, s26, s28
	s_cmp_ge_u32 s26, s28
	s_cselect_b32 s26, s30, s26
	s_xor_b32 s26, s26, s29
	s_sub_i32 s26, s26, s29
	s_add_i32 s26, s26, s27
	s_ashr_i32 s27, s26, 31
	s_lshl_b64 s[26:27], s[26:27], 14
	v_lshl_add_u64 v[84:85], v[2:3], 0, s[26:27]
	global_load_dwordx4 v[72:75], v[84:85], off offset:48
	global_load_dwordx4 v[76:79], v[84:85], off offset:32
	global_load_dwordx4 v[80:83], v[84:85], off offset:16
	s_nop 0
	global_load_dwordx4 v[84:87], v[84:85], off
.LBB0_400:
	s_or_b64 exec, exec, s[24:25]
	s_add_u32 s2, s2, s94
	s_addc_u32 s3, s3, s34
	v_cmp_gt_i64_e32 vcc, s[2:3], v[192:193]
	s_cbranch_vccnz .Lmy_rsb_0_c4
	s_and_saveexec_b64 s[24:25], s[36:37]
	s_cbranch_execz .LBB0_403
	s_ashr_i32 s26, s2, 31
	s_lshr_b32 s26, s26, 29
	s_add_i32 s26, s2, s26
	s_ashr_i32 s27, s26, 3
	s_and_b32 s26, s26, -8
	s_sub_i32 s26, s2, s26
	s_cmp_lt_i32 s26, 0
	s_movk_i32 s28, 0x121
	s_cselect_b32 s28, s28, 0x120
	s_mul_i32 s26, s26, s28
	s_add_i32 s26, s26, s27
	s_mul_hi_i32 s27, s26, 0x38e38e39
	s_lshr_b32 s28, s27, 31
	s_ashr_i32 s27, s27, 6
	s_add_i32 s27, s27, s28
	s_mul_i32 s28, s27, 0x120
	s_lshl_b32 s27, s27, 3
	s_sub_i32 s26, s26, s28
	s_sub_i32 s28, 64, s27
	s_min_i32 s28, s28, 8
	s_abs_i32 s28, s28
	v_cvt_f32_u32_e32 v88, s28
	s_sub_i32 s30, 0, s28
	s_ashr_i32 s29, s26, 31
	s_abs_i32 s26, s26
	v_rcp_iflag_f32_e32 v88, v88
	s_nop 0
	v_mul_f32_e32 v88, 0x4f7ffffe, v88
	v_cvt_u32_f32_e32 v88, v88
	s_nop 0
	v_readfirstlane_b32 s31, v88
	s_mul_i32 s30, s30, s31
	s_mul_hi_u32 s30, s31, s30
	s_add_i32 s31, s31, s30
	s_mul_hi_u32 s30, s26, s31
	s_mul_i32 s30, s30, s28
	s_sub_i32 s26, s26, s30
	s_sub_i32 s30, s26, s28
	s_cmp_ge_u32 s26, s28
	s_cselect_b32 s26, s30, s26
	s_sub_i32 s30, s26, s28
	s_cmp_ge_u32 s26, s28
	s_cselect_b32 s26, s30, s26
	s_xor_b32 s26, s26, s29
	s_sub_i32 s26, s26, s29
	s_add_i32 s26, s26, s27
	s_ashr_i32 s27, s26, 31
	s_lshl_b64 s[26:27], s[26:27], 14
	v_lshl_add_u64 v[100:101], v[2:3], 0, s[26:27]
	global_load_dwordx4 v[88:91], v[100:101], off offset:48
	global_load_dwordx4 v[92:95], v[100:101], off offset:32
	global_load_dwordx4 v[96:99], v[100:101], off offset:16
	s_nop 0
	global_load_dwordx4 v[100:103], v[100:101], off
.LBB0_403:
	s_or_b64 exec, exec, s[24:25]
	s_add_u32 s2, s2, s94
	s_addc_u32 s3, s3, s34
	v_cmp_gt_i64_e32 vcc, s[2:3], v[192:193]
	s_cbranch_vccnz .Lmy_rsb_0_c5
	s_and_saveexec_b64 s[24:25], s[36:37]
	s_cbranch_execz .LBB0_406
	s_ashr_i32 s26, s2, 31
	s_lshr_b32 s26, s26, 29
	s_add_i32 s26, s2, s26
	s_ashr_i32 s27, s26, 3
	s_and_b32 s26, s26, -8
	s_sub_i32 s26, s2, s26
	s_cmp_lt_i32 s26, 0
	s_movk_i32 s28, 0x121
	s_cselect_b32 s28, s28, 0x120
	s_mul_i32 s26, s26, s28
	s_add_i32 s26, s26, s27
	s_mul_hi_i32 s27, s26, 0x38e38e39
	s_lshr_b32 s28, s27, 31
	s_ashr_i32 s27, s27, 6
	s_add_i32 s27, s27, s28
	s_mul_i32 s28, s27, 0x120
	s_lshl_b32 s27, s27, 3
	s_sub_i32 s26, s26, s28
	s_sub_i32 s28, 64, s27
	s_min_i32 s28, s28, 8
	s_abs_i32 s28, s28
	v_cvt_f32_u32_e32 v104, s28
	s_sub_i32 s30, 0, s28
	s_ashr_i32 s29, s26, 31
	s_abs_i32 s26, s26
	v_rcp_iflag_f32_e32 v104, v104
	s_nop 0
	v_mul_f32_e32 v104, 0x4f7ffffe, v104
	v_cvt_u32_f32_e32 v104, v104
	s_nop 0
	v_readfirstlane_b32 s31, v104
	s_mul_i32 s30, s30, s31
	s_mul_hi_u32 s30, s31, s30
	s_add_i32 s31, s31, s30
	s_mul_hi_u32 s30, s26, s31
	s_mul_i32 s30, s30, s28
	s_sub_i32 s26, s26, s30
	s_sub_i32 s30, s26, s28
	s_cmp_ge_u32 s26, s28
	s_cselect_b32 s26, s30, s26
	s_sub_i32 s30, s26, s28
	s_cmp_ge_u32 s26, s28
	s_cselect_b32 s26, s30, s26
	s_xor_b32 s26, s26, s29
	s_sub_i32 s26, s26, s29
	s_add_i32 s26, s26, s27
	s_ashr_i32 s27, s26, 31
	s_lshl_b64 s[26:27], s[26:27], 14
	v_lshl_add_u64 v[116:117], v[2:3], 0, s[26:27]
	global_load_dwordx4 v[104:107], v[116:117], off offset:48
	global_load_dwordx4 v[108:111], v[116:117], off offset:32
	global_load_dwordx4 v[112:115], v[116:117], off offset:16
	s_nop 0
	global_load_dwordx4 v[116:119], v[116:117], off
	s_or_b64 exec, exec, s[24:25]
.Lmy_rsb_0_c6:
	s_and_saveexec_b64 s[24:25], s[36:37]
	s_cbranch_execz .Lmy_rsb_0_s5
	s_mov_b32 s26, 0x800000
	s_waitcnt vmcnt(2)
	v_add_f32_e32 v108, v108, v109
	v_add_f32_e32 v110, v110, v111
	s_waitcnt vmcnt(0)
	v_mov_b32_e32 v20, v117
	v_mov_b32_e32 v21, v118
	v_mov_b32_e32 v117, v119
	v_mov_b32_e32 v118, v113
	v_mov_b32_e32 v119, v114
	v_mov_b32_e32 v113, v115
	v_pk_add_f32 v[116:117], v[20:21], v[116:117]
	v_pk_add_f32 v[112:113], v[118:119], v[112:113]
	v_pk_add_f32 v[116:117], v[116:117], v[116:117] op_sel:[0,1] op_sel_hi:[1,0]
	v_pk_add_f32 v[112:113], v[112:113], v[112:113] op_sel:[0,1] op_sel_hi:[1,0]
	v_mov_b32_e32 v117, v104
	v_mov_b32_e32 v113, v105
	v_mov_b32_e32 v109, v106
	v_mov_b32_e32 v111, v107
	v_pk_add_f32 v[104:105], v[116:117], v[112:113]
	v_pk_add_f32 v[106:107], v[108:109], v[110:111]
	s_nop 0
	v_pk_add_f32 v[104:105], v[104:105], v[106:107]
	s_nop 0
	v_add_f32_e32 v104, v104, v105
	v_fmamk_f32 v104, v104, 0x3a800000, v218
	v_cmp_gt_f32_e32 vcc, s26, v104
	v_mul_f32_e32 v105, 0x4b800000, v104
	s_nop 0
	v_cndmask_b32_e32 v104, v104, v105, vcc
	v_rsq_f32_e32 v104, v104
	s_nop 0
	v_mul_f32_e32 v105, 0x45800000, v104
	v_cndmask_b32_e32 v104, v104, v105, vcc
	ds_write_b32 v0, v104 offset:5120

;     __device__ bool next(int i, Unit& u) const { Unit b; if (!so.next(i >> 2, b)) return false; const int sub = i & 3; u.pm = b.pm; u.pn = sub * 4 + b.pn; u.acol = sub * 512; u.ord = i; return true; }
; __device__ __forceinline__ float row_rstd(const float* rowsq, size_t row) {
;     const f32x4* q = (const f32x4*)(rowsq + row * 16); const f32x4 a = q[0], b = q[1], c = q[2], d = q[3];
;     const float s = ((a[0] + a[1]) + (a[2] + a[3])) + ((b[0] + b[1]) + (b[2] + b[3])) + ((c[0] + c[1]) + (c[2] + c[3])) + ((d[0] + d[1]) + (d[2] + d[3]));
;     return rsqrtf(s * (1.f / DM) + EPS);
; }
; template <class Sched> __device__ __forceinline__ void rstd_prologue(const Sched& S, const float* rowsq, LAS float* rst) {
;     ...
;     for (int i = 0; i < 12 && S.next(i, u); ++i) if (t_ < 256) rst[i * 256 + t_] = pg8::row_rstd(rowsq, (size_t)u.pm * 256 + t_);
.Lmy_rsb_0_c5:
	s_and_saveexec_b64 s[24:25], s[36:37]
	s_cbranch_execz .Lmy_rsb_0_s4
	s_mov_b32 s26, 0x800000
	s_waitcnt vmcnt(2)
	v_add_f32_e32 v92, v92, v93
	v_add_f32_e32 v94, v94, v95
	s_waitcnt vmcnt(0)
	v_mov_b32_e32 v20, v101
	v_mov_b32_e32 v21, v102
	v_mov_b32_e32 v101, v103
	v_mov_b32_e32 v102, v97
	v_mov_b32_e32 v103, v98
	v_mov_b32_e32 v97, v99
	v_pk_add_f32 v[100:101], v[20:21], v[100:101]
	v_pk_add_f32 v[96:97], v[102:103], v[96:97]
	v_pk_add_f32 v[100:101], v[100:101], v[100:101] op_sel:[0,1] op_sel_hi:[1,0]
	v_pk_add_f32 v[96:97], v[96:97], v[96:97] op_sel:[0,1] op_sel_hi:[1,0]
	v_mov_b32_e32 v101, v88
	v_mov_b32_e32 v97, v89
	v_mov_b32_e32 v93, v90
	v_mov_b32_e32 v95, v91
	v_pk_add_f32 v[88:89], v[100:101], v[96:97]
	v_pk_add_f32 v[90:91], v[92:93], v[94:95]
	s_nop 0
	v_pk_add_f32 v[88:89], v[88:89], v[90:91]
	s_nop 0
	v_add_f32_e32 v88, v88, v89
	v_fmamk_f32 v88, v88, 0x3a800000, v218
	v_cmp_gt_f32_e32 vcc, s26, v88
	v_mul_f32_e32 v89, 0x4b800000, v88
	s_nop 0
	v_cndmask_b32_e32 v88, v88, v89, vcc
	v_rsq_f32_e32 v88, v88
	s_nop 0
	v_mul_f32_e32 v89, 0x45800000, v88
	v_cndmask_b32_e32 v88, v88, v89, vcc
	ds_write_b32 v0, v88 offset:4096

;     __device__ bool next(int i, Unit& u) const { Unit b; if (!so.next(i >> 2, b)) return false; const int sub = i & 3; u.pm = b.pm; u.pn = sub * 4 + b.pn; u.acol = sub * 512; u.ord = i; return true; }
; __device__ __forceinline__ float row_rstd(const float* rowsq, size_t row) {
;     const f32x4* q = (const f32x4*)(rowsq + row * 16); const f32x4 a = q[0], b = q[1], c = q[2], d = q[3];
;     const float s = ((a[0] + a[1]) + (a[2] + a[3])) + ((b[0] + b[1]) + (b[2] + b[3])) + ((c[0] + c[1]) + (c[2] + c[3])) + ((d[0] + d[1]) + (d[2] + d[3]));
;     return rsqrtf(s * (1.f / DM) + EPS);
; }
; template <class Sched> __device__ __forceinline__ void rstd_prologue(const Sched& S, const float* rowsq, LAS float* rst) {
;     ...
;     for (int i = 0; i < 12 && S.next(i, u); ++i) if (t_ < 256) rst[i * 256 + t_] = pg8::row_rstd(rowsq, (size_t)u.pm * 256 + t_);
.Lmy_rsb_0_c4:
	s_and_saveexec_b64 s[24:25], s[36:37]
	s_cbranch_execz .Lmy_rsb_0_s3
	s_mov_b32 s26, 0x800000
	s_waitcnt vmcnt(2)
	v_add_f32_e32 v76, v76, v77
	v_add_f32_e32 v78, v78, v79
	s_waitcnt vmcnt(0)
	v_mov_b32_e32 v20, v85
	v_mov_b32_e32 v21, v86
	v_mov_b32_e32 v85, v87
	v_mov_b32_e32 v86, v81
	v_mov_b32_e32 v87, v82
	v_mov_b32_e32 v81, v83
	v_pk_add_f32 v[84:85], v[20:21], v[84:85]
	v_pk_add_f32 v[80:81], v[86:87], v[80:81]
	v_pk_add_f32 v[84:85], v[84:85], v[84:85] op_sel:[0,1] op_sel_hi:[1,0]
	v_pk_add_f32 v[80:81], v[80:81], v[80:81] op_sel:[0,1] op_sel_hi:[1,0]
	v_mov_b32_e32 v85, v72
	v_mov_b32_e32 v81, v73
	v_mov_b32_e32 v77, v74
	v_mov_b32_e32 v79, v75
	v_pk_add_f32 v[72:73], v[84:85], v[80:81]
	v_pk_add_f32 v[74:75], v[76:77], v[78:79]
	s_nop 0
	v_pk_add_f32 v[72:73], v[72:73], v[74:75]
	s_nop 0
	v_add_f32_e32 v72, v72, v73
	v_fmamk_f32 v72, v72, 0x3a800000, v218
	v_cmp_gt_f32_e32 vcc, s26, v72
	v_mul_f32_e32 v73, 0x4b800000, v72
	s_nop 0
	v_cndmask_b32_e32 v72, v72, v73, vcc
	v_rsq_f32_e32 v72, v72
	s_nop 0
	v_mul_f32_e32 v73, 0x45800000, v72
	v_cndmask_b32_e32 v72, v72, v73, vcc
	ds_write_b32 v0, v72 offset:3072

;     __device__ bool next(int i, Unit& u) const { Unit b; if (!so.next(i >> 2, b)) return false; const int sub = i & 3; u.pm = b.pm; u.pn = sub * 4 + b.pn; u.acol = sub * 512; u.ord = i; return true; }
; __device__ __forceinline__ float row_rstd(const float* rowsq, size_t row) {
;     const f32x4* q = (const f32x4*)(rowsq + row * 16); const f32x4 a = q[0], b = q[1], c = q[2], d = q[3];
;     const float s = ((a[0] + a[1]) + (a[2] + a[3])) + ((b[0] + b[1]) + (b[2] + b[3])) + ((c[0] + c[1]) + (c[2] + c[3])) + ((d[0] + d[1]) + (d[2] + d[3]));
;     return rsqrtf(s * (1.f / DM) + EPS);
; }
; template <class Sched> __device__ __forceinline__ void rstd_prologue(const Sched& S, const float* rowsq, LAS float* rst) {
;     ...
;     for (int i = 0; i < 12 && S.next(i, u); ++i) if (t_ < 256) rst[i * 256 + t_] = pg8::row_rstd(rowsq, (size_t)u.pm * 256 + t_);
.Lmy_rsb_0_c3:
	s_and_saveexec_b64 s[24:25], s[36:37]
	s_cbranch_execz .Lmy_rsb_0_s2
	s_mov_b32 s26, 0x800000
	s_waitcnt vmcnt(2)
	v_add_f32_e32 v60, v60, v61
	v_add_f32_e32 v62, v62, v63
	s_waitcnt vmcnt(0)
	v_mov_b32_e32 v20, v69
	v_mov_b32_e32 v21, v70
	v_mov_b32_e32 v69, v71
	v_mov_b32_e32 v70, v65
	v_mov_b32_e32 v71, v66
	v_mov_b32_e32 v65, v67
	v_pk_add_f32 v[68:69], v[20:21], v[68:69]
	v_pk_add_f32 v[64:65], v[70:71], v[64:65]
	v_pk_add_f32 v[68:69], v[68:69], v[68:69] op_sel:[0,1] op_sel_hi:[1,0]
	v_pk_add_f32 v[64:65], v[64:65], v[64:65] op_sel:[0,1] op_sel_hi:[1,0]
	v_mov_b32_e32 v69, v56
	v_mov_b32_e32 v65, v57
	v_mov_b32_e32 v61, v58
	v_mov_b32_e32 v63, v59
	v_pk_add_f32 v[56:57], v[68:69], v[64:65]
	v_pk_add_f32 v[58:59], v[60:61], v[62:63]
	s_nop 0
	v_pk_add_f32 v[56:57], v[56:57], v[58:59]
	s_nop 0
	v_add_f32_e32 v56, v56, v57
	v_fmamk_f32 v56, v56, 0x3a800000, v218
	v_cmp_gt_f32_e32 vcc, s26, v56
	v_mul_f32_e32 v57, 0x4b800000, v56
	s_nop 0
	v_cndmask_b32_e32 v56, v56, v57, vcc
	v_rsq_f32_e32 v56, v56
	s_nop 0
	v_mul_f32_e32 v57, 0x45800000, v56
	v_cndmask_b32_e32 v56, v56, v57, vcc
	ds_write_b32 v0, v56 offset:2048

;     __device__ bool next(int i, Unit& u) const { Unit b; if (!so.next(i >> 2, b)) return false; const int sub = i & 3; u.pm = b.pm; u.pn = sub * 4 + b.pn; u.acol = sub * 512; u.ord = i; return true; }
; __device__ __forceinline__ float row_rstd(const float* rowsq, size_t row) {
;     const f32x4* q = (const f32x4*)(rowsq + row * 16); const f32x4 a = q[0], b = q[1], c = q[2], d = q[3];
;     const float s = ((a[0] + a[1]) + (a[2] + a[3])) + ((b[0] + b[1]) + (b[2] + b[3])) + ((c[0] + c[1]) + (c[2] + c[3])) + ((d[0] + d[1]) + (d[2] + d[3]));
;     return rsqrtf(s * (1.f / DM) + EPS);
; }
; template <class Sched> __device__ __forceinline__ void rstd_prologue(const Sched& S, const float* rowsq, LAS float* rst) {
;     ...
;     for (int i = 0; i < 12 && S.next(i, u); ++i) if (t_ < 256) rst[i * 256 + t_] = pg8::row_rstd(rowsq, (size_t)u.pm * 256 + t_);
.Lmy_rsb_0_c2:
	s_and_saveexec_b64 s[24:25], s[36:37]
	s_cbranch_execz .Lmy_rsb_0_s1
	s_mov_b32 s26, 0x800000
	s_waitcnt vmcnt(2)
	v_add_f32_e32 v44, v44, v45
	v_add_f32_e32 v46, v46, v47
	s_waitcnt vmcnt(0)
	v_mov_b32_e32 v20, v53
	v_mov_b32_e32 v21, v54
	v_mov_b32_e32 v53, v55
	v_mov_b32_e32 v54, v49
	v_mov_b32_e32 v55, v50
	v_mov_b32_e32 v49, v51
	v_pk_add_f32 v[52:53], v[20:21], v[52:53]
	v_pk_add_f32 v[48:49], v[54:55], v[48:49]
	v_pk_add_f32 v[52:53], v[52:53], v[52:53] op_sel:[0,1] op_sel_hi:[1,0]
	v_pk_add_f32 v[48:49], v[48:49], v[48:49] op_sel:[0,1] op_sel_hi:[1,0]
	v_mov_b32_e32 v53, v40
	v_mov_b32_e32 v49, v41
	v_mov_b32_e32 v45, v42
	v_mov_b32_e32 v47, v43
	v_pk_add_f32 v[40:41], v[52:53], v[48:49]
	v_pk_add_f32 v[42:43], v[44:45], v[46:47]
	s_nop 0
	v_pk_add_f32 v[40:41], v[40:41], v[42:43]
	s_nop 0
	v_add_f32_e32 v40, v40, v41
	v_fmamk_f32 v40, v40, 0x3a800000, v218
	v_cmp_gt_f32_e32 vcc, s26, v40
	v_mul_f32_e32 v41, 0x4b800000, v40
	s_nop 0
	v_cndmask_b32_e32 v40, v40, v41, vcc
	v_rsq_f32_e32 v40, v40
	s_nop 0
	v_mul_f32_e32 v41, 0x45800000, v40
	v_cndmask_b32_e32 v40, v40, v41, vcc
	ds_write_b32 v0, v40 offset:1024

;     __device__ bool next(int i, Unit& u) const { Unit b; if (!so.next(i >> 2, b)) return false; const int sub = i & 3; u.pm = b.pm; u.pn = sub * 4 + b.pn; u.acol = sub * 512; u.ord = i; return true; }
; __device__ __forceinline__ float row_rstd(const float* rowsq, size_t row) {
;     const f32x4* q = (const f32x4*)(rowsq + row * 16); const f32x4 a = q[0], b = q[1], c = q[2], d = q[3];
;     const float s = ((a[0] + a[1]) + (a[2] + a[3])) + ((b[0] + b[1]) + (b[2] + b[3])) + ((c[0] + c[1]) + (c[2] + c[3])) + ((d[0] + d[1]) + (d[2] + d[3]));
;     return rsqrtf(s * (1.f / DM) + EPS);
; }
; template <class Sched> __device__ __forceinline__ void rstd_prologue(const Sched& S, const float* rowsq, LAS float* rst) {
;     ...
;     for (int i = 0; i < 12 && S.next(i, u); ++i) if (t_ < 256) rst[i * 256 + t_] = pg8::row_rstd(rowsq, (size_t)u.pm * 256 + t_);
.Lmy_rsb_0_c1:
	s_and_saveexec_b64 s[24:25], s[36:37]
	s_cbranch_execz .Lmy_rsb_0_s0
	s_mov_b32 s24, 0x800000
	s_waitcnt vmcnt(2)
	v_add_f32_e32 v28, v28, v29
	v_add_f32_e32 v30, v30, v31
	s_waitcnt vmcnt(0)
	v_mov_b32_e32 v20, v37
	v_mov_b32_e32 v21, v38
	v_mov_b32_e32 v37, v39
	v_mov_b32_e32 v38, v33
	v_mov_b32_e32 v39, v34
	v_mov_b32_e32 v33, v35
	v_pk_add_f32 v[36:37], v[20:21], v[36:37]
	v_pk_add_f32 v[32:33], v[38:39], v[32:33]
	v_pk_add_f32 v[36:37], v[36:37], v[36:37] op_sel:[0,1] op_sel_hi:[1,0]
	v_pk_add_f32 v[32:33], v[32:33], v[32:33] op_sel:[0,1] op_sel_hi:[1,0]
	v_mov_b32_e32 v37, v24
	v_mov_b32_e32 v33, v25
	v_mov_b32_e32 v29, v26
	v_mov_b32_e32 v31, v27
	v_pk_add_f32 v[24:25], v[36:37], v[32:33]
	v_pk_add_f32 v[26:27], v[28:29], v[30:31]
	s_nop 0
	v_pk_add_f32 v[24:25], v[24:25], v[26:27]
	s_nop 0
	v_add_f32_e32 v24, v24, v25
	v_fmamk_f32 v24, v24, 0x3a800000, v218
	v_cmp_gt_f32_e32 vcc, s24, v24
	v_mul_f32_e32 v25, 0x4b800000, v24
	s_nop 0
	v_cndmask_b32_e32 v24, v24, v25, vcc
	v_rsq_f32_e32 v24, v24
	s_nop 0
	v_mul_f32_e32 v25, 0x45800000, v24
	v_cndmask_b32_e32 v24, v24, v25, vcc
	ds_write_b32 v0, v24

;     __device__ bool next(int i, Unit& u) const { Unit b; if (!so.next(i >> 2, b)) return false; const int sub = i & 3; u.pm = b.pm; u.pn = sub * 4 + b.pn; u.acol = sub * 512; u.ord = i; return true; }
;     __device__ bool next(int i, Unit& u) const {
;         const long L = (long)i * G + c; if (L >= nwg) return false;
;         int wgid = (int)L; { const int q = nwg / NXCD, r = nwg % NXCD, xcd = wgid % NXCD, off = wgid / NXCD; wgid = (xcd < r ? xcd * (q + 1) : r * (q + 1) + (xcd - r) * q) + off; }
;         const int nig = WGM * nN, gid = wgid / nig, fm = gid * WGM, gsz = (nM - fm) < WGM ? (nM - fm) : WGM;
;         u.pm = fm + ((wgid % nig) % gsz); u.pn = (wgid % nig) / gsz; u.acol = 0; u.ord = i; return true;
; __device__ __forceinline__ float row_rstd(const float* rowsq, size_t row) {
;     const f32x4* q = (const f32x4*)(rowsq + row * 16); const f32x4 a = q[0], b = q[1], c = q[2], d = q[3];
;     const float s = ((a[0] + a[1]) + (a[2] + a[3])) + ((b[0] + b[1]) + (b[2] + b[3])) + ((c[0] + c[1]) + (c[2] + c[3])) + ((d[0] + d[1]) + (d[2] + d[3]));
;     return rsqrtf(s * (1.f / DM) + EPS);
.LBB0_406:
	s_or_b64 exec, exec, s[24:25]
	s_add_u32 s2, s2, s94
	s_addc_u32 s3, s3, s34
	v_cmp_gt_i64_e32 vcc, s[2:3], v[192:193]
	s_cbranch_vccnz .LBB0_424
	s_and_saveexec_b64 s[24:25], s[36:37]
	s_cbranch_execz .LBB0_409
	s_ashr_i32 s26, s2, 31
	s_lshr_b32 s26, s26, 29
	s_add_i32 s26, s2, s26
	s_ashr_i32 s27, s26, 3
	s_and_b32 s26, s26, -8
	s_sub_i32 s26, s2, s26
	s_cmp_lt_i32 s26, 0
	s_movk_i32 s28, 0x121
	s_cselect_b32 s28, s28, 0x120
	s_mul_i32 s26, s26, s28
	s_add_i32 s26, s26, s27
	s_mul_hi_i32 s27, s26, 0x38e38e39
	s_lshr_b32 s28, s27, 31
	s_ashr_i32 s27, s27, 6
	s_add_i32 s27, s27, s28
	s_mul_i32 s28, s27, 0x120
	s_lshl_b32 s27, s27, 3
	s_sub_i32 s26, s26, s28
	s_sub_i32 s28, 64, s27
	s_min_i32 s28, s28, 8
	s_abs_i32 s28, s28
	v_cvt_f32_u32_e32 v24, s28
	s_sub_i32 s30, 0, s28
	s_ashr_i32 s29, s26, 31
	s_abs_i32 s26, s26
	v_rcp_iflag_f32_e32 v24, v24
	s_nop 0
	v_mul_f32_e32 v24, 0x4f7ffffe, v24
	v_cvt_u32_f32_e32 v24, v24
	s_nop 0
	v_readfirstlane_b32 s31, v24
	s_mul_i32 s30, s30, s31
	s_mul_hi_u32 s30, s31, s30
	s_add_i32 s31, s31, s30
	s_mul_hi_u32 s30, s26, s31
	s_mul_i32 s30, s30, s28
	s_sub_i32 s26, s26, s30
	s_sub_i32 s30, s26, s28
	s_cmp_ge_u32 s26, s28
	s_cselect_b32 s26, s30, s26
	s_sub_i32 s30, s26, s28
	s_cmp_ge_u32 s26, s28
	s_cselect_b32 s26, s30, s26
	s_xor_b32 s26, s26, s29
	s_sub_i32 s26, s26, s29
	s_add_i32 s26, s26, s27
	s_ashr_i32 s27, s26, 31
	s_lshl_b64 s[26:27], s[26:27], 14
	v_lshl_add_u64 v[36:37], v[2:3], 0, s[26:27]
	global_load_dwordx4 v[24:27], v[36:37], off offset:48
	global_load_dwordx4 v[28:31], v[36:37], off offset:32
	global_load_dwordx4 v[32:35], v[36:37], off offset:16
	s_nop 0
	global_load_dwordx4 v[36:39], v[36:37], off
.LBB0_409:
	s_or_b64 exec, exec, s[24:25]
	s_add_u32 s2, s2, s94
	s_addc_u32 s3, s3, s34
	v_cmp_gt_i64_e32 vcc, s[2:3], v[192:193]
	s_cbranch_vccnz .Lmy_rsb_6_c1
	s_and_saveexec_b64 s[24:25], s[36:37]
	s_cbranch_execz .LBB0_412
	s_ashr_i32 s26, s2, 31
	s_lshr_b32 s26, s26, 29
	s_add_i32 s26, s2, s26
	s_ashr_i32 s27, s26, 3
	s_and_b32 s26, s26, -8
	s_sub_i32 s26, s2, s26
	s_cmp_lt_i32 s26, 0
	s_movk_i32 s28, 0x121
	s_cselect_b32 s28, s28, 0x120
	s_mul_i32 s26, s26, s28
	s_add_i32 s26, s26, s27
	s_mul_hi_i32 s27, s26, 0x38e38e39
	s_lshr_b32 s28, s27, 31
	s_ashr_i32 s27, s27, 6
	s_add_i32 s27, s27, s28
	s_mul_i32 s28, s27, 0x120
	s_lshl_b32 s27, s27, 3
	s_sub_i32 s26, s26, s28
	s_sub_i32 s28, 64, s27
	s_min_i32 s28, s28, 8
	s_abs_i32 s28, s28
	v_cvt_f32_u32_e32 v40, s28
	s_sub_i32 s30, 0, s28
	s_ashr_i32 s29, s26, 31
	s_abs_i32 s26, s26
	v_rcp_iflag_f32_e32 v40, v40
	s_nop 0
	v_mul_f32_e32 v40, 0x4f7ffffe, v40
	v_cvt_u32_f32_e32 v40, v40
	s_nop 0
	v_readfirstlane_b32 s31, v40
	s_mul_i32 s30, s30, s31
	s_mul_hi_u32 s30, s31, s30
	s_add_i32 s31, s31, s30
	s_mul_hi_u32 s30, s26, s31
	s_mul_i32 s30, s30, s28
	s_sub_i32 s26, s26, s30
	s_sub_i32 s30, s26, s28
	s_cmp_ge_u32 s26, s28
	s_cselect_b32 s26, s30, s26
	s_sub_i32 s30, s26, s28
	s_cmp_ge_u32 s26, s28
	s_cselect_b32 s26, s30, s26
	s_xor_b32 s26, s26, s29
	s_sub_i32 s26, s26, s29
	s_add_i32 s26, s26, s27
	s_ashr_i32 s27, s26, 31
	s_lshl_b64 s[26:27], s[26:27], 14
	v_lshl_add_u64 v[52:53], v[2:3], 0, s[26:27]
	global_load_dwordx4 v[40:43], v[52:53], off offset:48
	global_load_dwordx4 v[44:47], v[52:53], off offset:32
	global_load_dwordx4 v[48:51], v[52:53], off offset:16
	s_nop 0
	global_load_dwordx4 v[52:55], v[52:53], off

;     __device__ bool next(int i, Unit& u) const { Unit b; if (!so.next(i >> 2, b)) return false; const int sub = i & 3; u.pm = b.pm; u.pn = sub * 4 + b.pn; u.acol = sub * 512; u.ord = i; return true; }
;     __device__ bool next(int i, Unit& u) const {
;         const long L = (long)i * G + c; if (L >= nwg) return false;
;         int wgid = (int)L; { const int q = nwg / NXCD, r = nwg % NXCD, xcd = wgid % NXCD, off = wgid / NXCD; wgid = (xcd < r ? xcd * (q + 1) : r * (q + 1) + (xcd - r) * q) + off; }
;         const int nig = WGM * nN, gid = wgid / nig, fm = gid * WGM, gsz = (nM - fm) < WGM ? (nM - fm) : WGM;
;         u.pm = fm + ((wgid % nig) % gsz); u.pn = (wgid % nig) / gsz; u.acol = 0; u.ord = i; return true;
; __device__ __forceinline__ float row_rstd(const float* rowsq, size_t row) {
;     const f32x4* q = (const f32x4*)(rowsq + row * 16); const f32x4 a = q[0], b = q[1], c = q[2], d = q[3];
;     const float s = ((a[0] + a[1]) + (a[2] + a[3])) + ((b[0] + b[1]) + (b[2] + b[3])) + ((c[0] + c[1]) + (c[2] + c[3])) + ((d[0] + d[1]) + (d[2] + d[3]));
;     return rsqrtf(s * (1.f / DM) + EPS);
.LBB0_418:
	s_or_b64 exec, exec, s[24:25]
	s_add_u32 s2, s2, s94
	s_addc_u32 s3, s3, s34
	v_cmp_gt_i64_e32 vcc, s[2:3], v[192:193]
	s_cbranch_vccnz .Lmy_rsb_6_c4
	s_and_saveexec_b64 s[24:25], s[36:37]
	s_cbranch_execz .LBB0_421
	s_ashr_i32 s26, s2, 31
	s_lshr_b32 s26, s26, 29
	s_add_i32 s26, s2, s26
	s_ashr_i32 s27, s26, 3
	s_and_b32 s26, s26, -8
	s_sub_i32 s26, s2, s26
	s_cmp_lt_i32 s26, 0
	s_movk_i32 s28, 0x121
	s_cselect_b32 s28, s28, 0x120
	s_mul_i32 s26, s26, s28
	s_add_i32 s26, s26, s27
	s_mul_hi_i32 s27, s26, 0x38e38e39
	s_lshr_b32 s28, s27, 31
	s_ashr_i32 s27, s27, 6
	s_add_i32 s27, s27, s28
	s_mul_i32 s28, s27, 0x120
	s_lshl_b32 s27, s27, 3
	s_sub_i32 s26, s26, s28
	s_sub_i32 s28, 64, s27
	s_min_i32 s28, s28, 8
	s_abs_i32 s28, s28
	v_cvt_f32_u32_e32 v88, s28
	s_sub_i32 s30, 0, s28
	s_ashr_i32 s29, s26, 31
	s_abs_i32 s26, s26
	v_rcp_iflag_f32_e32 v88, v88
	s_nop 0
	v_mul_f32_e32 v88, 0x4f7ffffe, v88
	v_cvt_u32_f32_e32 v88, v88
	s_nop 0
	v_readfirstlane_b32 s31, v88
	s_mul_i32 s30, s30, s31
	s_mul_hi_u32 s30, s31, s30
	s_add_i32 s31, s31, s30
	s_mul_hi_u32 s30, s26, s31
	s_mul_i32 s30, s30, s28
	s_sub_i32 s26, s26, s30
	s_sub_i32 s30, s26, s28
	s_cmp_ge_u32 s26, s28
	s_cselect_b32 s26, s30, s26
	s_sub_i32 s30, s26, s28
	s_cmp_ge_u32 s26, s28
	s_cselect_b32 s26, s30, s26
	s_xor_b32 s26, s26, s29
	s_sub_i32 s26, s26, s29
	s_add_i32 s26, s26, s27
	s_ashr_i32 s27, s26, 31
	s_lshl_b64 s[26:27], s[26:27], 14
	v_lshl_add_u64 v[100:101], v[2:3], 0, s[26:27]
	global_load_dwordx4 v[88:91], v[100:101], off offset:48
	global_load_dwordx4 v[92:95], v[100:101], off offset:32
	global_load_dwordx4 v[96:99], v[100:101], off offset:16
	s_nop 0
	global_load_dwordx4 v[100:103], v[100:101], off
	s_or_b64 exec, exec, s[24:25]
.Lmy_rsb_6_c5:
	s_and_saveexec_b64 s[24:25], s[36:37]
	s_cbranch_execz .Lmy_rsb_6_s4
	s_mov_b32 s26, 0x800000
	s_waitcnt vmcnt(2)
	v_add_f32_e32 v92, v92, v93
	v_add_f32_e32 v94, v94, v95
	s_waitcnt vmcnt(0)
	v_mov_b32_e32 v20, v101
	v_mov_b32_e32 v21, v102
	v_mov_b32_e32 v101, v103
	v_mov_b32_e32 v102, v97
	v_mov_b32_e32 v103, v98
	v_mov_b32_e32 v97, v99
	v_pk_add_f32 v[100:101], v[20:21], v[100:101]
	v_pk_add_f32 v[96:97], v[102:103], v[96:97]
	v_pk_add_f32 v[100:101], v[100:101], v[100:101] op_sel:[0,1] op_sel_hi:[1,0]
	v_pk_add_f32 v[96:97], v[96:97], v[96:97] op_sel:[0,1] op_sel_hi:[1,0]
	v_mov_b32_e32 v101, v88
	v_mov_b32_e32 v97, v89
	v_mov_b32_e32 v93, v90
	v_mov_b32_e32 v95, v91
	v_pk_add_f32 v[88:89], v[100:101], v[96:97]
	v_pk_add_f32 v[90:91], v[92:93], v[94:95]
	s_nop 0
	v_pk_add_f32 v[88:89], v[88:89], v[90:91]
	s_nop 0
	v_add_f32_e32 v88, v88, v89
	v_fmamk_f32 v88, v88, 0x3a800000, v218
	v_cmp_gt_f32_e32 vcc, s26, v88
	v_mul_f32_e32 v89, 0x4b800000, v88
	s_nop 0
	v_cndmask_b32_e32 v88, v88, v89, vcc
	v_rsq_f32_e32 v88, v88
	s_nop 0
	v_mul_f32_e32 v89, 0x45800000, v88
	v_cndmask_b32_e32 v88, v88, v89, vcc
	ds_write_b32 v0, v88 offset:10240

;     __device__ bool next(int i, Unit& u) const { Unit b; if (!so.next(i >> 2, b)) return false; const int sub = i & 3; u.pm = b.pm; u.pn = sub * 4 + b.pn; u.acol = sub * 512; u.ord = i; return true; }
; __device__ __forceinline__ float row_rstd(const float* rowsq, size_t row) {
;     const f32x4* q = (const f32x4*)(rowsq + row * 16); const f32x4 a = q[0], b = q[1], c = q[2], d = q[3];
;     const float s = ((a[0] + a[1]) + (a[2] + a[3])) + ((b[0] + b[1]) + (b[2] + b[3])) + ((c[0] + c[1]) + (c[2] + c[3])) + ((d[0] + d[1]) + (d[2] + d[3]));
;     return rsqrtf(s * (1.f / DM) + EPS);
; }
; template <class Sched> __device__ __forceinline__ void rstd_prologue(const Sched& S, const float* rowsq, LAS float* rst) {
;     ...
;     for (int i = 0; i < 12 && S.next(i, u); ++i) if (t_ < 256) rst[i * 256 + t_] = pg8::row_rstd(rowsq, (size_t)u.pm * 256 + t_);
.Lmy_rsb_6_c4:
	s_and_saveexec_b64 s[24:25], s[36:37]
	s_cbranch_execz .Lmy_rsb_6_s3
	s_mov_b32 s26, 0x800000
	s_waitcnt vmcnt(2)
	v_add_f32_e32 v76, v76, v77
	v_add_f32_e32 v78, v78, v79
	s_waitcnt vmcnt(0)
	v_mov_b32_e32 v20, v85
	v_mov_b32_e32 v21, v86
	v_mov_b32_e32 v85, v87
	v_mov_b32_e32 v86, v81
	v_mov_b32_e32 v87, v82
	v_mov_b32_e32 v81, v83
	v_pk_add_f32 v[84:85], v[20:21], v[84:85]
	v_pk_add_f32 v[80:81], v[86:87], v[80:81]
	v_pk_add_f32 v[84:85], v[84:85], v[84:85] op_sel:[0,1] op_sel_hi:[1,0]
	v_pk_add_f32 v[80:81], v[80:81], v[80:81] op_sel:[0,1] op_sel_hi:[1,0]
	v_mov_b32_e32 v85, v72
	v_mov_b32_e32 v81, v73
	v_mov_b32_e32 v77, v74
	v_mov_b32_e32 v79, v75
	v_pk_add_f32 v[72:73], v[84:85], v[80:81]
	v_pk_add_f32 v[74:75], v[76:77], v[78:79]
	s_nop 0
	v_pk_add_f32 v[72:73], v[72:73], v[74:75]
	s_nop 0
	v_add_f32_e32 v72, v72, v73
	v_fmamk_f32 v72, v72, 0x3a800000, v218
	v_cmp_gt_f32_e32 vcc, s26, v72
	v_mul_f32_e32 v73, 0x4b800000, v72
	s_nop 0
	v_cndmask_b32_e32 v72, v72, v73, vcc
	v_rsq_f32_e32 v72, v72
	s_nop 0
	v_mul_f32_e32 v73, 0x45800000, v72
	v_cndmask_b32_e32 v72, v72, v73, vcc
	ds_write_b32 v0, v72 offset:9216

;     __device__ bool next(int i, Unit& u) const { Unit b; if (!so.next(i >> 2, b)) return false; const int sub = i & 3; u.pm = b.pm; u.pn = sub * 4 + b.pn; u.acol = sub * 512; u.ord = i; return true; }
; __device__ __forceinline__ float row_rstd(const float* rowsq, size_t row) {
;     const f32x4* q = (const f32x4*)(rowsq + row * 16); const f32x4 a = q[0], b = q[1], c = q[2], d = q[3];
;     const float s = ((a[0] + a[1]) + (a[2] + a[3])) + ((b[0] + b[1]) + (b[2] + b[3])) + ((c[0] + c[1]) + (c[2] + c[3])) + ((d[0] + d[1]) + (d[2] + d[3]));
;     return rsqrtf(s * (1.f / DM) + EPS);
; }
; template <class Sched> __device__ __forceinline__ void rstd_prologue(const Sched& S, const float* rowsq, LAS float* rst) {
;     ...
;     for (int i = 0; i < 12 && S.next(i, u); ++i) if (t_ < 256) rst[i * 256 + t_] = pg8::row_rstd(rowsq, (size_t)u.pm * 256 + t_);
.Lmy_rsb_6_c3:
	s_and_saveexec_b64 s[24:25], s[36:37]
	s_cbranch_execz .Lmy_rsb_6_s2
	s_mov_b32 s26, 0x800000
	s_waitcnt vmcnt(2)
	v_add_f32_e32 v60, v60, v61
	v_add_f32_e32 v62, v62, v63
	s_waitcnt vmcnt(0)
	v_mov_b32_e32 v20, v69
	v_mov_b32_e32 v21, v70
	v_mov_b32_e32 v69, v71
	v_mov_b32_e32 v70, v65
	v_mov_b32_e32 v71, v66
	v_mov_b32_e32 v65, v67
	v_pk_add_f32 v[68:69], v[20:21], v[68:69]
	v_pk_add_f32 v[64:65], v[70:71], v[64:65]
	v_pk_add_f32 v[68:69], v[68:69], v[68:69] op_sel:[0,1] op_sel_hi:[1,0]
	v_pk_add_f32 v[64:65], v[64:65], v[64:65] op_sel:[0,1] op_sel_hi:[1,0]
	v_mov_b32_e32 v69, v56
	v_mov_b32_e32 v65, v57
	v_mov_b32_e32 v61, v58
	v_mov_b32_e32 v63, v59
	v_pk_add_f32 v[56:57], v[68:69], v[64:65]
	v_pk_add_f32 v[58:59], v[60:61], v[62:63]
	s_nop 0
	v_pk_add_f32 v[56:57], v[56:57], v[58:59]
	s_nop 0
	v_add_f32_e32 v56, v56, v57
	v_fmamk_f32 v56, v56, 0x3a800000, v218
	v_cmp_gt_f32_e32 vcc, s26, v56
	v_mul_f32_e32 v57, 0x4b800000, v56
	s_nop 0
	v_cndmask_b32_e32 v56, v56, v57, vcc
	v_rsq_f32_e32 v56, v56
	s_nop 0
	v_mul_f32_e32 v57, 0x45800000, v56
	v_cndmask_b32_e32 v56, v56, v57, vcc
	ds_write_b32 v0, v56 offset:8192

;     __device__ bool next(int i, Unit& u) const { Unit b; if (!so.next(i >> 2, b)) return false; const int sub = i & 3; u.pm = b.pm; u.pn = sub * 4 + b.pn; u.acol = sub * 512; u.ord = i; return true; }
; __device__ __forceinline__ float row_rstd(const float* rowsq, size_t row) {
;     const f32x4* q = (const f32x4*)(rowsq + row * 16); const f32x4 a = q[0], b = q[1], c = q[2], d = q[3];
;     const float s = ((a[0] + a[1]) + (a[2] + a[3])) + ((b[0] + b[1]) + (b[2] + b[3])) + ((c[0] + c[1]) + (c[2] + c[3])) + ((d[0] + d[1]) + (d[2] + d[3]));
;     return rsqrtf(s * (1.f / DM) + EPS);
; }
; template <class Sched> __device__ __forceinline__ void rstd_prologue(const Sched& S, const float* rowsq, LAS float* rst) {
;     ...
;     for (int i = 0; i < 12 && S.next(i, u); ++i) if (t_ < 256) rst[i * 256 + t_] = pg8::row_rstd(rowsq, (size_t)u.pm * 256 + t_);
.Lmy_rsb_6_c2:
	s_and_saveexec_b64 s[24:25], s[36:37]
	s_cbranch_execz .Lmy_rsb_6_s1
	s_mov_b32 s26, 0x800000
	s_waitcnt vmcnt(2)
	v_add_f32_e32 v44, v44, v45
	v_add_f32_e32 v46, v46, v47
	s_waitcnt vmcnt(0)
	v_mov_b32_e32 v20, v53
	v_mov_b32_e32 v21, v54
	v_mov_b32_e32 v53, v55
	v_mov_b32_e32 v54, v49
	v_mov_b32_e32 v55, v50
	v_mov_b32_e32 v49, v51
	v_pk_add_f32 v[52:53], v[20:21], v[52:53]
	v_pk_add_f32 v[48:49], v[54:55], v[48:49]
	v_pk_add_f32 v[52:53], v[52:53], v[52:53] op_sel:[0,1] op_sel_hi:[1,0]
	v_pk_add_f32 v[48:49], v[48:49], v[48:49] op_sel:[0,1] op_sel_hi:[1,0]
	v_mov_b32_e32 v53, v40
	v_mov_b32_e32 v49, v41
	v_mov_b32_e32 v45, v42
	v_mov_b32_e32 v47, v43
	v_pk_add_f32 v[40:41], v[52:53], v[48:49]
	v_pk_add_f32 v[42:43], v[44:45], v[46:47]
	s_nop 0
	v_pk_add_f32 v[40:41], v[40:41], v[42:43]
	s_nop 0
	v_add_f32_e32 v40, v40, v41
	v_fmamk_f32 v40, v40, 0x3a800000, v218
	v_cmp_gt_f32_e32 vcc, s26, v40
	v_mul_f32_e32 v41, 0x4b800000, v40
	s_nop 0
	v_cndmask_b32_e32 v40, v40, v41, vcc
	v_rsq_f32_e32 v40, v40
	s_nop 0
	v_mul_f32_e32 v41, 0x45800000, v40
	v_cndmask_b32_e32 v40, v40, v41, vcc
	ds_write_b32 v0, v40 offset:7168

;     __device__ bool next(int i, Unit& u) const { Unit b; if (!so.next(i >> 2, b)) return false; const int sub = i & 3; u.pm = b.pm; u.pn = sub * 4 + b.pn; u.acol = sub * 512; u.ord = i; return true; }
; __device__ __forceinline__ float row_rstd(const float* rowsq, size_t row) {
;     const f32x4* q = (const f32x4*)(rowsq + row * 16); const f32x4 a = q[0], b = q[1], c = q[2], d = q[3];
;     const float s = ((a[0] + a[1]) + (a[2] + a[3])) + ((b[0] + b[1]) + (b[2] + b[3])) + ((c[0] + c[1]) + (c[2] + c[3])) + ((d[0] + d[1]) + (d[2] + d[3]));
;     return rsqrtf(s * (1.f / DM) + EPS);
; }
; template <class Sched> __device__ __forceinline__ void rstd_prologue(const Sched& S, const float* rowsq, LAS float* rst) {
;     ...
;     for (int i = 0; i < 12 && S.next(i, u); ++i) if (t_ < 256) rst[i * 256 + t_] = pg8::row_rstd(rowsq, (size_t)u.pm * 256 + t_);
;     __syncthreads();
.Lmy_rsb_6_c1:
	s_and_saveexec_b64 s[24:25], s[36:37]
	s_cbranch_execz .Lmy_rsb_6_s0
	s_mov_b32 s26, 0x800000
	s_waitcnt vmcnt(2)
	v_add_f32_e32 v28, v28, v29
	v_add_f32_e32 v30, v30, v31
	s_waitcnt vmcnt(0)
	v_mov_b32_e32 v20, v37
	v_mov_b32_e32 v21, v38
	v_mov_b32_e32 v37, v39
	v_mov_b32_e32 v38, v33
	v_mov_b32_e32 v39, v34
	v_mov_b32_e32 v33, v35
	v_pk_add_f32 v[36:37], v[20:21], v[36:37]
	v_pk_add_f32 v[32:33], v[38:39], v[32:33]
	v_pk_add_f32 v[36:37], v[36:37], v[36:37] op_sel:[0,1] op_sel_hi:[1,0]
	v_pk_add_f32 v[32:33], v[32:33], v[32:33] op_sel:[0,1] op_sel_hi:[1,0]
	v_mov_b32_e32 v37, v24
	v_mov_b32_e32 v33, v25
	v_mov_b32_e32 v29, v26
	v_mov_b32_e32 v31, v27
	v_pk_add_f32 v[24:25], v[36:37], v[32:33]
	v_pk_add_f32 v[26:27], v[28:29], v[30:31]
	s_nop 0
	v_pk_add_f32 v[24:25], v[24:25], v[26:27]
	s_nop 0
	v_add_f32_e32 v24, v24, v25
	v_fmamk_f32 v24, v24, 0x3a800000, v218
	v_cmp_gt_f32_e32 vcc, s26, v24
	v_mul_f32_e32 v25, 0x4b800000, v24
	s_nop 0
	v_cndmask_b32_e32 v24, v24, v25, vcc
	v_rsq_f32_e32 v24, v24
	s_nop 0
	v_mul_f32_e32 v25, 0x45800000, v24
	v_cndmask_b32_e32 v24, v24, v25, vcc
	ds_write_b32 v0, v24 offset:6144
.Lmy_rsb_6_s0:
	s_or_b64 exec, exec, s[24:25]
.LBB0_421:
	s_or_b64 exec, exec, s[24:25]
	s_add_u32 s24, s2, s94
	s_addc_u32 s25, s3, s34
	v_cmp_lt_i64_e32 vcc, s[24:25], v[194:195]
	s_and_b64 s[26:27], vcc, s[36:37]
	s_and_saveexec_b64 s[2:3], s[26:27]
	s_cbranch_execz .LBB0_423
	s_ashr_i32 s25, s24, 31
	s_lshr_b32 s25, s25, 29
	s_add_i32 s25, s24, s25
	s_ashr_i32 s26, s25, 3
	s_and_b32 s25, s25, -8
	s_sub_i32 s24, s24, s25
	s_cmp_lt_i32 s24, 0
	s_movk_i32 s25, 0x121
	s_cselect_b32 s25, s25, 0x120
	s_mul_i32 s24, s24, s25
	s_add_i32 s24, s24, s26
	s_mul_hi_i32 s25, s24, 0x38e38e39
	s_lshr_b32 s26, s25, 31
	s_ashr_i32 s25, s25, 6
	s_add_i32 s25, s25, s26
	s_mul_i32 s26, s25, 0x120
	s_lshl_b32 s25, s25, 3
	s_sub_i32 s24, s24, s26
	s_sub_i32 s26, 64, s25
	s_min_i32 s26, s26, 8
	s_abs_i32 s26, s26
	v_cvt_f32_u32_e32 v4, s26
	s_sub_i32 s28, 0, s26
	s_ashr_i32 s27, s24, 31
	s_abs_i32 s24, s24
	v_rcp_iflag_f32_e32 v4, v4
	s_nop 0
	v_mul_f32_e32 v4, 0x4f7ffffe, v4
	v_cvt_u32_f32_e32 v4, v4
	s_nop 0
	v_readfirstlane_b32 s29, v4
	s_mul_i32 s28, s28, s29
	s_mul_hi_u32 s28, s29, s28
	s_add_i32 s29, s29, s28
	s_mul_hi_u32 s28, s24, s29
	s_mul_i32 s28, s28, s26
	s_sub_i32 s24, s24, s28
	s_sub_i32 s28, s24, s26
	s_cmp_ge_u32 s24, s26
	s_cselect_b32 s24, s28, s24
	s_sub_i32 s28, s24, s26
	s_cmp_ge_u32 s24, s26
	s_cselect_b32 s24, s28, s24
	s_xor_b32 s24, s24, s27
	s_sub_i32 s24, s24, s27
	s_add_i32 s24, s24, s25
	s_ashr_i32 s25, s24, 31
	s_lshl_b64 s[24:25], s[24:25], 14
	v_lshl_add_u64 v[14:15], v[2:3], 0, s[24:25]
	global_load_dwordx4 v[2:5], v[14:15], off offset:48
	global_load_dwordx4 v[6:9], v[14:15], off offset:32
	global_load_dwordx4 v[10:13], v[14:15], off offset:16
	s_nop 0
	global_load_dwordx4 v[14:17], v[14:15], off
	s_mov_b32 s24, 0x800000
	s_waitcnt vmcnt(2)
	v_add_f32_e32 v6, v6, v7
	v_add_f32_e32 v8, v8, v9
	s_waitcnt vmcnt(0)
	v_mov_b32_e32 v18, v15
	v_mov_b32_e32 v19, v16
	v_mov_b32_e32 v15, v17
	v_mov_b32_e32 v16, v11
	v_mov_b32_e32 v17, v12
	v_mov_b32_e32 v11, v13
	v_pk_add_f32 v[14:15], v[18:19], v[14:15]
	v_pk_add_f32 v[10:11], v[16:17], v[10:11]
	v_pk_add_f32 v[14:15], v[14:15], v[14:15] op_sel:[0,1] op_sel_hi:[1,0]
	v_pk_add_f32 v[10:11], v[10:11], v[10:11] op_sel:[0,1] op_sel_hi:[1,0]
	v_mov_b32_e32 v15, v2
	v_mov_b32_e32 v11, v3
	v_mov_b32_e32 v7, v4
	v_mov_b32_e32 v9, v5
	v_pk_add_f32 v[2:3], v[14:15], v[10:11]
	v_pk_add_f32 v[4:5], v[6:7], v[8:9]
	s_nop 0
	v_pk_add_f32 v[2:3], v[2:3], v[4:5]
	s_nop 0
	v_add_f32_e32 v2, v2, v3
	v_fmamk_f32 v2, v2, 0x3a800000, v218
	v_cmp_gt_f32_e32 vcc, s24, v2
	v_mul_f32_e32 v3, 0x4b800000, v2
	s_nop 0
	v_cndmask_b32_e32 v2, v2, v3, vcc
	v_rsq_f32_e32 v2, v2
	s_nop 0
	v_mul_f32_e32 v3, 0x45800000, v2
	v_cndmask_b32_e32 v2, v2, v3, vcc
	ds_write_b32 v0, v2 offset:11264

; __device__ __forceinline__ u32x4 pack8(const float* f) { u32x4 o; o.x = pk2(f[0], f[1]); o.y = pk2(f[2], f[3]); o.z = pk2(f[4], f[5]); o.w = pk2(f[6], f[7]); return o; }
; __device__ __forceinline__ float sigmoidf_(float x) { return rcpf(1.0f + __expf(-x)); }
; __device__ __forceinline__ float gelu_tanh(float v) { const float u = 0.7978845608f * (v + 0.044715f * v * v * v); return v * rcpf(1.0f + __expf(-2.0f * u)); }
;     __device__ __forceinline__ void operator()(const f32x4 (&acc)[2][2][4][2], const Unit& u, int wr, int wc, int fr, int fq) const {
;         const int row0 = u.pm * BM + wr * 64 + fr;
;         const int mode = u.pn < 4 ? 0 : (u.pn < 20 ? 1 : 2);
;         float rsv[2][4];
; #pragma unroll
;         for (int ai = 0; ai < 2; ++ai)
; #pragma unroll
;             for (int m = 0; m < 4; ++m) rsv[ai][m] = rst[u.ord * 256 + wr * 64 + fr + ai * HALF + m * 16];
; #pragma unroll
;         for (int ai = 0; ai < 2; ++ai)
; #pragma unroll
;             for (int m = 0; m < 4; ++m) { const size_t row = (size_t)(row0 + ai * HALF + m * 16); const float rs = rsv[ai][m];
; #pragma unroll
;                 for (int bj = 0; bj < 2; ++bj) { float o[8];
;                     const int c0 = u.pn * BM + bj * HALF + wc * 32 + 8 * fq;
; #pragma unroll
;                     for (int n = 0; n < 2; ++n)
; #pragma unroll
;                         for (int j = 0; j < 4; ++j) { const float v = acc[ai][bj][m][n][j] * rs; o[n * 4 + j] = mode == 0 ? gelu_tanh(v) : (mode == 1 ? v : sigmoidf_(v)); }
;                     if (mode == 2) { unsigned w0 = 0u, w1 = 0u;
; #pragma unroll
;                         for (int j = 0; j < 4; ++j) { w0 = __builtin_amdgcn_cvt_pk_u8_f32(fmaxf(o[j] * 255.f, 1.f), j, w0); w1 = __builtin_amdgcn_cvt_pk_u8_f32(fmaxf(o[4 + j] * 255.f, 1.f), j, w1); }
;                         u32x2 wv; wv.x = w0; wv.y = w1; *(u32x2*)(gates + row * 4096 + (c0 - 5120)) = wv; }
;                     else if (c0 < PLD) *(u32x4*)(proj + row * PLD + c0) = pack8(o); } }
.LBB0_438:
	s_cmp_lt_i32 s30, 20
	v_lshl_add_u32 v140, s39, 10, v150
	s_cselect_b32 s2, 1, 2
	ds_read2_b32 v[146:147], v140 offset1:16
	ds_read2_b32 v[144:145], v140 offset0:32 offset1:48
	ds_read2_b32 v[142:143], v140 offset0:128 offset1:144
	ds_read2_b32 v[140:141], v140 offset0:160 offset1:176
	s_cmp_gt_i32 s30, 3
	s_cselect_b32 s28, s2, 0
	s_mov_b64 s[64:65], s[88:89]
	v_lshl_add_u32 v153, s38, 8, v148
	s_cmp_eq_u32 s28, 2
	s_cbranch_scc1 .Lmy_ip_m2
	s_movk_i32 s2, 0x1320
	v_lshl_or_b32 v154, s30, 8, v151
	v_or_b32_e32 v155, 0x80, v154
	v_cmp_gt_i32_e64 s[24:25], s2, v154
	v_mul_lo_u32 v153, v153, s70
	v_cmp_gt_i32_e64 s[38:39], s2, v155
	v_lshl_add_u32 v153, v154, 1, v153
	s_cmp_eq_u32 s28, 1
	s_waitcnt lgkmcnt(0)
	s_cbranch_scc1 .Lmy_ip_m1
	s_mov_b32 s2, 0x3d372713
	s_mov_b32 s3, 0x3f4c422a
	s_mov_b32 s28, 0x3fb8aa3b
	v_mul_f32_e32 v126, v126, v146
	v_mul_f32_e32 v127, v127, v146
	v_mul_f32_e32 v128, v128, v146
	v_mul_f32_e32 v129, v129, v146
	v_mul_f32_e32 v122, v122, v146
	v_mul_f32_e32 v123, v123, v146
	v_mul_f32_e32 v124, v124, v146
	v_mul_f32_e32 v125, v125, v146
	v_mul_f32_e32 v156, s2, v126
	v_mul_f32_e32 v157, s2, v127
	v_mul_f32_e32 v158, s2, v128
	v_mul_f32_e32 v159, s2, v129
	v_mul_f32_e32 v160, s2, v122
	v_mul_f32_e32 v161, s2, v123
	v_mul_f32_e32 v162, s2, v124
	v_mul_f32_e32 v163, s2, v125
	v_mul_f32_e32 v156, v126, v156
	v_mul_f32_e32 v157, v127, v157
	v_mul_f32_e32 v158, v128, v158
	v_mul_f32_e32 v159, v129, v159
	v_mul_f32_e32 v160, v122, v160
	v_mul_f32_e32 v161, v123, v161
	v_mul_f32_e32 v162, v124, v162
	v_mul_f32_e32 v163, v125, v163
	v_fma_f32 v156, v126, v156, v126
	v_fma_f32 v157, v127, v157, v127
	v_fma_f32 v158, v128, v158, v128
	v_fma_f32 v159, v129, v159, v129
	v_fma_f32 v160, v122, v160, v122
	v_fma_f32 v161, v123, v161, v123
	v_fma_f32 v162, v124, v162, v124
	v_fma_f32 v163, v125, v163, v125
	v_mul_f32_e32 v156, s3, v156
	v_mul_f32_e32 v157, s3, v157
	v_mul_f32_e32 v158, s3, v158
	v_mul_f32_e32 v159, s3, v159
	v_mul_f32_e32 v160, s3, v160
	v_mul_f32_e32 v161, s3, v161
	v_mul_f32_e32 v162, s3, v162
	v_mul_f32_e32 v163, s3, v163
	v_mul_f32_e32 v156, -2.0, v156
	v_mul_f32_e32 v157, -2.0, v157
	v_mul_f32_e32 v158, -2.0, v158
	v_mul_f32_e32 v159, -2.0, v159
	v_mul_f32_e32 v160, -2.0, v160
	v_mul_f32_e32 v161, -2.0, v161
	v_mul_f32_e32 v162, -2.0, v162
	v_mul_f32_e32 v163, -2.0, v163
	v_mul_f32_e32 v156, s28, v156
	v_mul_f32_e32 v157, s28, v157
	v_mul_f32_e32 v158, s28, v158
	v_mul_f32_e32 v159, s28, v159
	v_mul_f32_e32 v160, s28, v160
	v_mul_f32_e32 v161, s28, v161
	v_mul_f32_e32 v162, s28, v162
	v_mul_f32_e32 v163, s28, v163
	v_exp_f32_e32 v156, v156
	v_exp_f32_e32 v157, v157
	v_exp_f32_e32 v158, v158
	v_exp_f32_e32 v159, v159
	v_exp_f32_e32 v160, v160
	v_exp_f32_e32 v161, v161
	v_exp_f32_e32 v162, v162
	v_exp_f32_e32 v163, v163
	v_add_f32_e32 v156, 1.0, v156
	v_add_f32_e32 v157, 1.0, v157
	v_add_f32_e32 v158, 1.0, v158
	v_add_f32_e32 v159, 1.0, v159
	v_add_f32_e32 v160, 1.0, v160
	v_add_f32_e32 v161, 1.0, v161
	v_add_f32_e32 v162, 1.0, v162
	v_add_f32_e32 v163, 1.0, v163
	v_rcp_f32_e32 v156, v156
	v_rcp_f32_e32 v157, v157
	v_rcp_f32_e32 v158, v158
	v_rcp_f32_e32 v159, v159
	v_rcp_f32_e32 v160, v160
	v_rcp_f32_e32 v161, v161
	v_rcp_f32_e32 v162, v162
	v_rcp_f32_e32 v163, v163
	v_mul_f32_e32 v126, v126, v156
	v_mul_f32_e32 v127, v127, v157
	v_mul_f32_e32 v128, v128, v158
	v_mul_f32_e32 v129, v129, v159
	v_mul_f32_e32 v122, v122, v160
	v_mul_f32_e32 v123, v123, v161
	v_mul_f32_e32 v124, v124, v162
	v_mul_f32_e32 v125, v125, v163
	v_cvt_pk_bf16_f32 v164, v126, v127
	v_cvt_pk_bf16_f32 v165, v128, v129
	v_cvt_pk_bf16_f32 v166, v122, v123
	v_cvt_pk_bf16_f32 v167, v124, v125
	s_mov_b64 exec, s[24:25]
	global_store_dwordx4 v153, v[164:167], s[68:69]
	s_mov_b64 exec, -1
	v_mul_f32_e32 v118, v118, v146
	v_mul_f32_e32 v119, v119, v146
	v_mul_f32_e32 v120, v120, v146
	v_mul_f32_e32 v121, v121, v146
	v_mul_f32_e32 v114, v114, v146
	v_mul_f32_e32 v115, v115, v146
	v_mul_f32_e32 v116, v116, v146
	v_mul_f32_e32 v117, v117, v146
	v_mul_f32_e32 v156, s2, v118
	v_mul_f32_e32 v157, s2, v119
	v_mul_f32_e32 v158, s2, v120
	v_mul_f32_e32 v159, s2, v121
	v_mul_f32_e32 v160, s2, v114
	v_mul_f32_e32 v161, s2, v115
	v_mul_f32_e32 v162, s2, v116
	v_mul_f32_e32 v163, s2, v117
	v_mul_f32_e32 v156, v118, v156
	v_mul_f32_e32 v157, v119, v157
	v_mul_f32_e32 v158, v120, v158
	v_mul_f32_e32 v159, v121, v159
	v_mul_f32_e32 v160, v114, v160
	v_mul_f32_e32 v161, v115, v161
	v_mul_f32_e32 v162, v116, v162
	v_mul_f32_e32 v163, v117, v163
	v_fma_f32 v156, v118, v156, v118
	v_fma_f32 v157, v119, v157, v119
	v_fma_f32 v158, v120, v158, v120
	v_fma_f32 v159, v121, v159, v121
	v_fma_f32 v160, v114, v160, v114
	v_fma_f32 v161, v115, v161, v115
	v_fma_f32 v162, v116, v162, v116
	v_fma_f32 v163, v117, v163, v117
	v_mul_f32_e32 v156, s3, v156
	v_mul_f32_e32 v157, s3, v157
	v_mul_f32_e32 v158, s3, v158
	v_mul_f32_e32 v159, s3, v159
	v_mul_f32_e32 v160, s3, v160
	v_mul_f32_e32 v161, s3, v161
	v_mul_f32_e32 v162, s3, v162
	v_mul_f32_e32 v163, s3, v163
	v_mul_f32_e32 v156, -2.0, v156
	v_mul_f32_e32 v157, -2.0, v157
	v_mul_f32_e32 v158, -2.0, v158
	v_mul_f32_e32 v159, -2.0, v159
	v_mul_f32_e32 v160, -2.0, v160
	v_mul_f32_e32 v161, -2.0, v161
	v_mul_f32_e32 v162, -2.0, v162
	v_mul_f32_e32 v163, -2.0, v163
	v_mul_f32_e32 v156, s28, v156
	v_mul_f32_e32 v157, s28, v157
	v_mul_f32_e32 v158, s28, v158
	v_mul_f32_e32 v159, s28, v159
	v_mul_f32_e32 v160, s28, v160
	v_mul_f32_e32 v161, s28, v161
	v_mul_f32_e32 v162, s28, v162
	v_mul_f32_e32 v163, s28, v163
	v_exp_f32_e32 v156, v156
	v_exp_f32_e32 v157, v157
	v_exp_f32_e32 v158, v158
	v_exp_f32_e32 v159, v159
; __device__ __forceinline__ u32x4 pack8(const float* f) { u32x4 o; o.x = pk2(f[0], f[1]); o.y = pk2(f[2], f[3]); o.z = pk2(f[4], f[5]); o.w = pk2(f[6], f[7]); return o; }
; __device__ __forceinline__ float sigmoidf_(float x) { return rcpf(1.0f + __expf(-x)); }
; __device__ __forceinline__ float gelu_tanh(float v) { const float u = 0.7978845608f * (v + 0.044715f * v * v * v); return v * rcpf(1.0f + __expf(-2.0f * u)); }
;     __device__ __forceinline__ void operator()(const f32x4 (&acc)[2][2][4][2], const Unit& u, int wr, int wc, int fr, int fq) const {
;     ...
;         for (int ai = 0; ai < 2; ++ai)
; #pragma unroll
;             for (int m = 0; m < 4; ++m) { const size_t row = (size_t)(row0 + ai * HALF + m * 16); const float rs = rsv[ai][m];
; #pragma unroll
;                 for (int bj = 0; bj < 2; ++bj) { float o[8];
;                     const int c0 = u.pn * BM + bj * HALF + wc * 32 + 8 * fq;
; #pragma unroll
;                     for (int n = 0; n < 2; ++n)
; #pragma unroll
;                         for (int j = 0; j < 4; ++j) { const float v = acc[ai][bj][m][n][j] * rs; o[n * 4 + j] = mode == 0 ? gelu_tanh(v) : (mode == 1 ? v : sigmoidf_(v)); }
;                     if (mode == 2) { unsigned w0 = 0u, w1 = 0u;
; #pragma unroll
;                         for (int j = 0; j < 4; ++j) { w0 = __builtin_amdgcn_cvt_pk_u8_f32(fmaxf(o[j] * 255.f, 1.f), j, w0); w1 = __builtin_amdgcn_cvt_pk_u8_f32(fmaxf(o[4 + j] * 255.f, 1.f), j, w1); }
;                         u32x2 wv; wv.x = w0; wv.y = w1; *(u32x2*)(gates + row * 4096 + (c0 - 5120)) = wv; }
;                     else if (c0 < PLD) *(u32x4*)(proj + row * PLD + c0) = pack8(o); } }
	v_exp_f32_e32 v160, v160
	v_exp_f32_e32 v161, v161
	v_exp_f32_e32 v162, v162
	v_exp_f32_e32 v163, v163
	v_add_f32_e32 v156, 1.0, v156
	v_add_f32_e32 v157, 1.0, v157
	v_add_f32_e32 v158, 1.0, v158
	v_add_f32_e32 v159, 1.0, v159
	v_add_f32_e32 v160, 1.0, v160
	v_add_f32_e32 v161, 1.0, v161
	v_add_f32_e32 v162, 1.0, v162
	v_add_f32_e32 v163, 1.0, v163
	v_rcp_f32_e32 v156, v156
	v_rcp_f32_e32 v157, v157
	v_rcp_f32_e32 v158, v158
	v_rcp_f32_e32 v159, v159
	v_rcp_f32_e32 v160, v160
	v_rcp_f32_e32 v161, v161
	v_rcp_f32_e32 v162, v162
	v_rcp_f32_e32 v163, v163
	v_mul_f32_e32 v118, v118, v156
	v_mul_f32_e32 v119, v119, v157
	v_mul_f32_e32 v120, v120, v158
	v_mul_f32_e32 v121, v121, v159
	v_mul_f32_e32 v114, v114, v160
	v_mul_f32_e32 v115, v115, v161
	v_mul_f32_e32 v116, v116, v162
	v_mul_f32_e32 v117, v117, v163
	v_cvt_pk_bf16_f32 v168, v118, v119
	v_cvt_pk_bf16_f32 v169, v120, v121
	v_cvt_pk_bf16_f32 v170, v114, v115
	v_cvt_pk_bf16_f32 v171, v116, v117
	s_mov_b64 exec, s[38:39]
	global_store_dwordx4 v153, v[168:171], s[68:69] offset:256
	s_mov_b64 exec, -1
	v_mul_f32_e32 v110, v110, v147
	v_mul_f32_e32 v111, v111, v147
	v_mul_f32_e32 v112, v112, v147
	v_mul_f32_e32 v113, v113, v147
	v_mul_f32_e32 v106, v106, v147
	v_mul_f32_e32 v107, v107, v147
	v_mul_f32_e32 v108, v108, v147
	v_mul_f32_e32 v109, v109, v147
	v_mul_f32_e32 v156, s2, v110
	v_mul_f32_e32 v157, s2, v111
	v_mul_f32_e32 v158, s2, v112
	v_mul_f32_e32 v159, s2, v113
	v_mul_f32_e32 v160, s2, v106
	v_mul_f32_e32 v161, s2, v107
	v_mul_f32_e32 v162, s2, v108
	v_mul_f32_e32 v163, s2, v109
	v_mul_f32_e32 v156, v110, v156
	v_mul_f32_e32 v157, v111, v157
	v_mul_f32_e32 v158, v112, v158
	v_mul_f32_e32 v159, v113, v159
	v_mul_f32_e32 v160, v106, v160
	v_mul_f32_e32 v161, v107, v161
	v_mul_f32_e32 v162, v108, v162
	v_mul_f32_e32 v163, v109, v163
	v_fma_f32 v156, v110, v156, v110
	v_fma_f32 v157, v111, v157, v111
	v_fma_f32 v158, v112, v158, v112
	v_fma_f32 v159, v113, v159, v113
	v_fma_f32 v160, v106, v160, v106
	v_fma_f32 v161, v107, v161, v107
	v_fma_f32 v162, v108, v162, v108
	v_fma_f32 v163, v109, v163, v109
	v_mul_f32_e32 v156, s3, v156
	v_mul_f32_e32 v157, s3, v157
	v_mul_f32_e32 v158, s3, v158
	v_mul_f32_e32 v159, s3, v159
	v_mul_f32_e32 v160, s3, v160
	v_mul_f32_e32 v161, s3, v161
	v_mul_f32_e32 v162, s3, v162
	v_mul_f32_e32 v163, s3, v163
	v_mul_f32_e32 v156, -2.0, v156
	v_mul_f32_e32 v157, -2.0, v157
	v_mul_f32_e32 v158, -2.0, v158
	v_mul_f32_e32 v159, -2.0, v159
	v_mul_f32_e32 v160, -2.0, v160
	v_mul_f32_e32 v161, -2.0, v161
	v_mul_f32_e32 v162, -2.0, v162
	v_mul_f32_e32 v163, -2.0, v163
	v_mul_f32_e32 v156, s28, v156
	v_mul_f32_e32 v157, s28, v157
	v_mul_f32_e32 v158, s28, v158
	v_mul_f32_e32 v159, s28, v159
	v_mul_f32_e32 v160, s28, v160
	v_mul_f32_e32 v161, s28, v161
	v_mul_f32_e32 v162, s28, v162
	v_mul_f32_e32 v163, s28, v163
	v_exp_f32_e32 v156, v156
	v_exp_f32_e32 v157, v157
	v_exp_f32_e32 v158, v158
	v_exp_f32_e32 v159, v159
	v_exp_f32_e32 v160, v160
	v_exp_f32_e32 v161, v161
	v_exp_f32_e32 v162, v162
	v_exp_f32_e32 v163, v163
	v_add_f32_e32 v156, 1.0, v156
	v_add_f32_e32 v157, 1.0, v157
	v_add_f32_e32 v158, 1.0, v158
	v_add_f32_e32 v159, 1.0, v159
	v_add_f32_e32 v160, 1.0, v160
	v_add_f32_e32 v161, 1.0, v161
	v_add_f32_e32 v162, 1.0, v162
	v_add_f32_e32 v163, 1.0, v163
	v_rcp_f32_e32 v156, v156
	v_rcp_f32_e32 v157, v157
	v_rcp_f32_e32 v158, v158
	v_rcp_f32_e32 v159, v159
	v_rcp_f32_e32 v160, v160
	v_rcp_f32_e32 v161, v161
	v_rcp_f32_e32 v162, v162
	v_rcp_f32_e32 v163, v163
	v_mul_f32_e32 v110, v110, v156
	v_mul_f32_e32 v111, v111, v157
	v_mul_f32_e32 v112, v112, v158
	v_mul_f32_e32 v113, v113, v159
	v_mul_f32_e32 v106, v106, v160
	v_mul_f32_e32 v107, v107, v161
	v_mul_f32_e32 v108, v108, v162
	v_mul_f32_e32 v109, v109, v163
	v_add_u32_e32 v153, 0x26400, v153
	v_cvt_pk_bf16_f32 v164, v110, v111
	v_cvt_pk_bf16_f32 v165, v112, v113
	v_cvt_pk_bf16_f32 v166, v106, v107
	v_cvt_pk_bf16_f32 v167, v108, v109
	s_mov_b64 exec, s[24:25]
	global_store_dwordx4 v153, v[164:167], s[68:69]
	s_mov_b64 exec, -1
	v_mul_f32_e32 v102, v102, v147
	v_mul_f32_e32 v103, v103, v147
	v_mul_f32_e32 v104, v104, v147
	v_mul_f32_e32 v105, v105, v147
	v_mul_f32_e32 v98, v98, v147
	v_mul_f32_e32 v99, v99, v147
	v_mul_f32_e32 v100, v100, v147
	v_mul_f32_e32 v101, v101, v147
	v_mul_f32_e32 v156, s2, v102
	v_mul_f32_e32 v157, s2, v103
	v_mul_f32_e32 v158, s2, v104
	v_mul_f32_e32 v159, s2, v105
	v_mul_f32_e32 v160, s2, v98
	v_mul_f32_e32 v161, s2, v99
	v_mul_f32_e32 v162, s2, v100
	v_mul_f32_e32 v163, s2, v101
	v_mul_f32_e32 v156, v102, v156
	v_mul_f32_e32 v157, v103, v157
	v_mul_f32_e32 v158, v104, v158
	v_mul_f32_e32 v159, v105, v159
	v_mul_f32_e32 v160, v98, v160
	v_mul_f32_e32 v161, v99, v161
	v_mul_f32_e32 v162, v100, v162
	v_mul_f32_e32 v163, v101, v163
	v_fma_f32 v156, v102, v156, v102
	v_fma_f32 v157, v103, v157, v103
	v_fma_f32 v158, v104, v158, v104
	v_fma_f32 v159, v105, v159, v105
	v_fma_f32 v160, v98, v160, v98
	v_fma_f32 v161, v99, v161, v99
	v_fma_f32 v162, v100, v162, v100
	v_fma_f32 v163, v101, v163, v101
	v_mul_f32_e32 v156, s3, v156
	v_mul_f32_e32 v157, s3, v157
	v_mul_f32_e32 v158, s3, v158
	v_mul_f32_e32 v159, s3, v159
	v_mul_f32_e32 v160, s3, v160
	v_mul_f32_e32 v161, s3, v161
	v_mul_f32_e32 v162, s3, v162
	v_mul_f32_e32 v163, s3, v163
	v_mul_f32_e32 v156, -2.0, v156
	v_mul_f32_e32 v157, -2.0, v157
	v_mul_f32_e32 v158, -2.0, v158
	v_mul_f32_e32 v159, -2.0, v159
	v_mul_f32_e32 v160, -2.0, v160
	v_mul_f32_e32 v161, -2.0, v161
	v_mul_f32_e32 v162, -2.0, v162
	v_mul_f32_e32 v163, -2.0, v163
	v_mul_f32_e32 v156, s28, v156
	v_mul_f32_e32 v157, s28, v157
	v_mul_f32_e32 v158, s28, v158
; __device__ __forceinline__ u32x4 pack8(const float* f) { u32x4 o; o.x = pk2(f[0], f[1]); o.y = pk2(f[2], f[3]); o.z = pk2(f[4], f[5]); o.w = pk2(f[6], f[7]); return o; }
; __device__ __forceinline__ float sigmoidf_(float x) { return rcpf(1.0f + __expf(-x)); }
; __device__ __forceinline__ float gelu_tanh(float v) { const float u = 0.7978845608f * (v + 0.044715f * v * v * v); return v * rcpf(1.0f + __expf(-2.0f * u)); }
;     __device__ __forceinline__ void operator()(const f32x4 (&acc)[2][2][4][2], const Unit& u, int wr, int wc, int fr, int fq) const {
;     ...
;         for (int ai = 0; ai < 2; ++ai)
; #pragma unroll
;             for (int m = 0; m < 4; ++m) { const size_t row = (size_t)(row0 + ai * HALF + m * 16); const float rs = rsv[ai][m];
; #pragma unroll
;                 for (int bj = 0; bj < 2; ++bj) { float o[8];
;                     const int c0 = u.pn * BM + bj * HALF + wc * 32 + 8 * fq;
; #pragma unroll
;                     for (int n = 0; n < 2; ++n)
; #pragma unroll
;                         for (int j = 0; j < 4; ++j) { const float v = acc[ai][bj][m][n][j] * rs; o[n * 4 + j] = mode == 0 ? gelu_tanh(v) : (mode == 1 ? v : sigmoidf_(v)); }
;                     if (mode == 2) { unsigned w0 = 0u, w1 = 0u;
; #pragma unroll
;                         for (int j = 0; j < 4; ++j) { w0 = __builtin_amdgcn_cvt_pk_u8_f32(fmaxf(o[j] * 255.f, 1.f), j, w0); w1 = __builtin_amdgcn_cvt_pk_u8_f32(fmaxf(o[4 + j] * 255.f, 1.f), j, w1); }
;                         u32x2 wv; wv.x = w0; wv.y = w1; *(u32x2*)(gates + row * 4096 + (c0 - 5120)) = wv; }
;                     else if (c0 < PLD) *(u32x4*)(proj + row * PLD + c0) = pack8(o); } }
	v_mul_f32_e32 v159, s28, v159
	v_mul_f32_e32 v160, s28, v160
	v_mul_f32_e32 v161, s28, v161
	v_mul_f32_e32 v162, s28, v162
	v_mul_f32_e32 v163, s28, v163
	v_exp_f32_e32 v156, v156
	v_exp_f32_e32 v157, v157
	v_exp_f32_e32 v158, v158
	v_exp_f32_e32 v159, v159
	v_exp_f32_e32 v160, v160
	v_exp_f32_e32 v161, v161
	v_exp_f32_e32 v162, v162
	v_exp_f32_e32 v163, v163
	v_add_f32_e32 v156, 1.0, v156
	v_add_f32_e32 v157, 1.0, v157
	v_add_f32_e32 v158, 1.0, v158
	v_add_f32_e32 v159, 1.0, v159
	v_add_f32_e32 v160, 1.0, v160
	v_add_f32_e32 v161, 1.0, v161
	v_add_f32_e32 v162, 1.0, v162
	v_add_f32_e32 v163, 1.0, v163
	v_rcp_f32_e32 v156, v156
	v_rcp_f32_e32 v157, v157
	v_rcp_f32_e32 v158, v158
	v_rcp_f32_e32 v159, v159
	v_rcp_f32_e32 v160, v160
	v_rcp_f32_e32 v161, v161
	v_rcp_f32_e32 v162, v162
	v_rcp_f32_e32 v163, v163
	v_mul_f32_e32 v102, v102, v156
	v_mul_f32_e32 v103, v103, v157
	v_mul_f32_e32 v104, v104, v158
	v_mul_f32_e32 v105, v105, v159
	v_mul_f32_e32 v98, v98, v160
	v_mul_f32_e32 v99, v99, v161
	v_mul_f32_e32 v100, v100, v162
	v_mul_f32_e32 v101, v101, v163
	v_cvt_pk_bf16_f32 v168, v102, v103
	v_cvt_pk_bf16_f32 v169, v104, v105
	v_cvt_pk_bf16_f32 v170, v98, v99
	v_cvt_pk_bf16_f32 v171, v100, v101
	s_mov_b64 exec, s[38:39]
	global_store_dwordx4 v153, v[168:171], s[68:69] offset:256
	s_mov_b64 exec, -1
	v_mul_f32_e32 v94, v94, v144
	v_mul_f32_e32 v95, v95, v144
	v_mul_f32_e32 v96, v96, v144
	v_mul_f32_e32 v97, v97, v144
	v_mul_f32_e32 v90, v90, v144
	v_mul_f32_e32 v91, v91, v144
	v_mul_f32_e32 v92, v92, v144
	v_mul_f32_e32 v93, v93, v144
	v_mul_f32_e32 v156, s2, v94
	v_mul_f32_e32 v157, s2, v95
	v_mul_f32_e32 v158, s2, v96
	v_mul_f32_e32 v159, s2, v97
	v_mul_f32_e32 v160, s2, v90
	v_mul_f32_e32 v161, s2, v91
	v_mul_f32_e32 v162, s2, v92
	v_mul_f32_e32 v163, s2, v93
	v_mul_f32_e32 v156, v94, v156
	v_mul_f32_e32 v157, v95, v157
	v_mul_f32_e32 v158, v96, v158
	v_mul_f32_e32 v159, v97, v159
	v_mul_f32_e32 v160, v90, v160
	v_mul_f32_e32 v161, v91, v161
	v_mul_f32_e32 v162, v92, v162
	v_mul_f32_e32 v163, v93, v163
	v_fma_f32 v156, v94, v156, v94
	v_fma_f32 v157, v95, v157, v95
	v_fma_f32 v158, v96, v158, v96
	v_fma_f32 v159, v97, v159, v97
	v_fma_f32 v160, v90, v160, v90
	v_fma_f32 v161, v91, v161, v91
	v_fma_f32 v162, v92, v162, v92
	v_fma_f32 v163, v93, v163, v93
	v_mul_f32_e32 v156, s3, v156
	v_mul_f32_e32 v157, s3, v157
	v_mul_f32_e32 v158, s3, v158
	v_mul_f32_e32 v159, s3, v159
	v_mul_f32_e32 v160, s3, v160
	v_mul_f32_e32 v161, s3, v161
	v_mul_f32_e32 v162, s3, v162
	v_mul_f32_e32 v163, s3, v163
	v_mul_f32_e32 v156, -2.0, v156
	v_mul_f32_e32 v157, -2.0, v157
	v_mul_f32_e32 v158, -2.0, v158
	v_mul_f32_e32 v159, -2.0, v159
	v_mul_f32_e32 v160, -2.0, v160
	v_mul_f32_e32 v161, -2.0, v161
	v_mul_f32_e32 v162, -2.0, v162
	v_mul_f32_e32 v163, -2.0, v163
	v_mul_f32_e32 v156, s28, v156
	v_mul_f32_e32 v157, s28, v157
	v_mul_f32_e32 v158, s28, v158
	v_mul_f32_e32 v159, s28, v159
	v_mul_f32_e32 v160, s28, v160
	v_mul_f32_e32 v161, s28, v161
	v_mul_f32_e32 v162, s28, v162
	v_mul_f32_e32 v163, s28, v163
	v_exp_f32_e32 v156, v156
	v_exp_f32_e32 v157, v157
	v_exp_f32_e32 v158, v158
	v_exp_f32_e32 v159, v159
	v_exp_f32_e32 v160, v160
	v_exp_f32_e32 v161, v161
	v_exp_f32_e32 v162, v162
	v_exp_f32_e32 v163, v163
	v_add_f32_e32 v156, 1.0, v156
	v_add_f32_e32 v157, 1.0, v157
	v_add_f32_e32 v158, 1.0, v158
	v_add_f32_e32 v159, 1.0, v159
	v_add_f32_e32 v160, 1.0, v160
	v_add_f32_e32 v161, 1.0, v161
	v_add_f32_e32 v162, 1.0, v162
	v_add_f32_e32 v163, 1.0, v163
	v_rcp_f32_e32 v156, v156
	v_rcp_f32_e32 v157, v157
	v_rcp_f32_e32 v158, v158
	v_rcp_f32_e32 v159, v159
	v_rcp_f32_e32 v160, v160
	v_rcp_f32_e32 v161, v161
	v_rcp_f32_e32 v162, v162
	v_rcp_f32_e32 v163, v163
	v_mul_f32_e32 v94, v94, v156
	v_mul_f32_e32 v95, v95, v157
	v_mul_f32_e32 v96, v96, v158
	v_mul_f32_e32 v97, v97, v159
	v_mul_f32_e32 v90, v90, v160
	v_mul_f32_e32 v91, v91, v161
	v_mul_f32_e32 v92, v92, v162
	v_mul_f32_e32 v93, v93, v163
	v_add_u32_e32 v153, 0x26400, v153
	v_cvt_pk_bf16_f32 v164, v94, v95
	v_cvt_pk_bf16_f32 v165, v96, v97
	v_cvt_pk_bf16_f32 v166, v90, v91
	v_cvt_pk_bf16_f32 v167, v92, v93
	s_mov_b64 exec, s[24:25]
	global_store_dwordx4 v153, v[164:167], s[68:69]
	s_mov_b64 exec, -1
	v_mul_f32_e32 v86, v86, v144
	v_mul_f32_e32 v87, v87, v144
	v_mul_f32_e32 v88, v88, v144
	v_mul_f32_e32 v89, v89, v144
	v_mul_f32_e32 v82, v82, v144
	v_mul_f32_e32 v83, v83, v144
	v_mul_f32_e32 v84, v84, v144
	v_mul_f32_e32 v85, v85, v144
	v_mul_f32_e32 v156, s2, v86
	v_mul_f32_e32 v157, s2, v87
	v_mul_f32_e32 v158, s2, v88
	v_mul_f32_e32 v159, s2, v89
	v_mul_f32_e32 v160, s2, v82
	v_mul_f32_e32 v161, s2, v83
	v_mul_f32_e32 v162, s2, v84
	v_mul_f32_e32 v163, s2, v85
	v_mul_f32_e32 v156, v86, v156
	v_mul_f32_e32 v157, v87, v157
	v_mul_f32_e32 v158, v88, v158
	v_mul_f32_e32 v159, v89, v159
	v_mul_f32_e32 v160, v82, v160
	v_mul_f32_e32 v161, v83, v161
	v_mul_f32_e32 v162, v84, v162
	v_mul_f32_e32 v163, v85, v163
	v_fma_f32 v156, v86, v156, v86
	v_fma_f32 v157, v87, v157, v87
	v_fma_f32 v158, v88, v158, v88
	v_fma_f32 v159, v89, v159, v89
	v_fma_f32 v160, v82, v160, v82
	v_fma_f32 v161, v83, v161, v83
	v_fma_f32 v162, v84, v162, v84
	v_fma_f32 v163, v85, v163, v85
	v_mul_f32_e32 v156, s3, v156
	v_mul_f32_e32 v157, s3, v157
	v_mul_f32_e32 v158, s3, v158
	v_mul_f32_e32 v159, s3, v159
	v_mul_f32_e32 v160, s3, v160
	v_mul_f32_e32 v161, s3, v161
	v_mul_f32_e32 v162, s3, v162
	v_mul_f32_e32 v163, s3, v163
	v_mul_f32_e32 v156, -2.0, v156
	v_mul_f32_e32 v157, -2.0, v157
	v_mul_f32_e32 v158, -2.0, v158
	v_mul_f32_e32 v159, -2.0, v159
	v_mul_f32_e32 v160, -2.0, v160
	v_mul_f32_e32 v161, -2.0, v161
	v_mul_f32_e32 v162, -2.0, v162
; __device__ __forceinline__ u32x4 pack8(const float* f) { u32x4 o; o.x = pk2(f[0], f[1]); o.y = pk2(f[2], f[3]); o.z = pk2(f[4], f[5]); o.w = pk2(f[6], f[7]); return o; }
; __device__ __forceinline__ float sigmoidf_(float x) { return rcpf(1.0f + __expf(-x)); }
; __device__ __forceinline__ float gelu_tanh(float v) { const float u = 0.7978845608f * (v + 0.044715f * v * v * v); return v * rcpf(1.0f + __expf(-2.0f * u)); }
;     __device__ __forceinline__ void operator()(const f32x4 (&acc)[2][2][4][2], const Unit& u, int wr, int wc, int fr, int fq) const {
;     ...
;         for (int ai = 0; ai < 2; ++ai)
; #pragma unroll
;             for (int m = 0; m < 4; ++m) { const size_t row = (size_t)(row0 + ai * HALF + m * 16); const float rs = rsv[ai][m];
; #pragma unroll
;                 for (int bj = 0; bj < 2; ++bj) { float o[8];
;                     const int c0 = u.pn * BM + bj * HALF + wc * 32 + 8 * fq;
; #pragma unroll
;                     for (int n = 0; n < 2; ++n)
; #pragma unroll
;                         for (int j = 0; j < 4; ++j) { const float v = acc[ai][bj][m][n][j] * rs; o[n * 4 + j] = mode == 0 ? gelu_tanh(v) : (mode == 1 ? v : sigmoidf_(v)); }
;                     if (mode == 2) { unsigned w0 = 0u, w1 = 0u;
; #pragma unroll
;                         for (int j = 0; j < 4; ++j) { w0 = __builtin_amdgcn_cvt_pk_u8_f32(fmaxf(o[j] * 255.f, 1.f), j, w0); w1 = __builtin_amdgcn_cvt_pk_u8_f32(fmaxf(o[4 + j] * 255.f, 1.f), j, w1); }
;                         u32x2 wv; wv.x = w0; wv.y = w1; *(u32x2*)(gates + row * 4096 + (c0 - 5120)) = wv; }
;                     else if (c0 < PLD) *(u32x4*)(proj + row * PLD + c0) = pack8(o); } }
	v_mul_f32_e32 v163, -2.0, v163
	v_mul_f32_e32 v156, s28, v156
	v_mul_f32_e32 v157, s28, v157
	v_mul_f32_e32 v158, s28, v158
	v_mul_f32_e32 v159, s28, v159
	v_mul_f32_e32 v160, s28, v160
	v_mul_f32_e32 v161, s28, v161
	v_mul_f32_e32 v162, s28, v162
	v_mul_f32_e32 v163, s28, v163
	v_exp_f32_e32 v156, v156
	v_exp_f32_e32 v157, v157
	v_exp_f32_e32 v158, v158
	v_exp_f32_e32 v159, v159
	v_exp_f32_e32 v160, v160
	v_exp_f32_e32 v161, v161
	v_exp_f32_e32 v162, v162
	v_exp_f32_e32 v163, v163
	v_add_f32_e32 v156, 1.0, v156
	v_add_f32_e32 v157, 1.0, v157
	v_add_f32_e32 v158, 1.0, v158
	v_add_f32_e32 v159, 1.0, v159
	v_add_f32_e32 v160, 1.0, v160
	v_add_f32_e32 v161, 1.0, v161
	v_add_f32_e32 v162, 1.0, v162
	v_add_f32_e32 v163, 1.0, v163
	v_rcp_f32_e32 v156, v156
	v_rcp_f32_e32 v157, v157
	v_rcp_f32_e32 v158, v158
	v_rcp_f32_e32 v159, v159
	v_rcp_f32_e32 v160, v160
	v_rcp_f32_e32 v161, v161
	v_rcp_f32_e32 v162, v162
	v_rcp_f32_e32 v163, v163
	v_mul_f32_e32 v86, v86, v156
	v_mul_f32_e32 v87, v87, v157
	v_mul_f32_e32 v88, v88, v158
	v_mul_f32_e32 v89, v89, v159
	v_mul_f32_e32 v82, v82, v160
	v_mul_f32_e32 v83, v83, v161
	v_mul_f32_e32 v84, v84, v162
	v_mul_f32_e32 v85, v85, v163
	v_cvt_pk_bf16_f32 v168, v86, v87
	v_cvt_pk_bf16_f32 v169, v88, v89
	v_cvt_pk_bf16_f32 v170, v82, v83
	v_cvt_pk_bf16_f32 v171, v84, v85
	s_mov_b64 exec, s[38:39]
	global_store_dwordx4 v153, v[168:171], s[68:69] offset:256
	s_mov_b64 exec, -1
	v_mul_f32_e32 v78, v78, v145
	v_mul_f32_e32 v79, v79, v145
	v_mul_f32_e32 v80, v80, v145
	v_mul_f32_e32 v81, v81, v145
	v_mul_f32_e32 v74, v74, v145
	v_mul_f32_e32 v75, v75, v145
	v_mul_f32_e32 v76, v76, v145
	v_mul_f32_e32 v77, v77, v145
	v_mul_f32_e32 v156, s2, v78
	v_mul_f32_e32 v157, s2, v79
	v_mul_f32_e32 v158, s2, v80
	v_mul_f32_e32 v159, s2, v81
	v_mul_f32_e32 v160, s2, v74
	v_mul_f32_e32 v161, s2, v75
	v_mul_f32_e32 v162, s2, v76
	v_mul_f32_e32 v163, s2, v77
	v_mul_f32_e32 v156, v78, v156
	v_mul_f32_e32 v157, v79, v157
	v_mul_f32_e32 v158, v80, v158
	v_mul_f32_e32 v159, v81, v159
	v_mul_f32_e32 v160, v74, v160
	v_mul_f32_e32 v161, v75, v161
	v_mul_f32_e32 v162, v76, v162
	v_mul_f32_e32 v163, v77, v163
	v_fma_f32 v156, v78, v156, v78
	v_fma_f32 v157, v79, v157, v79
	v_fma_f32 v158, v80, v158, v80
	v_fma_f32 v159, v81, v159, v81
	v_fma_f32 v160, v74, v160, v74
	v_fma_f32 v161, v75, v161, v75
	v_fma_f32 v162, v76, v162, v76
	v_fma_f32 v163, v77, v163, v77
	v_mul_f32_e32 v156, s3, v156
	v_mul_f32_e32 v157, s3, v157
	v_mul_f32_e32 v158, s3, v158
	v_mul_f32_e32 v159, s3, v159
	v_mul_f32_e32 v160, s3, v160
	v_mul_f32_e32 v161, s3, v161
	v_mul_f32_e32 v162, s3, v162
	v_mul_f32_e32 v163, s3, v163
	v_mul_f32_e32 v156, -2.0, v156
	v_mul_f32_e32 v157, -2.0, v157
	v_mul_f32_e32 v158, -2.0, v158
	v_mul_f32_e32 v159, -2.0, v159
	v_mul_f32_e32 v160, -2.0, v160
	v_mul_f32_e32 v161, -2.0, v161
	v_mul_f32_e32 v162, -2.0, v162
	v_mul_f32_e32 v163, -2.0, v163
	v_mul_f32_e32 v156, s28, v156
	v_mul_f32_e32 v157, s28, v157
	v_mul_f32_e32 v158, s28, v158
	v_mul_f32_e32 v159, s28, v159
	v_mul_f32_e32 v160, s28, v160
	v_mul_f32_e32 v161, s28, v161
	v_mul_f32_e32 v162, s28, v162
	v_mul_f32_e32 v163, s28, v163
	v_exp_f32_e32 v156, v156
	v_exp_f32_e32 v157, v157
	v_exp_f32_e32 v158, v158
	v_exp_f32_e32 v159, v159
	v_exp_f32_e32 v160, v160
	v_exp_f32_e32 v161, v161
	v_exp_f32_e32 v162, v162
	v_exp_f32_e32 v163, v163
	v_add_f32_e32 v156, 1.0, v156
	v_add_f32_e32 v157, 1.0, v157
	v_add_f32_e32 v158, 1.0, v158
	v_add_f32_e32 v159, 1.0, v159
	v_add_f32_e32 v160, 1.0, v160
	v_add_f32_e32 v161, 1.0, v161
	v_add_f32_e32 v162, 1.0, v162
	v_add_f32_e32 v163, 1.0, v163
	v_rcp_f32_e32 v156, v156
	v_rcp_f32_e32 v157, v157
	v_rcp_f32_e32 v158, v158
	v_rcp_f32_e32 v159, v159
	v_rcp_f32_e32 v160, v160
	v_rcp_f32_e32 v161, v161
	v_rcp_f32_e32 v162, v162
	v_rcp_f32_e32 v163, v163
	v_mul_f32_e32 v78, v78, v156
	v_mul_f32_e32 v79, v79, v157
	v_mul_f32_e32 v80, v80, v158
	v_mul_f32_e32 v81, v81, v159
	v_mul_f32_e32 v74, v74, v160
	v_mul_f32_e32 v75, v75, v161
	v_mul_f32_e32 v76, v76, v162
	v_mul_f32_e32 v77, v77, v163
	v_add_u32_e32 v153, 0x26400, v153
	v_cvt_pk_bf16_f32 v164, v78, v79
	v_cvt_pk_bf16_f32 v165, v80, v81
	v_cvt_pk_bf16_f32 v166, v74, v75
	v_cvt_pk_bf16_f32 v167, v76, v77
	s_mov_b64 exec, s[24:25]
	global_store_dwordx4 v153, v[164:167], s[68:69]
	s_mov_b64 exec, -1
	v_mul_f32_e32 v70, v70, v145
	v_mul_f32_e32 v71, v71, v145
	v_mul_f32_e32 v72, v72, v145
	v_mul_f32_e32 v73, v73, v145
	v_mul_f32_e32 v66, v66, v145
	v_mul_f32_e32 v67, v67, v145
	v_mul_f32_e32 v68, v68, v145
	v_mul_f32_e32 v69, v69, v145
	v_mul_f32_e32 v156, s2, v70
	v_mul_f32_e32 v157, s2, v71
	v_mul_f32_e32 v158, s2, v72
	v_mul_f32_e32 v159, s2, v73
	v_mul_f32_e32 v160, s2, v66
	v_mul_f32_e32 v161, s2, v67
	v_mul_f32_e32 v162, s2, v68
	v_mul_f32_e32 v163, s2, v69
	v_mul_f32_e32 v156, v70, v156
	v_mul_f32_e32 v157, v71, v157
	v_mul_f32_e32 v158, v72, v158
	v_mul_f32_e32 v159, v73, v159
	v_mul_f32_e32 v160, v66, v160
	v_mul_f32_e32 v161, v67, v161
	v_mul_f32_e32 v162, v68, v162
	v_mul_f32_e32 v163, v69, v163
	v_fma_f32 v156, v70, v156, v70
	v_fma_f32 v157, v71, v157, v71
	v_fma_f32 v158, v72, v158, v72
	v_fma_f32 v159, v73, v159, v73
	v_fma_f32 v160, v66, v160, v66
	v_fma_f32 v161, v67, v161, v67
	v_fma_f32 v162, v68, v162, v68
	v_fma_f32 v163, v69, v163, v69
	v_mul_f32_e32 v156, s3, v156
	v_mul_f32_e32 v157, s3, v157
	v_mul_f32_e32 v158, s3, v158
	v_mul_f32_e32 v159, s3, v159
	v_mul_f32_e32 v160, s3, v160
	v_mul_f32_e32 v161, s3, v161
	v_mul_f32_e32 v162, s3, v162
	v_mul_f32_e32 v163, s3, v163
	v_mul_f32_e32 v156, -2.0, v156
	v_mul_f32_e32 v157, -2.0, v157
	v_mul_f32_e32 v158, -2.0, v158
; __device__ __forceinline__ u32x4 pack8(const float* f) { u32x4 o; o.x = pk2(f[0], f[1]); o.y = pk2(f[2], f[3]); o.z = pk2(f[4], f[5]); o.w = pk2(f[6], f[7]); return o; }
; __device__ __forceinline__ float sigmoidf_(float x) { return rcpf(1.0f + __expf(-x)); }
; __device__ __forceinline__ float gelu_tanh(float v) { const float u = 0.7978845608f * (v + 0.044715f * v * v * v); return v * rcpf(1.0f + __expf(-2.0f * u)); }
;     __device__ __forceinline__ void operator()(const f32x4 (&acc)[2][2][4][2], const Unit& u, int wr, int wc, int fr, int fq) const {
;     ...
;         for (int ai = 0; ai < 2; ++ai)
; #pragma unroll
;             for (int m = 0; m < 4; ++m) { const size_t row = (size_t)(row0 + ai * HALF + m * 16); const float rs = rsv[ai][m];
; #pragma unroll
;                 for (int bj = 0; bj < 2; ++bj) { float o[8];
;                     const int c0 = u.pn * BM + bj * HALF + wc * 32 + 8 * fq;
; #pragma unroll
;                     for (int n = 0; n < 2; ++n)
; #pragma unroll
;                         for (int j = 0; j < 4; ++j) { const float v = acc[ai][bj][m][n][j] * rs; o[n * 4 + j] = mode == 0 ? gelu_tanh(v) : (mode == 1 ? v : sigmoidf_(v)); }
;                     if (mode == 2) { unsigned w0 = 0u, w1 = 0u;
; #pragma unroll
;                         for (int j = 0; j < 4; ++j) { w0 = __builtin_amdgcn_cvt_pk_u8_f32(fmaxf(o[j] * 255.f, 1.f), j, w0); w1 = __builtin_amdgcn_cvt_pk_u8_f32(fmaxf(o[4 + j] * 255.f, 1.f), j, w1); }
;                         u32x2 wv; wv.x = w0; wv.y = w1; *(u32x2*)(gates + row * 4096 + (c0 - 5120)) = wv; }
;                     else if (c0 < PLD) *(u32x4*)(proj + row * PLD + c0) = pack8(o); } }
	v_mul_f32_e32 v159, -2.0, v159
	v_mul_f32_e32 v160, -2.0, v160
	v_mul_f32_e32 v161, -2.0, v161
	v_mul_f32_e32 v162, -2.0, v162
	v_mul_f32_e32 v163, -2.0, v163
	v_mul_f32_e32 v156, s28, v156
	v_mul_f32_e32 v157, s28, v157
	v_mul_f32_e32 v158, s28, v158
	v_mul_f32_e32 v159, s28, v159
	v_mul_f32_e32 v160, s28, v160
	v_mul_f32_e32 v161, s28, v161
	v_mul_f32_e32 v162, s28, v162
	v_mul_f32_e32 v163, s28, v163
	v_exp_f32_e32 v156, v156
	v_exp_f32_e32 v157, v157
	v_exp_f32_e32 v158, v158
	v_exp_f32_e32 v159, v159
	v_exp_f32_e32 v160, v160
	v_exp_f32_e32 v161, v161
	v_exp_f32_e32 v162, v162
	v_exp_f32_e32 v163, v163
	v_add_f32_e32 v156, 1.0, v156
	v_add_f32_e32 v157, 1.0, v157
	v_add_f32_e32 v158, 1.0, v158
	v_add_f32_e32 v159, 1.0, v159
	v_add_f32_e32 v160, 1.0, v160
	v_add_f32_e32 v161, 1.0, v161
	v_add_f32_e32 v162, 1.0, v162
	v_add_f32_e32 v163, 1.0, v163
	v_rcp_f32_e32 v156, v156
	v_rcp_f32_e32 v157, v157
	v_rcp_f32_e32 v158, v158
	v_rcp_f32_e32 v159, v159
	v_rcp_f32_e32 v160, v160
	v_rcp_f32_e32 v161, v161
	v_rcp_f32_e32 v162, v162
	v_rcp_f32_e32 v163, v163
	v_mul_f32_e32 v70, v70, v156
	v_mul_f32_e32 v71, v71, v157
	v_mul_f32_e32 v72, v72, v158
	v_mul_f32_e32 v73, v73, v159
	v_mul_f32_e32 v66, v66, v160
	v_mul_f32_e32 v67, v67, v161
	v_mul_f32_e32 v68, v68, v162
	v_mul_f32_e32 v69, v69, v163
	v_cvt_pk_bf16_f32 v168, v70, v71
	v_cvt_pk_bf16_f32 v169, v72, v73
	v_cvt_pk_bf16_f32 v170, v66, v67
	v_cvt_pk_bf16_f32 v171, v68, v69
	s_mov_b64 exec, s[38:39]
	global_store_dwordx4 v153, v[168:171], s[68:69] offset:256
	s_mov_b64 exec, -1
	v_mul_f32_e32 v62, v62, v142
	v_mul_f32_e32 v63, v63, v142
	v_mul_f32_e32 v64, v64, v142
	v_mul_f32_e32 v65, v65, v142
	v_mul_f32_e32 v58, v58, v142
	v_mul_f32_e32 v59, v59, v142
	v_mul_f32_e32 v60, v60, v142
	v_mul_f32_e32 v61, v61, v142
	v_mul_f32_e32 v156, s2, v62
	v_mul_f32_e32 v157, s2, v63
	v_mul_f32_e32 v158, s2, v64
	v_mul_f32_e32 v159, s2, v65
	v_mul_f32_e32 v160, s2, v58
	v_mul_f32_e32 v161, s2, v59
	v_mul_f32_e32 v162, s2, v60
	v_mul_f32_e32 v163, s2, v61
	v_mul_f32_e32 v156, v62, v156
	v_mul_f32_e32 v157, v63, v157
	v_mul_f32_e32 v158, v64, v158
	v_mul_f32_e32 v159, v65, v159
	v_mul_f32_e32 v160, v58, v160
	v_mul_f32_e32 v161, v59, v161
	v_mul_f32_e32 v162, v60, v162
	v_mul_f32_e32 v163, v61, v163
	v_fma_f32 v156, v62, v156, v62
	v_fma_f32 v157, v63, v157, v63
	v_fma_f32 v158, v64, v158, v64
	v_fma_f32 v159, v65, v159, v65
	v_fma_f32 v160, v58, v160, v58
	v_fma_f32 v161, v59, v161, v59
	v_fma_f32 v162, v60, v162, v60
	v_fma_f32 v163, v61, v163, v61
	v_mul_f32_e32 v156, s3, v156
	v_mul_f32_e32 v157, s3, v157
	v_mul_f32_e32 v158, s3, v158
	v_mul_f32_e32 v159, s3, v159
	v_mul_f32_e32 v160, s3, v160
	v_mul_f32_e32 v161, s3, v161
	v_mul_f32_e32 v162, s3, v162
	v_mul_f32_e32 v163, s3, v163
	v_mul_f32_e32 v156, -2.0, v156
	v_mul_f32_e32 v157, -2.0, v157
	v_mul_f32_e32 v158, -2.0, v158
	v_mul_f32_e32 v159, -2.0, v159
	v_mul_f32_e32 v160, -2.0, v160
	v_mul_f32_e32 v161, -2.0, v161
	v_mul_f32_e32 v162, -2.0, v162
	v_mul_f32_e32 v163, -2.0, v163
	v_mul_f32_e32 v156, s28, v156
	v_mul_f32_e32 v157, s28, v157
	v_mul_f32_e32 v158, s28, v158
	v_mul_f32_e32 v159, s28, v159
	v_mul_f32_e32 v160, s28, v160
	v_mul_f32_e32 v161, s28, v161
	v_mul_f32_e32 v162, s28, v162
	v_mul_f32_e32 v163, s28, v163
	v_exp_f32_e32 v156, v156
	v_exp_f32_e32 v157, v157
	v_exp_f32_e32 v158, v158
	v_exp_f32_e32 v159, v159
	v_exp_f32_e32 v160, v160
	v_exp_f32_e32 v161, v161
	v_exp_f32_e32 v162, v162
	v_exp_f32_e32 v163, v163
	v_add_f32_e32 v156, 1.0, v156
	v_add_f32_e32 v157, 1.0, v157
	v_add_f32_e32 v158, 1.0, v158
	v_add_f32_e32 v159, 1.0, v159
	v_add_f32_e32 v160, 1.0, v160
	v_add_f32_e32 v161, 1.0, v161
	v_add_f32_e32 v162, 1.0, v162
	v_add_f32_e32 v163, 1.0, v163
	v_rcp_f32_e32 v156, v156
	v_rcp_f32_e32 v157, v157
	v_rcp_f32_e32 v158, v158
	v_rcp_f32_e32 v159, v159
	v_rcp_f32_e32 v160, v160
	v_rcp_f32_e32 v161, v161
	v_rcp_f32_e32 v162, v162
	v_rcp_f32_e32 v163, v163
	v_mul_f32_e32 v62, v62, v156
	v_mul_f32_e32 v63, v63, v157
	v_mul_f32_e32 v64, v64, v158
	v_mul_f32_e32 v65, v65, v159
	v_mul_f32_e32 v58, v58, v160
	v_mul_f32_e32 v59, v59, v161
	v_mul_f32_e32 v60, v60, v162
	v_mul_f32_e32 v61, v61, v163
	v_add_u32_e32 v153, 0xbf400, v153
	v_cvt_pk_bf16_f32 v164, v62, v63
	v_cvt_pk_bf16_f32 v165, v64, v65
	v_cvt_pk_bf16_f32 v166, v58, v59
	v_cvt_pk_bf16_f32 v167, v60, v61
	s_mov_b64 exec, s[24:25]
	global_store_dwordx4 v153, v[164:167], s[68:69]
	s_mov_b64 exec, -1
	v_mul_f32_e32 v54, v54, v142
	v_mul_f32_e32 v55, v55, v142
	v_mul_f32_e32 v56, v56, v142
	v_mul_f32_e32 v57, v57, v142
	v_mul_f32_e32 v50, v50, v142
	v_mul_f32_e32 v51, v51, v142
	v_mul_f32_e32 v52, v52, v142
	v_mul_f32_e32 v53, v53, v142
	v_mul_f32_e32 v156, s2, v54
	v_mul_f32_e32 v157, s2, v55
	v_mul_f32_e32 v158, s2, v56
	v_mul_f32_e32 v159, s2, v57
	v_mul_f32_e32 v160, s2, v50
	v_mul_f32_e32 v161, s2, v51
	v_mul_f32_e32 v162, s2, v52
	v_mul_f32_e32 v163, s2, v53
	v_mul_f32_e32 v156, v54, v156
	v_mul_f32_e32 v157, v55, v157
	v_mul_f32_e32 v158, v56, v158
	v_mul_f32_e32 v159, v57, v159
	v_mul_f32_e32 v160, v50, v160
	v_mul_f32_e32 v161, v51, v161
	v_mul_f32_e32 v162, v52, v162
	v_mul_f32_e32 v163, v53, v163
	v_fma_f32 v156, v54, v156, v54
	v_fma_f32 v157, v55, v157, v55
	v_fma_f32 v158, v56, v158, v56
	v_fma_f32 v159, v57, v159, v57
	v_fma_f32 v160, v50, v160, v50
	v_fma_f32 v161, v51, v161, v51
	v_fma_f32 v162, v52, v162, v52
	v_fma_f32 v163, v53, v163, v53
	v_mul_f32_e32 v156, s3, v156
	v_mul_f32_e32 v157, s3, v157
	v_mul_f32_e32 v158, s3, v158
	v_mul_f32_e32 v159, s3, v159
	v_mul_f32_e32 v160, s3, v160
	v_mul_f32_e32 v161, s3, v161
	v_mul_f32_e32 v162, s3, v162
; __device__ __forceinline__ u32x4 pack8(const float* f) { u32x4 o; o.x = pk2(f[0], f[1]); o.y = pk2(f[2], f[3]); o.z = pk2(f[4], f[5]); o.w = pk2(f[6], f[7]); return o; }
; __device__ __forceinline__ float sigmoidf_(float x) { return rcpf(1.0f + __expf(-x)); }
; __device__ __forceinline__ float gelu_tanh(float v) { const float u = 0.7978845608f * (v + 0.044715f * v * v * v); return v * rcpf(1.0f + __expf(-2.0f * u)); }
;     __device__ __forceinline__ void operator()(const f32x4 (&acc)[2][2][4][2], const Unit& u, int wr, int wc, int fr, int fq) const {
;     ...
;         for (int ai = 0; ai < 2; ++ai)
; #pragma unroll
;             for (int m = 0; m < 4; ++m) { const size_t row = (size_t)(row0 + ai * HALF + m * 16); const float rs = rsv[ai][m];
; #pragma unroll
;                 for (int bj = 0; bj < 2; ++bj) { float o[8];
;                     const int c0 = u.pn * BM + bj * HALF + wc * 32 + 8 * fq;
; #pragma unroll
;                     for (int n = 0; n < 2; ++n)
; #pragma unroll
;                         for (int j = 0; j < 4; ++j) { const float v = acc[ai][bj][m][n][j] * rs; o[n * 4 + j] = mode == 0 ? gelu_tanh(v) : (mode == 1 ? v : sigmoidf_(v)); }
;                     if (mode == 2) { unsigned w0 = 0u, w1 = 0u;
; #pragma unroll
;                         for (int j = 0; j < 4; ++j) { w0 = __builtin_amdgcn_cvt_pk_u8_f32(fmaxf(o[j] * 255.f, 1.f), j, w0); w1 = __builtin_amdgcn_cvt_pk_u8_f32(fmaxf(o[4 + j] * 255.f, 1.f), j, w1); }
;                         u32x2 wv; wv.x = w0; wv.y = w1; *(u32x2*)(gates + row * 4096 + (c0 - 5120)) = wv; }
;                     else if (c0 < PLD) *(u32x4*)(proj + row * PLD + c0) = pack8(o); } }
	v_mul_f32_e32 v163, s3, v163
	v_mul_f32_e32 v156, -2.0, v156
	v_mul_f32_e32 v157, -2.0, v157
	v_mul_f32_e32 v158, -2.0, v158
	v_mul_f32_e32 v159, -2.0, v159
	v_mul_f32_e32 v160, -2.0, v160
	v_mul_f32_e32 v161, -2.0, v161
	v_mul_f32_e32 v162, -2.0, v162
	v_mul_f32_e32 v163, -2.0, v163
	v_mul_f32_e32 v156, s28, v156
	v_mul_f32_e32 v157, s28, v157
	v_mul_f32_e32 v158, s28, v158
	v_mul_f32_e32 v159, s28, v159
	v_mul_f32_e32 v160, s28, v160
	v_mul_f32_e32 v161, s28, v161
	v_mul_f32_e32 v162, s28, v162
	v_mul_f32_e32 v163, s28, v163
	v_exp_f32_e32 v156, v156
	v_exp_f32_e32 v157, v157
	v_exp_f32_e32 v158, v158
	v_exp_f32_e32 v159, v159
	v_exp_f32_e32 v160, v160
	v_exp_f32_e32 v161, v161
	v_exp_f32_e32 v162, v162
	v_exp_f32_e32 v163, v163
	v_add_f32_e32 v156, 1.0, v156
	v_add_f32_e32 v157, 1.0, v157
	v_add_f32_e32 v158, 1.0, v158
	v_add_f32_e32 v159, 1.0, v159
	v_add_f32_e32 v160, 1.0, v160
	v_add_f32_e32 v161, 1.0, v161
	v_add_f32_e32 v162, 1.0, v162
	v_add_f32_e32 v163, 1.0, v163
	v_rcp_f32_e32 v156, v156
	v_rcp_f32_e32 v157, v157
	v_rcp_f32_e32 v158, v158
	v_rcp_f32_e32 v159, v159
	v_rcp_f32_e32 v160, v160
	v_rcp_f32_e32 v161, v161
	v_rcp_f32_e32 v162, v162
	v_rcp_f32_e32 v163, v163
	v_mul_f32_e32 v54, v54, v156
	v_mul_f32_e32 v55, v55, v157
	v_mul_f32_e32 v56, v56, v158
	v_mul_f32_e32 v57, v57, v159
	v_mul_f32_e32 v50, v50, v160
	v_mul_f32_e32 v51, v51, v161
	v_mul_f32_e32 v52, v52, v162
	v_mul_f32_e32 v53, v53, v163
	v_cvt_pk_bf16_f32 v168, v54, v55
	v_cvt_pk_bf16_f32 v169, v56, v57
	v_cvt_pk_bf16_f32 v170, v50, v51
	v_cvt_pk_bf16_f32 v171, v52, v53
	s_mov_b64 exec, s[38:39]
	global_store_dwordx4 v153, v[168:171], s[68:69] offset:256
	s_mov_b64 exec, -1
	v_mul_f32_e32 v46, v46, v143
	v_mul_f32_e32 v47, v47, v143
	v_mul_f32_e32 v48, v48, v143
	v_mul_f32_e32 v49, v49, v143
	v_mul_f32_e32 v42, v42, v143
	v_mul_f32_e32 v43, v43, v143
	v_mul_f32_e32 v44, v44, v143
	v_mul_f32_e32 v45, v45, v143
	v_mul_f32_e32 v156, s2, v46
	v_mul_f32_e32 v157, s2, v47
	v_mul_f32_e32 v158, s2, v48
	v_mul_f32_e32 v159, s2, v49
	v_mul_f32_e32 v160, s2, v42
	v_mul_f32_e32 v161, s2, v43
	v_mul_f32_e32 v162, s2, v44
	v_mul_f32_e32 v163, s2, v45
	v_mul_f32_e32 v156, v46, v156
	v_mul_f32_e32 v157, v47, v157
	v_mul_f32_e32 v158, v48, v158
	v_mul_f32_e32 v159, v49, v159
	v_mul_f32_e32 v160, v42, v160
	v_mul_f32_e32 v161, v43, v161
	v_mul_f32_e32 v162, v44, v162
	v_mul_f32_e32 v163, v45, v163
	v_fma_f32 v156, v46, v156, v46
	v_fma_f32 v157, v47, v157, v47
	v_fma_f32 v158, v48, v158, v48
	v_fma_f32 v159, v49, v159, v49
	v_fma_f32 v160, v42, v160, v42
	v_fma_f32 v161, v43, v161, v43
	v_fma_f32 v162, v44, v162, v44
	v_fma_f32 v163, v45, v163, v45
	v_mul_f32_e32 v156, s3, v156
	v_mul_f32_e32 v157, s3, v157
	v_mul_f32_e32 v158, s3, v158
	v_mul_f32_e32 v159, s3, v159
	v_mul_f32_e32 v160, s3, v160
	v_mul_f32_e32 v161, s3, v161
	v_mul_f32_e32 v162, s3, v162
	v_mul_f32_e32 v163, s3, v163
	v_mul_f32_e32 v156, -2.0, v156
	v_mul_f32_e32 v157, -2.0, v157
	v_mul_f32_e32 v158, -2.0, v158
	v_mul_f32_e32 v159, -2.0, v159
	v_mul_f32_e32 v160, -2.0, v160
	v_mul_f32_e32 v161, -2.0, v161
	v_mul_f32_e32 v162, -2.0, v162
	v_mul_f32_e32 v163, -2.0, v163
	v_mul_f32_e32 v156, s28, v156
	v_mul_f32_e32 v157, s28, v157
	v_mul_f32_e32 v158, s28, v158
	v_mul_f32_e32 v159, s28, v159
	v_mul_f32_e32 v160, s28, v160
	v_mul_f32_e32 v161, s28, v161
	v_mul_f32_e32 v162, s28, v162
	v_mul_f32_e32 v163, s28, v163
	v_exp_f32_e32 v156, v156
	v_exp_f32_e32 v157, v157
	v_exp_f32_e32 v158, v158
	v_exp_f32_e32 v159, v159
	v_exp_f32_e32 v160, v160
	v_exp_f32_e32 v161, v161
	v_exp_f32_e32 v162, v162
	v_exp_f32_e32 v163, v163
	v_add_f32_e32 v156, 1.0, v156
	v_add_f32_e32 v157, 1.0, v157
	v_add_f32_e32 v158, 1.0, v158
	v_add_f32_e32 v159, 1.0, v159
	v_add_f32_e32 v160, 1.0, v160
	v_add_f32_e32 v161, 1.0, v161
	v_add_f32_e32 v162, 1.0, v162
	v_add_f32_e32 v163, 1.0, v163
	v_rcp_f32_e32 v156, v156
	v_rcp_f32_e32 v157, v157
	v_rcp_f32_e32 v158, v158
	v_rcp_f32_e32 v159, v159
	v_rcp_f32_e32 v160, v160
	v_rcp_f32_e32 v161, v161
	v_rcp_f32_e32 v162, v162
	v_rcp_f32_e32 v163, v163
	v_mul_f32_e32 v46, v46, v156
	v_mul_f32_e32 v47, v47, v157
	v_mul_f32_e32 v48, v48, v158
	v_mul_f32_e32 v49, v49, v159
	v_mul_f32_e32 v42, v42, v160
	v_mul_f32_e32 v43, v43, v161
	v_mul_f32_e32 v44, v44, v162
	v_mul_f32_e32 v45, v45, v163
	v_add_u32_e32 v153, 0x26400, v153
	v_cvt_pk_bf16_f32 v164, v46, v47
	v_cvt_pk_bf16_f32 v165, v48, v49
	v_cvt_pk_bf16_f32 v166, v42, v43
	v_cvt_pk_bf16_f32 v167, v44, v45
	s_mov_b64 exec, s[24:25]
	global_store_dwordx4 v153, v[164:167], s[68:69]
	s_mov_b64 exec, -1
	v_mul_f32_e32 v38, v38, v143
	v_mul_f32_e32 v39, v39, v143
	v_mul_f32_e32 v40, v40, v143
	v_mul_f32_e32 v41, v41, v143
	v_mul_f32_e32 v34, v34, v143
	v_mul_f32_e32 v35, v35, v143
	v_mul_f32_e32 v36, v36, v143
	v_mul_f32_e32 v37, v37, v143
	v_mul_f32_e32 v156, s2, v38
	v_mul_f32_e32 v157, s2, v39
	v_mul_f32_e32 v158, s2, v40
	v_mul_f32_e32 v159, s2, v41
	v_mul_f32_e32 v160, s2, v34
	v_mul_f32_e32 v161, s2, v35
	v_mul_f32_e32 v162, s2, v36
	v_mul_f32_e32 v163, s2, v37
	v_mul_f32_e32 v156, v38, v156
	v_mul_f32_e32 v157, v39, v157
	v_mul_f32_e32 v158, v40, v158
	v_mul_f32_e32 v159, v41, v159
	v_mul_f32_e32 v160, v34, v160
	v_mul_f32_e32 v161, v35, v161
	v_mul_f32_e32 v162, v36, v162
	v_mul_f32_e32 v163, v37, v163
	v_fma_f32 v156, v38, v156, v38
	v_fma_f32 v157, v39, v157, v39
	v_fma_f32 v158, v40, v158, v40
	v_fma_f32 v159, v41, v159, v41
	v_fma_f32 v160, v34, v160, v34
	v_fma_f32 v161, v35, v161, v35
	v_fma_f32 v162, v36, v162, v36
	v_fma_f32 v163, v37, v163, v37
	v_mul_f32_e32 v156, s3, v156
	v_mul_f32_e32 v157, s3, v157
	v_mul_f32_e32 v158, s3, v158
; __device__ __forceinline__ u32x4 pack8(const float* f) { u32x4 o; o.x = pk2(f[0], f[1]); o.y = pk2(f[2], f[3]); o.z = pk2(f[4], f[5]); o.w = pk2(f[6], f[7]); return o; }
; __device__ __forceinline__ float sigmoidf_(float x) { return rcpf(1.0f + __expf(-x)); }
; __device__ __forceinline__ float gelu_tanh(float v) { const float u = 0.7978845608f * (v + 0.044715f * v * v * v); return v * rcpf(1.0f + __expf(-2.0f * u)); }
;     __device__ __forceinline__ void operator()(const f32x4 (&acc)[2][2][4][2], const Unit& u, int wr, int wc, int fr, int fq) const {
;     ...
;         for (int ai = 0; ai < 2; ++ai)
; #pragma unroll
;             for (int m = 0; m < 4; ++m) { const size_t row = (size_t)(row0 + ai * HALF + m * 16); const float rs = rsv[ai][m];
; #pragma unroll
;                 for (int bj = 0; bj < 2; ++bj) { float o[8];
;                     const int c0 = u.pn * BM + bj * HALF + wc * 32 + 8 * fq;
; #pragma unroll
;                     for (int n = 0; n < 2; ++n)
; #pragma unroll
;                         for (int j = 0; j < 4; ++j) { const float v = acc[ai][bj][m][n][j] * rs; o[n * 4 + j] = mode == 0 ? gelu_tanh(v) : (mode == 1 ? v : sigmoidf_(v)); }
;                     if (mode == 2) { unsigned w0 = 0u, w1 = 0u;
; #pragma unroll
;                         for (int j = 0; j < 4; ++j) { w0 = __builtin_amdgcn_cvt_pk_u8_f32(fmaxf(o[j] * 255.f, 1.f), j, w0); w1 = __builtin_amdgcn_cvt_pk_u8_f32(fmaxf(o[4 + j] * 255.f, 1.f), j, w1); }
;                         u32x2 wv; wv.x = w0; wv.y = w1; *(u32x2*)(gates + row * 4096 + (c0 - 5120)) = wv; }
;                     else if (c0 < PLD) *(u32x4*)(proj + row * PLD + c0) = pack8(o); } }
	v_mul_f32_e32 v159, s3, v159
	v_mul_f32_e32 v160, s3, v160
	v_mul_f32_e32 v161, s3, v161
	v_mul_f32_e32 v162, s3, v162
	v_mul_f32_e32 v163, s3, v163
	v_mul_f32_e32 v156, -2.0, v156
	v_mul_f32_e32 v157, -2.0, v157
	v_mul_f32_e32 v158, -2.0, v158
	v_mul_f32_e32 v159, -2.0, v159
	v_mul_f32_e32 v160, -2.0, v160
	v_mul_f32_e32 v161, -2.0, v161
	v_mul_f32_e32 v162, -2.0, v162
	v_mul_f32_e32 v163, -2.0, v163
	v_mul_f32_e32 v156, s28, v156
	v_mul_f32_e32 v157, s28, v157
	v_mul_f32_e32 v158, s28, v158
	v_mul_f32_e32 v159, s28, v159
	v_mul_f32_e32 v160, s28, v160
	v_mul_f32_e32 v161, s28, v161
	v_mul_f32_e32 v162, s28, v162
	v_mul_f32_e32 v163, s28, v163
	v_exp_f32_e32 v156, v156
	v_exp_f32_e32 v157, v157
	v_exp_f32_e32 v158, v158
	v_exp_f32_e32 v159, v159
	v_exp_f32_e32 v160, v160
	v_exp_f32_e32 v161, v161
	v_exp_f32_e32 v162, v162
	v_exp_f32_e32 v163, v163
	v_add_f32_e32 v156, 1.0, v156
	v_add_f32_e32 v157, 1.0, v157
	v_add_f32_e32 v158, 1.0, v158
	v_add_f32_e32 v159, 1.0, v159
	v_add_f32_e32 v160, 1.0, v160
	v_add_f32_e32 v161, 1.0, v161
	v_add_f32_e32 v162, 1.0, v162
	v_add_f32_e32 v163, 1.0, v163
	v_rcp_f32_e32 v156, v156
	v_rcp_f32_e32 v157, v157
	v_rcp_f32_e32 v158, v158
	v_rcp_f32_e32 v159, v159
	v_rcp_f32_e32 v160, v160
	v_rcp_f32_e32 v161, v161
	v_rcp_f32_e32 v162, v162
	v_rcp_f32_e32 v163, v163
	v_mul_f32_e32 v38, v38, v156
	v_mul_f32_e32 v39, v39, v157
	v_mul_f32_e32 v40, v40, v158
	v_mul_f32_e32 v41, v41, v159
	v_mul_f32_e32 v34, v34, v160
	v_mul_f32_e32 v35, v35, v161
	v_mul_f32_e32 v36, v36, v162
	v_mul_f32_e32 v37, v37, v163
	v_cvt_pk_bf16_f32 v168, v38, v39
	v_cvt_pk_bf16_f32 v169, v40, v41
	v_cvt_pk_bf16_f32 v170, v34, v35
	v_cvt_pk_bf16_f32 v171, v36, v37
	s_mov_b64 exec, s[38:39]
	global_store_dwordx4 v153, v[168:171], s[68:69] offset:256
	s_mov_b64 exec, -1
	v_mul_f32_e32 v30, v30, v140
	v_mul_f32_e32 v31, v31, v140
	v_mul_f32_e32 v32, v32, v140
	v_mul_f32_e32 v33, v33, v140
	v_mul_f32_e32 v26, v26, v140
	v_mul_f32_e32 v27, v27, v140
	v_mul_f32_e32 v28, v28, v140
	v_mul_f32_e32 v29, v29, v140
	v_mul_f32_e32 v156, s2, v30
	v_mul_f32_e32 v157, s2, v31
	v_mul_f32_e32 v158, s2, v32
	v_mul_f32_e32 v159, s2, v33
	v_mul_f32_e32 v160, s2, v26
	v_mul_f32_e32 v161, s2, v27
	v_mul_f32_e32 v162, s2, v28
	v_mul_f32_e32 v163, s2, v29
	v_mul_f32_e32 v156, v30, v156
	v_mul_f32_e32 v157, v31, v157
	v_mul_f32_e32 v158, v32, v158
	v_mul_f32_e32 v159, v33, v159
	v_mul_f32_e32 v160, v26, v160
	v_mul_f32_e32 v161, v27, v161
	v_mul_f32_e32 v162, v28, v162
	v_mul_f32_e32 v163, v29, v163
	v_fma_f32 v156, v30, v156, v30
	v_fma_f32 v157, v31, v157, v31
	v_fma_f32 v158, v32, v158, v32
	v_fma_f32 v159, v33, v159, v33
	v_fma_f32 v160, v26, v160, v26
	v_fma_f32 v161, v27, v161, v27
	v_fma_f32 v162, v28, v162, v28
	v_fma_f32 v163, v29, v163, v29
	v_mul_f32_e32 v156, s3, v156
	v_mul_f32_e32 v157, s3, v157
	v_mul_f32_e32 v158, s3, v158
	v_mul_f32_e32 v159, s3, v159
	v_mul_f32_e32 v160, s3, v160
	v_mul_f32_e32 v161, s3, v161
	v_mul_f32_e32 v162, s3, v162
	v_mul_f32_e32 v163, s3, v163
	v_mul_f32_e32 v156, -2.0, v156
	v_mul_f32_e32 v157, -2.0, v157
	v_mul_f32_e32 v158, -2.0, v158
	v_mul_f32_e32 v159, -2.0, v159
	v_mul_f32_e32 v160, -2.0, v160
	v_mul_f32_e32 v161, -2.0, v161
	v_mul_f32_e32 v162, -2.0, v162
	v_mul_f32_e32 v163, -2.0, v163
	v_mul_f32_e32 v156, s28, v156
	v_mul_f32_e32 v157, s28, v157
	v_mul_f32_e32 v158, s28, v158
	v_mul_f32_e32 v159, s28, v159
	v_mul_f32_e32 v160, s28, v160
	v_mul_f32_e32 v161, s28, v161
	v_mul_f32_e32 v162, s28, v162
	v_mul_f32_e32 v163, s28, v163
	v_exp_f32_e32 v156, v156
	v_exp_f32_e32 v157, v157
	v_exp_f32_e32 v158, v158
	v_exp_f32_e32 v159, v159
	v_exp_f32_e32 v160, v160
	v_exp_f32_e32 v161, v161
	v_exp_f32_e32 v162, v162
	v_exp_f32_e32 v163, v163
	v_add_f32_e32 v156, 1.0, v156
	v_add_f32_e32 v157, 1.0, v157
	v_add_f32_e32 v158, 1.0, v158
	v_add_f32_e32 v159, 1.0, v159
	v_add_f32_e32 v160, 1.0, v160
	v_add_f32_e32 v161, 1.0, v161
	v_add_f32_e32 v162, 1.0, v162
	v_add_f32_e32 v163, 1.0, v163
	v_rcp_f32_e32 v156, v156
	v_rcp_f32_e32 v157, v157
	v_rcp_f32_e32 v158, v158
	v_rcp_f32_e32 v159, v159
	v_rcp_f32_e32 v160, v160
	v_rcp_f32_e32 v161, v161
	v_rcp_f32_e32 v162, v162
	v_rcp_f32_e32 v163, v163
	v_mul_f32_e32 v30, v30, v156
	v_mul_f32_e32 v31, v31, v157
	v_mul_f32_e32 v32, v32, v158
	v_mul_f32_e32 v33, v33, v159
	v_mul_f32_e32 v26, v26, v160
	v_mul_f32_e32 v27, v27, v161
	v_mul_f32_e32 v28, v28, v162
	v_mul_f32_e32 v29, v29, v163
	v_add_u32_e32 v153, 0x26400, v153
	v_cvt_pk_bf16_f32 v164, v30, v31
	v_cvt_pk_bf16_f32 v165, v32, v33
	v_cvt_pk_bf16_f32 v166, v26, v27
	v_cvt_pk_bf16_f32 v167, v28, v29
	s_mov_b64 exec, s[24:25]
	global_store_dwordx4 v153, v[164:167], s[68:69]
	s_mov_b64 exec, -1
	v_mul_f32_e32 v22, v22, v140
	v_mul_f32_e32 v23, v23, v140
	v_mul_f32_e32 v24, v24, v140
	v_mul_f32_e32 v25, v25, v140
	v_mul_f32_e32 v18, v18, v140
	v_mul_f32_e32 v19, v19, v140
	v_mul_f32_e32 v20, v20, v140
	v_mul_f32_e32 v21, v21, v140
	v_mul_f32_e32 v156, s2, v22
	v_mul_f32_e32 v157, s2, v23
	v_mul_f32_e32 v158, s2, v24
	v_mul_f32_e32 v159, s2, v25
	v_mul_f32_e32 v160, s2, v18
	v_mul_f32_e32 v161, s2, v19
	v_mul_f32_e32 v162, s2, v20
	v_mul_f32_e32 v163, s2, v21
	v_mul_f32_e32 v156, v22, v156
	v_mul_f32_e32 v157, v23, v157
	v_mul_f32_e32 v158, v24, v158
	v_mul_f32_e32 v159, v25, v159
	v_mul_f32_e32 v160, v18, v160
	v_mul_f32_e32 v161, v19, v161
	v_mul_f32_e32 v162, v20, v162
	v_mul_f32_e32 v163, v21, v163
	v_fma_f32 v156, v22, v156, v22
	v_fma_f32 v157, v23, v157, v23
	v_fma_f32 v158, v24, v158, v24
	v_fma_f32 v159, v25, v159, v25
	v_fma_f32 v160, v18, v160, v18
	v_fma_f32 v161, v19, v161, v19
	v_fma_f32 v162, v20, v162, v20
; __device__ __forceinline__ u32x4 pack8(const float* f) { u32x4 o; o.x = pk2(f[0], f[1]); o.y = pk2(f[2], f[3]); o.z = pk2(f[4], f[5]); o.w = pk2(f[6], f[7]); return o; }
; __device__ __forceinline__ float sigmoidf_(float x) { return rcpf(1.0f + __expf(-x)); }
; __device__ __forceinline__ float gelu_tanh(float v) { const float u = 0.7978845608f * (v + 0.044715f * v * v * v); return v * rcpf(1.0f + __expf(-2.0f * u)); }
;     __device__ __forceinline__ void operator()(const f32x4 (&acc)[2][2][4][2], const Unit& u, int wr, int wc, int fr, int fq) const {
;     ...
;         for (int ai = 0; ai < 2; ++ai)
; #pragma unroll
;             for (int m = 0; m < 4; ++m) { const size_t row = (size_t)(row0 + ai * HALF + m * 16); const float rs = rsv[ai][m];
; #pragma unroll
;                 for (int bj = 0; bj < 2; ++bj) { float o[8];
;                     const int c0 = u.pn * BM + bj * HALF + wc * 32 + 8 * fq;
; #pragma unroll
;                     for (int n = 0; n < 2; ++n)
; #pragma unroll
;                         for (int j = 0; j < 4; ++j) { const float v = acc[ai][bj][m][n][j] * rs; o[n * 4 + j] = mode == 0 ? gelu_tanh(v) : (mode == 1 ? v : sigmoidf_(v)); }
;                     if (mode == 2) { unsigned w0 = 0u, w1 = 0u;
; #pragma unroll
;                         for (int j = 0; j < 4; ++j) { w0 = __builtin_amdgcn_cvt_pk_u8_f32(fmaxf(o[j] * 255.f, 1.f), j, w0); w1 = __builtin_amdgcn_cvt_pk_u8_f32(fmaxf(o[4 + j] * 255.f, 1.f), j, w1); }
;                         u32x2 wv; wv.x = w0; wv.y = w1; *(u32x2*)(gates + row * 4096 + (c0 - 5120)) = wv; }
;                     else if (c0 < PLD) *(u32x4*)(proj + row * PLD + c0) = pack8(o); } }
	v_fma_f32 v163, v21, v163, v21
	v_mul_f32_e32 v156, s3, v156
	v_mul_f32_e32 v157, s3, v157
	v_mul_f32_e32 v158, s3, v158
	v_mul_f32_e32 v159, s3, v159
	v_mul_f32_e32 v160, s3, v160
	v_mul_f32_e32 v161, s3, v161
	v_mul_f32_e32 v162, s3, v162
	v_mul_f32_e32 v163, s3, v163
	v_mul_f32_e32 v156, -2.0, v156
	v_mul_f32_e32 v157, -2.0, v157
	v_mul_f32_e32 v158, -2.0, v158
	v_mul_f32_e32 v159, -2.0, v159
	v_mul_f32_e32 v160, -2.0, v160
	v_mul_f32_e32 v161, -2.0, v161
	v_mul_f32_e32 v162, -2.0, v162
	v_mul_f32_e32 v163, -2.0, v163
	v_mul_f32_e32 v156, s28, v156
	v_mul_f32_e32 v157, s28, v157
	v_mul_f32_e32 v158, s28, v158
	v_mul_f32_e32 v159, s28, v159
	v_mul_f32_e32 v160, s28, v160
	v_mul_f32_e32 v161, s28, v161
	v_mul_f32_e32 v162, s28, v162
	v_mul_f32_e32 v163, s28, v163
	v_exp_f32_e32 v156, v156
	v_exp_f32_e32 v157, v157
	v_exp_f32_e32 v158, v158
	v_exp_f32_e32 v159, v159
	v_exp_f32_e32 v160, v160
	v_exp_f32_e32 v161, v161
	v_exp_f32_e32 v162, v162
	v_exp_f32_e32 v163, v163
	v_add_f32_e32 v156, 1.0, v156
	v_add_f32_e32 v157, 1.0, v157
	v_add_f32_e32 v158, 1.0, v158
	v_add_f32_e32 v159, 1.0, v159
	v_add_f32_e32 v160, 1.0, v160
	v_add_f32_e32 v161, 1.0, v161
	v_add_f32_e32 v162, 1.0, v162
	v_add_f32_e32 v163, 1.0, v163
	v_rcp_f32_e32 v156, v156
	v_rcp_f32_e32 v157, v157
	v_rcp_f32_e32 v158, v158
	v_rcp_f32_e32 v159, v159
	v_rcp_f32_e32 v160, v160
	v_rcp_f32_e32 v161, v161
	v_rcp_f32_e32 v162, v162
	v_rcp_f32_e32 v163, v163
	v_mul_f32_e32 v22, v22, v156
	v_mul_f32_e32 v23, v23, v157
	v_mul_f32_e32 v24, v24, v158
	v_mul_f32_e32 v25, v25, v159
	v_mul_f32_e32 v18, v18, v160
	v_mul_f32_e32 v19, v19, v161
	v_mul_f32_e32 v20, v20, v162
	v_mul_f32_e32 v21, v21, v163
	v_cvt_pk_bf16_f32 v168, v22, v23
	v_cvt_pk_bf16_f32 v169, v24, v25
	v_cvt_pk_bf16_f32 v170, v18, v19
	v_cvt_pk_bf16_f32 v171, v20, v21
	s_mov_b64 exec, s[38:39]
	global_store_dwordx4 v153, v[168:171], s[68:69] offset:256
	s_mov_b64 exec, -1
	v_mul_f32_e32 v14, v14, v141
	v_mul_f32_e32 v15, v15, v141
	v_mul_f32_e32 v16, v16, v141
	v_mul_f32_e32 v17, v17, v141
	v_mul_f32_e32 v10, v10, v141
	v_mul_f32_e32 v11, v11, v141
	v_mul_f32_e32 v12, v12, v141
	v_mul_f32_e32 v13, v13, v141
	v_mul_f32_e32 v156, s2, v14
	v_mul_f32_e32 v157, s2, v15
	v_mul_f32_e32 v158, s2, v16
	v_mul_f32_e32 v159, s2, v17
	v_mul_f32_e32 v160, s2, v10
	v_mul_f32_e32 v161, s2, v11
	v_mul_f32_e32 v162, s2, v12
	v_mul_f32_e32 v163, s2, v13
	v_mul_f32_e32 v156, v14, v156
	v_mul_f32_e32 v157, v15, v157
	v_mul_f32_e32 v158, v16, v158
	v_mul_f32_e32 v159, v17, v159
	v_mul_f32_e32 v160, v10, v160
	v_mul_f32_e32 v161, v11, v161
	v_mul_f32_e32 v162, v12, v162
	v_mul_f32_e32 v163, v13, v163
	v_fma_f32 v156, v14, v156, v14
	v_fma_f32 v157, v15, v157, v15
	v_fma_f32 v158, v16, v158, v16
	v_fma_f32 v159, v17, v159, v17
	v_fma_f32 v160, v10, v160, v10
	v_fma_f32 v161, v11, v161, v11
	v_fma_f32 v162, v12, v162, v12
	v_fma_f32 v163, v13, v163, v13
	v_mul_f32_e32 v156, s3, v156
	v_mul_f32_e32 v157, s3, v157
	v_mul_f32_e32 v158, s3, v158
	v_mul_f32_e32 v159, s3, v159
	v_mul_f32_e32 v160, s3, v160
	v_mul_f32_e32 v161, s3, v161
	v_mul_f32_e32 v162, s3, v162
	v_mul_f32_e32 v163, s3, v163
	v_mul_f32_e32 v156, -2.0, v156
	v_mul_f32_e32 v157, -2.0, v157
	v_mul_f32_e32 v158, -2.0, v158
	v_mul_f32_e32 v159, -2.0, v159
	v_mul_f32_e32 v160, -2.0, v160
	v_mul_f32_e32 v161, -2.0, v161
	v_mul_f32_e32 v162, -2.0, v162
	v_mul_f32_e32 v163, -2.0, v163
	v_mul_f32_e32 v156, s28, v156
	v_mul_f32_e32 v157, s28, v157
	v_mul_f32_e32 v158, s28, v158
	v_mul_f32_e32 v159, s28, v159
	v_mul_f32_e32 v160, s28, v160
	v_mul_f32_e32 v161, s28, v161
	v_mul_f32_e32 v162, s28, v162
	v_mul_f32_e32 v163, s28, v163
	v_exp_f32_e32 v156, v156
	v_exp_f32_e32 v157, v157
	v_exp_f32_e32 v158, v158
	v_exp_f32_e32 v159, v159
	v_exp_f32_e32 v160, v160
	v_exp_f32_e32 v161, v161
	v_exp_f32_e32 v162, v162
	v_exp_f32_e32 v163, v163
	v_add_f32_e32 v156, 1.0, v156
	v_add_f32_e32 v157, 1.0, v157
	v_add_f32_e32 v158, 1.0, v158
	v_add_f32_e32 v159, 1.0, v159
	v_add_f32_e32 v160, 1.0, v160
	v_add_f32_e32 v161, 1.0, v161
	v_add_f32_e32 v162, 1.0, v162
	v_add_f32_e32 v163, 1.0, v163
	v_rcp_f32_e32 v156, v156
	v_rcp_f32_e32 v157, v157
	v_rcp_f32_e32 v158, v158
	v_rcp_f32_e32 v159, v159
	v_rcp_f32_e32 v160, v160
	v_rcp_f32_e32 v161, v161
	v_rcp_f32_e32 v162, v162
	v_rcp_f32_e32 v163, v163
	v_mul_f32_e32 v14, v14, v156
	v_mul_f32_e32 v15, v15, v157
	v_mul_f32_e32 v16, v16, v158
	v_mul_f32_e32 v17, v17, v159
	v_mul_f32_e32 v10, v10, v160
	v_mul_f32_e32 v11, v11, v161
	v_mul_f32_e32 v12, v12, v162
	v_mul_f32_e32 v13, v13, v163
	v_add_u32_e32 v153, 0x26400, v153
	v_cvt_pk_bf16_f32 v164, v14, v15
	v_cvt_pk_bf16_f32 v165, v16, v17
	v_cvt_pk_bf16_f32 v166, v10, v11
	v_cvt_pk_bf16_f32 v167, v12, v13
	s_mov_b64 exec, s[24:25]
	global_store_dwordx4 v153, v[164:167], s[68:69]
	s_mov_b64 exec, -1
	v_mul_f32_e32 v6, v6, v141
	v_mul_f32_e32 v7, v7, v141
	v_mul_f32_e32 v8, v8, v141
	v_mul_f32_e32 v9, v9, v141
	v_mul_f32_e32 v2, v2, v141
	v_mul_f32_e32 v3, v3, v141
	v_mul_f32_e32 v4, v4, v141
	v_mul_f32_e32 v5, v5, v141
	v_mul_f32_e32 v156, s2, v6
	v_mul_f32_e32 v157, s2, v7
	v_mul_f32_e32 v158, s2, v8
	v_mul_f32_e32 v159, s2, v9
	v_mul_f32_e32 v160, s2, v2
	v_mul_f32_e32 v161, s2, v3
	v_mul_f32_e32 v162, s2, v4
	v_mul_f32_e32 v163, s2, v5
	v_mul_f32_e32 v156, v6, v156
	v_mul_f32_e32 v157, v7, v157
	v_mul_f32_e32 v158, v8, v158
	v_mul_f32_e32 v159, v9, v159
	v_mul_f32_e32 v160, v2, v160
	v_mul_f32_e32 v161, v3, v161
	v_mul_f32_e32 v162, v4, v162
	v_mul_f32_e32 v163, v5, v163
	v_fma_f32 v156, v6, v156, v6
	v_fma_f32 v157, v7, v157, v7
	v_fma_f32 v158, v8, v158, v8
	v_fma_f32 v159, v9, v159, v9
	v_fma_f32 v160, v2, v160, v2
; __device__ __forceinline__ u32x4 pack8(const float* f) { u32x4 o; o.x = pk2(f[0], f[1]); o.y = pk2(f[2], f[3]); o.z = pk2(f[4], f[5]); o.w = pk2(f[6], f[7]); return o; }
; __device__ __forceinline__ float sigmoidf_(float x) { return rcpf(1.0f + __expf(-x)); }
; __device__ __forceinline__ float gelu_tanh(float v) { const float u = 0.7978845608f * (v + 0.044715f * v * v * v); return v * rcpf(1.0f + __expf(-2.0f * u)); }
;     __device__ __forceinline__ void operator()(const f32x4 (&acc)[2][2][4][2], const Unit& u, int wr, int wc, int fr, int fq) const {
;     ...
;         for (int ai = 0; ai < 2; ++ai)
; #pragma unroll
;             for (int m = 0; m < 4; ++m) { const size_t row = (size_t)(row0 + ai * HALF + m * 16); const float rs = rsv[ai][m];
; #pragma unroll
;                 for (int bj = 0; bj < 2; ++bj) { float o[8];
;                     const int c0 = u.pn * BM + bj * HALF + wc * 32 + 8 * fq;
; #pragma unroll
;                     for (int n = 0; n < 2; ++n)
; #pragma unroll
;                         for (int j = 0; j < 4; ++j) { const float v = acc[ai][bj][m][n][j] * rs; o[n * 4 + j] = mode == 0 ? gelu_tanh(v) : (mode == 1 ? v : sigmoidf_(v)); }
;                     if (mode == 2) { unsigned w0 = 0u, w1 = 0u;
; #pragma unroll
;                         for (int j = 0; j < 4; ++j) { w0 = __builtin_amdgcn_cvt_pk_u8_f32(fmaxf(o[j] * 255.f, 1.f), j, w0); w1 = __builtin_amdgcn_cvt_pk_u8_f32(fmaxf(o[4 + j] * 255.f, 1.f), j, w1); }
;                         u32x2 wv; wv.x = w0; wv.y = w1; *(u32x2*)(gates + row * 4096 + (c0 - 5120)) = wv; }
;                     else if (c0 < PLD) *(u32x4*)(proj + row * PLD + c0) = pack8(o); } }
	v_fma_f32 v161, v3, v161, v3
	v_fma_f32 v162, v4, v162, v4
	v_fma_f32 v163, v5, v163, v5
	v_mul_f32_e32 v156, s3, v156
	v_mul_f32_e32 v157, s3, v157
	v_mul_f32_e32 v158, s3, v158
	v_mul_f32_e32 v159, s3, v159
	v_mul_f32_e32 v160, s3, v160
	v_mul_f32_e32 v161, s3, v161
	v_mul_f32_e32 v162, s3, v162
	v_mul_f32_e32 v163, s3, v163
	v_mul_f32_e32 v156, -2.0, v156
	v_mul_f32_e32 v157, -2.0, v157
	v_mul_f32_e32 v158, -2.0, v158
	v_mul_f32_e32 v159, -2.0, v159
	v_mul_f32_e32 v160, -2.0, v160
	v_mul_f32_e32 v161, -2.0, v161
	v_mul_f32_e32 v162, -2.0, v162
	v_mul_f32_e32 v163, -2.0, v163
	v_mul_f32_e32 v156, s28, v156
	v_mul_f32_e32 v157, s28, v157
	v_mul_f32_e32 v158, s28, v158
	v_mul_f32_e32 v159, s28, v159
	v_mul_f32_e32 v160, s28, v160
	v_mul_f32_e32 v161, s28, v161
	v_mul_f32_e32 v162, s28, v162
	v_mul_f32_e32 v163, s28, v163
	v_exp_f32_e32 v156, v156
	v_exp_f32_e32 v157, v157
	v_exp_f32_e32 v158, v158
	v_exp_f32_e32 v159, v159
	v_exp_f32_e32 v160, v160
	v_exp_f32_e32 v161, v161
	v_exp_f32_e32 v162, v162
	v_exp_f32_e32 v163, v163
	v_add_f32_e32 v156, 1.0, v156
	v_add_f32_e32 v157, 1.0, v157
	v_add_f32_e32 v158, 1.0, v158
	v_add_f32_e32 v159, 1.0, v159
	v_add_f32_e32 v160, 1.0, v160
	v_add_f32_e32 v161, 1.0, v161
	v_add_f32_e32 v162, 1.0, v162
	v_add_f32_e32 v163, 1.0, v163
	v_rcp_f32_e32 v156, v156
	v_rcp_f32_e32 v157, v157
	v_rcp_f32_e32 v158, v158
	v_rcp_f32_e32 v159, v159
	v_rcp_f32_e32 v160, v160
	v_rcp_f32_e32 v161, v161
	v_rcp_f32_e32 v162, v162
	v_rcp_f32_e32 v163, v163
	v_mul_f32_e32 v6, v6, v156
	v_mul_f32_e32 v7, v7, v157
	v_mul_f32_e32 v8, v8, v158
	v_mul_f32_e32 v9, v9, v159
	v_mul_f32_e32 v2, v2, v160
	v_mul_f32_e32 v3, v3, v161
	v_mul_f32_e32 v4, v4, v162
	v_mul_f32_e32 v5, v5, v163
	v_cvt_pk_bf16_f32 v168, v6, v7
	v_cvt_pk_bf16_f32 v169, v8, v9
	v_cvt_pk_bf16_f32 v170, v2, v3
	v_cvt_pk_bf16_f32 v171, v4, v5
	s_mov_b64 exec, s[38:39]
	global_store_dwordx4 v153, v[168:171], s[68:69] offset:256
	s_mov_b64 exec, -1
	s_branch .Lmy_ip_done
.Lmy_ip_m1:
	v_mul_f32_e32 v126, v126, v146
	v_mul_f32_e32 v127, v127, v146
	v_mul_f32_e32 v128, v128, v146
	v_mul_f32_e32 v129, v129, v146
	v_mul_f32_e32 v122, v122, v146
	v_mul_f32_e32 v123, v123, v146
	v_mul_f32_e32 v124, v124, v146
	v_mul_f32_e32 v125, v125, v146
	v_cvt_pk_bf16_f32 v164, v126, v127
	v_cvt_pk_bf16_f32 v165, v128, v129
	v_cvt_pk_bf16_f32 v166, v122, v123
	v_cvt_pk_bf16_f32 v167, v124, v125
	s_mov_b64 exec, s[24:25]
	global_store_dwordx4 v153, v[164:167], s[68:69]
	s_mov_b64 exec, -1
	v_mul_f32_e32 v118, v118, v146
	v_mul_f32_e32 v119, v119, v146
	v_mul_f32_e32 v120, v120, v146
	v_mul_f32_e32 v121, v121, v146
	v_mul_f32_e32 v114, v114, v146
	v_mul_f32_e32 v115, v115, v146
	v_mul_f32_e32 v116, v116, v146
	v_mul_f32_e32 v117, v117, v146
	v_cvt_pk_bf16_f32 v168, v118, v119
	v_cvt_pk_bf16_f32 v169, v120, v121
	v_cvt_pk_bf16_f32 v170, v114, v115
	v_cvt_pk_bf16_f32 v171, v116, v117
	s_mov_b64 exec, s[38:39]
	global_store_dwordx4 v153, v[168:171], s[68:69] offset:256
	s_mov_b64 exec, -1
	v_mul_f32_e32 v110, v110, v147
	v_mul_f32_e32 v111, v111, v147
	v_mul_f32_e32 v112, v112, v147
	v_mul_f32_e32 v113, v113, v147
	v_mul_f32_e32 v106, v106, v147
	v_mul_f32_e32 v107, v107, v147
	v_mul_f32_e32 v108, v108, v147
	v_mul_f32_e32 v109, v109, v147
	v_add_u32_e32 v153, 0x26400, v153
	v_cvt_pk_bf16_f32 v164, v110, v111
	v_cvt_pk_bf16_f32 v165, v112, v113
	v_cvt_pk_bf16_f32 v166, v106, v107
	v_cvt_pk_bf16_f32 v167, v108, v109
	s_mov_b64 exec, s[24:25]
	global_store_dwordx4 v153, v[164:167], s[68:69]
	s_mov_b64 exec, -1
	v_mul_f32_e32 v102, v102, v147
	v_mul_f32_e32 v103, v103, v147
	v_mul_f32_e32 v104, v104, v147
	v_mul_f32_e32 v105, v105, v147
	v_mul_f32_e32 v98, v98, v147
	v_mul_f32_e32 v99, v99, v147
	v_mul_f32_e32 v100, v100, v147
	v_mul_f32_e32 v101, v101, v147
	v_cvt_pk_bf16_f32 v168, v102, v103
	v_cvt_pk_bf16_f32 v169, v104, v105
	v_cvt_pk_bf16_f32 v170, v98, v99
	v_cvt_pk_bf16_f32 v171, v100, v101
	s_mov_b64 exec, s[38:39]
	global_store_dwordx4 v153, v[168:171], s[68:69] offset:256
	s_mov_b64 exec, -1
	v_mul_f32_e32 v94, v94, v144
	v_mul_f32_e32 v95, v95, v144
	v_mul_f32_e32 v96, v96, v144
	v_mul_f32_e32 v97, v97, v144
	v_mul_f32_e32 v90, v90, v144
	v_mul_f32_e32 v91, v91, v144
	v_mul_f32_e32 v92, v92, v144
	v_mul_f32_e32 v93, v93, v144
	v_add_u32_e32 v153, 0x26400, v153
	v_cvt_pk_bf16_f32 v164, v94, v95
	v_cvt_pk_bf16_f32 v165, v96, v97
	v_cvt_pk_bf16_f32 v166, v90, v91
	v_cvt_pk_bf16_f32 v167, v92, v93
	s_mov_b64 exec, s[24:25]
	global_store_dwordx4 v153, v[164:167], s[68:69]
	s_mov_b64 exec, -1
	v_mul_f32_e32 v86, v86, v144
	v_mul_f32_e32 v87, v87, v144
	v_mul_f32_e32 v88, v88, v144
	v_mul_f32_e32 v89, v89, v144
	v_mul_f32_e32 v82, v82, v144
	v_mul_f32_e32 v83, v83, v144
	v_mul_f32_e32 v84, v84, v144
	v_mul_f32_e32 v85, v85, v144
	v_cvt_pk_bf16_f32 v168, v86, v87
	v_cvt_pk_bf16_f32 v169, v88, v89
	v_cvt_pk_bf16_f32 v170, v82, v83
	v_cvt_pk_bf16_f32 v171, v84, v85
	s_mov_b64 exec, s[38:39]
	global_store_dwordx4 v153, v[168:171], s[68:69] offset:256
; __device__ __forceinline__ u32x4 pack8(const float* f) { u32x4 o; o.x = pk2(f[0], f[1]); o.y = pk2(f[2], f[3]); o.z = pk2(f[4], f[5]); o.w = pk2(f[6], f[7]); return o; }
; __device__ __forceinline__ float sigmoidf_(float x) { return rcpf(1.0f + __expf(-x)); }
; __device__ __forceinline__ float gelu_tanh(float v) { const float u = 0.7978845608f * (v + 0.044715f * v * v * v); return v * rcpf(1.0f + __expf(-2.0f * u)); }
;     __device__ __forceinline__ void operator()(const f32x4 (&acc)[2][2][4][2], const Unit& u, int wr, int wc, int fr, int fq) const {
;     ...
;         for (int ai = 0; ai < 2; ++ai)
; #pragma unroll
;             for (int m = 0; m < 4; ++m) { const size_t row = (size_t)(row0 + ai * HALF + m * 16); const float rs = rsv[ai][m];
; #pragma unroll
;                 for (int bj = 0; bj < 2; ++bj) { float o[8];
;                     const int c0 = u.pn * BM + bj * HALF + wc * 32 + 8 * fq;
; #pragma unroll
;                     for (int n = 0; n < 2; ++n)
; #pragma unroll
;                         for (int j = 0; j < 4; ++j) { const float v = acc[ai][bj][m][n][j] * rs; o[n * 4 + j] = mode == 0 ? gelu_tanh(v) : (mode == 1 ? v : sigmoidf_(v)); }
;                     if (mode == 2) { unsigned w0 = 0u, w1 = 0u;
; #pragma unroll
;                         for (int j = 0; j < 4; ++j) { w0 = __builtin_amdgcn_cvt_pk_u8_f32(fmaxf(o[j] * 255.f, 1.f), j, w0); w1 = __builtin_amdgcn_cvt_pk_u8_f32(fmaxf(o[4 + j] * 255.f, 1.f), j, w1); }
;                         u32x2 wv; wv.x = w0; wv.y = w1; *(u32x2*)(gates + row * 4096 + (c0 - 5120)) = wv; }
;                     else if (c0 < PLD) *(u32x4*)(proj + row * PLD + c0) = pack8(o); } }
	s_mov_b64 exec, -1
	v_mul_f32_e32 v78, v78, v145
	v_mul_f32_e32 v79, v79, v145
	v_mul_f32_e32 v80, v80, v145
	v_mul_f32_e32 v81, v81, v145
	v_mul_f32_e32 v74, v74, v145
	v_mul_f32_e32 v75, v75, v145
	v_mul_f32_e32 v76, v76, v145
	v_mul_f32_e32 v77, v77, v145
	v_add_u32_e32 v153, 0x26400, v153
	v_cvt_pk_bf16_f32 v164, v78, v79
	v_cvt_pk_bf16_f32 v165, v80, v81
	v_cvt_pk_bf16_f32 v166, v74, v75
	v_cvt_pk_bf16_f32 v167, v76, v77
	s_mov_b64 exec, s[24:25]
	global_store_dwordx4 v153, v[164:167], s[68:69]
	s_mov_b64 exec, -1
	v_mul_f32_e32 v70, v70, v145
	v_mul_f32_e32 v71, v71, v145
	v_mul_f32_e32 v72, v72, v145
	v_mul_f32_e32 v73, v73, v145
	v_mul_f32_e32 v66, v66, v145
	v_mul_f32_e32 v67, v67, v145
	v_mul_f32_e32 v68, v68, v145
	v_mul_f32_e32 v69, v69, v145
	v_cvt_pk_bf16_f32 v168, v70, v71
	v_cvt_pk_bf16_f32 v169, v72, v73
	v_cvt_pk_bf16_f32 v170, v66, v67
	v_cvt_pk_bf16_f32 v171, v68, v69
	s_mov_b64 exec, s[38:39]
	global_store_dwordx4 v153, v[168:171], s[68:69] offset:256
	s_mov_b64 exec, -1
	v_mul_f32_e32 v62, v62, v142
	v_mul_f32_e32 v63, v63, v142
	v_mul_f32_e32 v64, v64, v142
	v_mul_f32_e32 v65, v65, v142
	v_mul_f32_e32 v58, v58, v142
	v_mul_f32_e32 v59, v59, v142
	v_mul_f32_e32 v60, v60, v142
	v_mul_f32_e32 v61, v61, v142
	v_add_u32_e32 v153, 0xbf400, v153
	v_cvt_pk_bf16_f32 v164, v62, v63
	v_cvt_pk_bf16_f32 v165, v64, v65
	v_cvt_pk_bf16_f32 v166, v58, v59
	v_cvt_pk_bf16_f32 v167, v60, v61
	s_mov_b64 exec, s[24:25]
	global_store_dwordx4 v153, v[164:167], s[68:69]
	s_mov_b64 exec, -1
	v_mul_f32_e32 v54, v54, v142
	v_mul_f32_e32 v55, v55, v142
	v_mul_f32_e32 v56, v56, v142
	v_mul_f32_e32 v57, v57, v142
	v_mul_f32_e32 v50, v50, v142
	v_mul_f32_e32 v51, v51, v142
	v_mul_f32_e32 v52, v52, v142
	v_mul_f32_e32 v53, v53, v142
	v_cvt_pk_bf16_f32 v168, v54, v55
	v_cvt_pk_bf16_f32 v169, v56, v57
	v_cvt_pk_bf16_f32 v170, v50, v51
	v_cvt_pk_bf16_f32 v171, v52, v53
	s_mov_b64 exec, s[38:39]
	global_store_dwordx4 v153, v[168:171], s[68:69] offset:256
	s_mov_b64 exec, -1
	v_mul_f32_e32 v46, v46, v143
	v_mul_f32_e32 v47, v47, v143
	v_mul_f32_e32 v48, v48, v143
	v_mul_f32_e32 v49, v49, v143
	v_mul_f32_e32 v42, v42, v143
	v_mul_f32_e32 v43, v43, v143
	v_mul_f32_e32 v44, v44, v143
	v_mul_f32_e32 v45, v45, v143
	v_add_u32_e32 v153, 0x26400, v153
	v_cvt_pk_bf16_f32 v164, v46, v47
	v_cvt_pk_bf16_f32 v165, v48, v49
	v_cvt_pk_bf16_f32 v166, v42, v43
	v_cvt_pk_bf16_f32 v167, v44, v45
	s_mov_b64 exec, s[24:25]
	global_store_dwordx4 v153, v[164:167], s[68:69]
	s_mov_b64 exec, -1
	v_mul_f32_e32 v38, v38, v143
	v_mul_f32_e32 v39, v39, v143
	v_mul_f32_e32 v40, v40, v143
	v_mul_f32_e32 v41, v41, v143
	v_mul_f32_e32 v34, v34, v143
	v_mul_f32_e32 v35, v35, v143
	v_mul_f32_e32 v36, v36, v143
	v_mul_f32_e32 v37, v37, v143
	v_cvt_pk_bf16_f32 v168, v38, v39
	v_cvt_pk_bf16_f32 v169, v40, v41
	v_cvt_pk_bf16_f32 v170, v34, v35
	v_cvt_pk_bf16_f32 v171, v36, v37
	s_mov_b64 exec, s[38:39]
	global_store_dwordx4 v153, v[168:171], s[68:69] offset:256
	s_mov_b64 exec, -1
	v_mul_f32_e32 v30, v30, v140
	v_mul_f32_e32 v31, v31, v140
	v_mul_f32_e32 v32, v32, v140
	v_mul_f32_e32 v33, v33, v140
	v_mul_f32_e32 v26, v26, v140
	v_mul_f32_e32 v27, v27, v140
	v_mul_f32_e32 v28, v28, v140
	v_mul_f32_e32 v29, v29, v140
	v_add_u32_e32 v153, 0x26400, v153
	v_cvt_pk_bf16_f32 v164, v30, v31
	v_cvt_pk_bf16_f32 v165, v32, v33
	v_cvt_pk_bf16_f32 v166, v26, v27
	v_cvt_pk_bf16_f32 v167, v28, v29
	s_mov_b64 exec, s[24:25]
	global_store_dwordx4 v153, v[164:167], s[68:69]
	s_mov_b64 exec, -1
	v_mul_f32_e32 v22, v22, v140
	v_mul_f32_e32 v23, v23, v140
	v_mul_f32_e32 v24, v24, v140
	v_mul_f32_e32 v25, v25, v140
	v_mul_f32_e32 v18, v18, v140
	v_mul_f32_e32 v19, v19, v140
	v_mul_f32_e32 v20, v20, v140
	v_mul_f32_e32 v21, v21, v140
	v_cvt_pk_bf16_f32 v168, v22, v23
	v_cvt_pk_bf16_f32 v169, v24, v25
	v_cvt_pk_bf16_f32 v170, v18, v19
	v_cvt_pk_bf16_f32 v171, v20, v21
	s_mov_b64 exec, s[38:39]
	global_store_dwordx4 v153, v[168:171], s[68:69] offset:256
	s_mov_b64 exec, -1
	v_mul_f32_e32 v14, v14, v141
	v_mul_f32_e32 v15, v15, v141
	v_mul_f32_e32 v16, v16, v141
	v_mul_f32_e32 v17, v17, v141
	v_mul_f32_e32 v10, v10, v141
	v_mul_f32_e32 v11, v11, v141
	v_mul_f32_e32 v12, v12, v141
	v_mul_f32_e32 v13, v13, v141
	v_add_u32_e32 v153, 0x26400, v153
	v_cvt_pk_bf16_f32 v164, v14, v15
	v_cvt_pk_bf16_f32 v165, v16, v17
	v_cvt_pk_bf16_f32 v166, v10, v11
	v_cvt_pk_bf16_f32 v167, v12, v13
	s_mov_b64 exec, s[24:25]
	global_store_dwordx4 v153, v[164:167], s[68:69]
	s_mov_b64 exec, -1
	v_mul_f32_e32 v6, v6, v141
	v_mul_f32_e32 v7, v7, v141
	v_mul_f32_e32 v8, v8, v141
	v_mul_f32_e32 v9, v9, v141
	v_mul_f32_e32 v2, v2, v141
	v_mul_f32_e32 v3, v3, v141
	v_mul_f32_e32 v4, v4, v141
	v_mul_f32_e32 v5, v5, v141
	v_cvt_pk_bf16_f32 v168, v6, v7
	v_cvt_pk_bf16_f32 v169, v8, v9
	v_cvt_pk_bf16_f32 v170, v2, v3
	v_cvt_pk_bf16_f32 v171, v4, v5
	s_mov_b64 exec, s[38:39]
	global_store_dwordx4 v153, v[168:171], s[68:69] offset:256
	s_mov_b64 exec, -1
	s_branch .Lmy_ip_done

;     __device__ bool next(int i, Unit& u) const { Unit b; if (!so.next(i >> 2, b)) return false; const int sub = i & 3; u.pm = b.pm; u.pn = sub * 4 + b.pn; u.acol = sub * 512; u.ord = i; return true; }
;     __device__ bool next(int i, Unit& u) const {
;         const long L = (long)i * G + c; if (L >= nwg) return false;
;         int wgid = (int)L; { const int q = nwg / NXCD, r = nwg % NXCD, xcd = wgid % NXCD, off = wgid / NXCD; wgid = (xcd < r ? xcd * (q + 1) : r * (q + 1) + (xcd - r) * q) + off; }
;         const int nig = WGM * nN, gid = wgid / nig, fm = gid * WGM, gsz = (nM - fm) < WGM ? (nM - fm) : WGM;
;         u.pm = fm + ((wgid % nig) % gsz); u.pn = (wgid % nig) / gsz; u.acol = 0; u.ord = i; return true;
; __device__ __forceinline__ float row_rstd(const float* rowsq, size_t row) {
;     const f32x4* q = (const f32x4*)(rowsq + row * 16); const f32x4 a = q[0], b = q[1], c = q[2], d = q[3];
;     const float s = ((a[0] + a[1]) + (a[2] + a[3])) + ((b[0] + b[1]) + (b[2] + b[3])) + ((c[0] + c[1]) + (c[2] + c[3])) + ((d[0] + d[1]) + (d[2] + d[3]));
;     return rsqrtf(s * (1.f / DM) + EPS);
.LBB0_2291:
	s_or_b64 exec, exec, s[0:1]
	v_readlane_b32 s0, v254, 5
	s_waitcnt lgkmcnt(0)
	s_barrier
	v_readlane_b32 s1, v254, 6
	s_ashr_i32 s34, s94, 31
	s_ashr_i32 s46, s71, 31
	v_writelane_b32 v254, s0, 5
	s_cmpk_lt_i32 s71, 0x580
	v_mov_b32_e32 v2, v216
	v_writelane_b32 v254, s1, 6
	s_cselect_b64 s[0:1], -1, 0
	s_cmpk_gt_i32 s71, 0x57f
	s_cbranch_scc1 .LBB0_2327
	v_readlane_b32 s2, v253, 37
	v_ashrrev_i32_e32 v3, 31, v2
	v_cmp_gt_i32_e64 s[36:37], s91, v2
	v_lshl_add_u32 v0, v2, 2, s2
	v_readlane_b32 s2, v251, 44
	v_lshlrev_b64 v[2:3], 6, v[2:3]
	v_readlane_b32 s3, v251, 45
	s_nop 1
	v_lshl_add_u64 v[2:3], s[2:3], 0, v[2:3]
	s_and_saveexec_b64 s[2:3], s[36:37]
	s_cbranch_execz .LBB0_2294
	s_lshr_b32 s24, s46, 29
	s_add_i32 s24, s71, s24
	s_and_b32 s25, s24, -8
	s_sub_i32 s25, s71, s25
	s_cmp_lt_i32 s25, 0
	s_movk_i32 s26, 0xb1
	s_cselect_b32 s26, s26, 0xb0
	s_mul_i32 s25, s25, s26
	s_ashr_i32 s24, s24, 3
	s_add_i32 s25, s25, s24
	s_mul_hi_i32 s24, s25, 0x2e8ba2e9
	s_lshr_b32 s26, s24, 31
	s_ashr_i32 s24, s24, 5
	s_add_i32 s24, s24, s26
	s_mul_i32 s26, s24, 0xb0
	s_lshl_b32 s24, s24, 3
	s_sub_i32 s25, s25, s26
	s_sub_i32 s26, 64, s24
	s_min_i32 s26, s26, 8
	s_abs_i32 s26, s26
	v_cvt_f32_u32_e32 v24, s26
	s_sub_i32 s28, 0, s26
	s_ashr_i32 s27, s25, 31
	s_abs_i32 s25, s25
	v_rcp_iflag_f32_e32 v24, v24
	s_nop 0
	v_mul_f32_e32 v24, 0x4f7ffffe, v24
	v_cvt_u32_f32_e32 v24, v24
	s_nop 0
	v_readfirstlane_b32 s29, v24
	s_mul_i32 s28, s28, s29
	s_mul_hi_u32 s28, s29, s28
	s_add_i32 s29, s29, s28
	s_mul_hi_u32 s28, s25, s29
	s_mul_i32 s28, s28, s26
	s_sub_i32 s25, s25, s28
	s_sub_i32 s28, s25, s26
	s_cmp_ge_u32 s25, s26
	s_cselect_b32 s25, s28, s25
	s_sub_i32 s28, s25, s26
	s_cmp_ge_u32 s25, s26
	s_cselect_b32 s25, s28, s25
	s_xor_b32 s25, s25, s27
	s_sub_i32 s25, s25, s27
	s_add_i32 s24, s25, s24
	s_ashr_i32 s25, s24, 31
	s_lshl_b64 s[24:25], s[24:25], 14
	v_lshl_add_u64 v[36:37], v[2:3], 0, s[24:25]
	global_load_dwordx4 v[24:27], v[36:37], off offset:48
	global_load_dwordx4 v[28:31], v[36:37], off offset:32
	global_load_dwordx4 v[32:35], v[36:37], off offset:16
	s_nop 0
	global_load_dwordx4 v[36:39], v[36:37], off
.LBB0_2294:
	s_or_b64 exec, exec, s[2:3]
	s_add_u32 s2, s94, s71
	s_addc_u32 s3, s34, s46
	v_cmp_gt_i64_e32 vcc, s[2:3], v[184:185]
	s_cbranch_vccnz .Lmy_rsc_0_c1
	s_and_saveexec_b64 s[24:25], s[36:37]
	s_cbranch_execz .LBB0_2297
	s_ashr_i32 s26, s2, 31
	s_lshr_b32 s26, s26, 29
	s_add_i32 s26, s2, s26
	s_ashr_i32 s27, s26, 3
	s_and_b32 s26, s26, -8
	s_sub_i32 s26, s2, s26
	s_cmp_lt_i32 s26, 0
	s_movk_i32 s28, 0xb1
	s_cselect_b32 s28, s28, 0xb0
	s_mul_i32 s26, s26, s28
	s_add_i32 s26, s26, s27
	s_mul_hi_i32 s27, s26, 0x2e8ba2e9
	s_lshr_b32 s28, s27, 31
	s_ashr_i32 s27, s27, 5
	s_add_i32 s27, s27, s28
	s_mul_i32 s28, s27, 0xb0
	s_lshl_b32 s27, s27, 3
	s_sub_i32 s26, s26, s28
	s_sub_i32 s28, 64, s27
	s_min_i32 s28, s28, 8
	s_abs_i32 s28, s28
	v_cvt_f32_u32_e32 v40, s28
	s_sub_i32 s30, 0, s28
	s_ashr_i32 s29, s26, 31
	s_abs_i32 s26, s26
	v_rcp_iflag_f32_e32 v40, v40
	s_nop 0
	v_mul_f32_e32 v40, 0x4f7ffffe, v40
	v_cvt_u32_f32_e32 v40, v40
	s_nop 0
	v_readfirstlane_b32 s31, v40
	s_mul_i32 s30, s30, s31
	s_mul_hi_u32 s30, s31, s30
	s_add_i32 s31, s31, s30
	s_mul_hi_u32 s30, s26, s31
	s_mul_i32 s30, s30, s28
	s_sub_i32 s26, s26, s30
	s_sub_i32 s30, s26, s28
	s_cmp_ge_u32 s26, s28
	s_cselect_b32 s26, s30, s26
	s_sub_i32 s30, s26, s28
	s_cmp_ge_u32 s26, s28
	s_cselect_b32 s26, s30, s26
	s_xor_b32 s26, s26, s29
	s_sub_i32 s26, s26, s29
	s_add_i32 s26, s26, s27
	s_ashr_i32 s27, s26, 31
	s_lshl_b64 s[26:27], s[26:27], 14
	v_lshl_add_u64 v[52:53], v[2:3], 0, s[26:27]
	global_load_dwordx4 v[40:43], v[52:53], off offset:48
	global_load_dwordx4 v[44:47], v[52:53], off offset:32
	global_load_dwordx4 v[48:51], v[52:53], off offset:16
	s_nop 0
	global_load_dwordx4 v[52:55], v[52:53], off
.LBB0_2297:
	s_or_b64 exec, exec, s[24:25]
	s_add_u32 s2, s2, s94
	s_addc_u32 s3, s3, s34
	v_cmp_gt_i64_e32 vcc, s[2:3], v[184:185]
	s_cbranch_vccnz .Lmy_rsc_0_c2
	s_and_saveexec_b64 s[24:25], s[36:37]
	s_cbranch_execz .LBB0_2300
	s_ashr_i32 s26, s2, 31
	s_lshr_b32 s26, s26, 29
	s_add_i32 s26, s2, s26
	s_ashr_i32 s27, s26, 3
	s_and_b32 s26, s26, -8
	s_sub_i32 s26, s2, s26
	s_cmp_lt_i32 s26, 0
	s_movk_i32 s28, 0xb1
	s_cselect_b32 s28, s28, 0xb0
	s_mul_i32 s26, s26, s28
	s_add_i32 s26, s26, s27
	s_mul_hi_i32 s27, s26, 0x2e8ba2e9
	s_lshr_b32 s28, s27, 31
	s_ashr_i32 s27, s27, 5
	s_add_i32 s27, s27, s28
	s_mul_i32 s28, s27, 0xb0
	s_lshl_b32 s27, s27, 3
	s_sub_i32 s26, s26, s28
	s_sub_i32 s28, 64, s27
	s_min_i32 s28, s28, 8
	s_abs_i32 s28, s28
	v_cvt_f32_u32_e32 v56, s28
	s_sub_i32 s30, 0, s28
	s_ashr_i32 s29, s26, 31
	s_abs_i32 s26, s26
	v_rcp_iflag_f32_e32 v56, v56
	s_nop 0
	v_mul_f32_e32 v56, 0x4f7ffffe, v56
	v_cvt_u32_f32_e32 v56, v56
	s_nop 0
	v_readfirstlane_b32 s31, v56
	s_mul_i32 s30, s30, s31
	s_mul_hi_u32 s30, s31, s30
	s_add_i32 s31, s31, s30
	s_mul_hi_u32 s30, s26, s31
	s_mul_i32 s30, s30, s28
	s_sub_i32 s26, s26, s30
	s_sub_i32 s30, s26, s28
	s_cmp_ge_u32 s26, s28
	s_cselect_b32 s26, s30, s26
	s_sub_i32 s30, s26, s28
	s_cmp_ge_u32 s26, s28
	s_cselect_b32 s26, s30, s26
	s_xor_b32 s26, s26, s29
	s_sub_i32 s26, s26, s29
	s_add_i32 s26, s26, s27
	s_ashr_i32 s27, s26, 31
	s_lshl_b64 s[26:27], s[26:27], 14
	v_lshl_add_u64 v[68:69], v[2:3], 0, s[26:27]
	global_load_dwordx4 v[56:59], v[68:69], off offset:48
	global_load_dwordx4 v[60:63], v[68:69], off offset:32
	global_load_dwordx4 v[64:67], v[68:69], off offset:16
	s_nop 0
	global_load_dwordx4 v[68:71], v[68:69], off
;     __device__ bool next(int i, Unit& u) const { Unit b; if (!so.next(i >> 2, b)) return false; const int sub = i & 3; u.pm = b.pm; u.pn = sub * 4 + b.pn; u.acol = sub * 512; u.ord = i; return true; }
;     __device__ bool next(int i, Unit& u) const {
;         const long L = (long)i * G + c; if (L >= nwg) return false;
;         int wgid = (int)L; { const int q = nwg / NXCD, r = nwg % NXCD, xcd = wgid % NXCD, off = wgid / NXCD; wgid = (xcd < r ? xcd * (q + 1) : r * (q + 1) + (xcd - r) * q) + off; }
;         const int nig = WGM * nN, gid = wgid / nig, fm = gid * WGM, gsz = (nM - fm) < WGM ? (nM - fm) : WGM;
;         u.pm = fm + ((wgid % nig) % gsz); u.pn = (wgid % nig) / gsz; u.acol = 0; u.ord = i; return true;
; __device__ __forceinline__ float row_rstd(const float* rowsq, size_t row) {
;     const f32x4* q = (const f32x4*)(rowsq + row * 16); const f32x4 a = q[0], b = q[1], c = q[2], d = q[3];
;     const float s = ((a[0] + a[1]) + (a[2] + a[3])) + ((b[0] + b[1]) + (b[2] + b[3])) + ((c[0] + c[1]) + (c[2] + c[3])) + ((d[0] + d[1]) + (d[2] + d[3]));
;     return rsqrtf(s * (1.f / DM) + EPS);
.LBB0_2300:
	s_or_b64 exec, exec, s[24:25]
	s_add_u32 s2, s2, s94
	s_addc_u32 s3, s3, s34
	v_cmp_gt_i64_e32 vcc, s[2:3], v[184:185]
	s_cbranch_vccnz .Lmy_rsc_0_c3
	s_and_saveexec_b64 s[24:25], s[36:37]
	s_cbranch_execz .LBB0_2303
	s_ashr_i32 s26, s2, 31
	s_lshr_b32 s26, s26, 29
	s_add_i32 s26, s2, s26
	s_ashr_i32 s27, s26, 3
	s_and_b32 s26, s26, -8
	s_sub_i32 s26, s2, s26
	s_cmp_lt_i32 s26, 0
	s_movk_i32 s28, 0xb1
	s_cselect_b32 s28, s28, 0xb0
	s_mul_i32 s26, s26, s28
	s_add_i32 s26, s26, s27
	s_mul_hi_i32 s27, s26, 0x2e8ba2e9
	s_lshr_b32 s28, s27, 31
	s_ashr_i32 s27, s27, 5
	s_add_i32 s27, s27, s28
	s_mul_i32 s28, s27, 0xb0
	s_lshl_b32 s27, s27, 3
	s_sub_i32 s26, s26, s28
	s_sub_i32 s28, 64, s27
	s_min_i32 s28, s28, 8
	s_abs_i32 s28, s28
	v_cvt_f32_u32_e32 v72, s28
	s_sub_i32 s30, 0, s28
	s_ashr_i32 s29, s26, 31
	s_abs_i32 s26, s26
	v_rcp_iflag_f32_e32 v72, v72
	s_nop 0
	v_mul_f32_e32 v72, 0x4f7ffffe, v72
	v_cvt_u32_f32_e32 v72, v72
	s_nop 0
	v_readfirstlane_b32 s31, v72
	s_mul_i32 s30, s30, s31
	s_mul_hi_u32 s30, s31, s30
	s_add_i32 s31, s31, s30
	s_mul_hi_u32 s30, s26, s31
	s_mul_i32 s30, s30, s28
	s_sub_i32 s26, s26, s30
	s_sub_i32 s30, s26, s28
	s_cmp_ge_u32 s26, s28
	s_cselect_b32 s26, s30, s26
	s_sub_i32 s30, s26, s28
	s_cmp_ge_u32 s26, s28
	s_cselect_b32 s26, s30, s26
	s_xor_b32 s26, s26, s29
	s_sub_i32 s26, s26, s29
	s_add_i32 s26, s26, s27
	s_ashr_i32 s27, s26, 31
	s_lshl_b64 s[26:27], s[26:27], 14
	v_lshl_add_u64 v[84:85], v[2:3], 0, s[26:27]
	global_load_dwordx4 v[72:75], v[84:85], off offset:48
	global_load_dwordx4 v[76:79], v[84:85], off offset:32
	global_load_dwordx4 v[80:83], v[84:85], off offset:16
	s_nop 0
	global_load_dwordx4 v[84:87], v[84:85], off
.LBB0_2303:
	s_or_b64 exec, exec, s[24:25]
	s_add_u32 s2, s2, s94
	s_addc_u32 s3, s3, s34
	v_cmp_gt_i64_e32 vcc, s[2:3], v[184:185]
	s_cbranch_vccnz .Lmy_rsc_0_c4
	s_and_saveexec_b64 s[24:25], s[36:37]
	s_cbranch_execz .LBB0_2306
	s_ashr_i32 s26, s2, 31
	s_lshr_b32 s26, s26, 29
	s_add_i32 s26, s2, s26
	s_ashr_i32 s27, s26, 3
	s_and_b32 s26, s26, -8
	s_sub_i32 s26, s2, s26
	s_cmp_lt_i32 s26, 0
	s_movk_i32 s28, 0xb1
	s_cselect_b32 s28, s28, 0xb0
	s_mul_i32 s26, s26, s28
	s_add_i32 s26, s26, s27
	s_mul_hi_i32 s27, s26, 0x2e8ba2e9
	s_lshr_b32 s28, s27, 31
	s_ashr_i32 s27, s27, 5
	s_add_i32 s27, s27, s28
	s_mul_i32 s28, s27, 0xb0
	s_lshl_b32 s27, s27, 3
	s_sub_i32 s26, s26, s28
	s_sub_i32 s28, 64, s27
	s_min_i32 s28, s28, 8
	s_abs_i32 s28, s28
	v_cvt_f32_u32_e32 v88, s28
	s_sub_i32 s30, 0, s28
	s_ashr_i32 s29, s26, 31
	s_abs_i32 s26, s26
	v_rcp_iflag_f32_e32 v88, v88
	s_nop 0
	v_mul_f32_e32 v88, 0x4f7ffffe, v88
	v_cvt_u32_f32_e32 v88, v88
	s_nop 0
	v_readfirstlane_b32 s31, v88
	s_mul_i32 s30, s30, s31
	s_mul_hi_u32 s30, s31, s30
	s_add_i32 s31, s31, s30
	s_mul_hi_u32 s30, s26, s31
	s_mul_i32 s30, s30, s28
	s_sub_i32 s26, s26, s30
	s_sub_i32 s30, s26, s28
	s_cmp_ge_u32 s26, s28
	s_cselect_b32 s26, s30, s26
	s_sub_i32 s30, s26, s28
	s_cmp_ge_u32 s26, s28
	s_cselect_b32 s26, s30, s26
	s_xor_b32 s26, s26, s29
	s_sub_i32 s26, s26, s29
	s_add_i32 s26, s26, s27
	s_ashr_i32 s27, s26, 31
	s_lshl_b64 s[26:27], s[26:27], 14
	v_lshl_add_u64 v[100:101], v[2:3], 0, s[26:27]
	global_load_dwordx4 v[88:91], v[100:101], off offset:48
	global_load_dwordx4 v[92:95], v[100:101], off offset:32
	global_load_dwordx4 v[96:99], v[100:101], off offset:16
	s_nop 0
	global_load_dwordx4 v[100:103], v[100:101], off
.LBB0_2306:
	s_or_b64 exec, exec, s[24:25]
	s_add_u32 s2, s2, s94
	s_addc_u32 s3, s3, s34
	v_cmp_gt_i64_e32 vcc, s[2:3], v[184:185]
	s_cbranch_vccnz .Lmy_rsc_0_c5
	s_and_saveexec_b64 s[24:25], s[36:37]
	s_cbranch_execz .LBB0_2309
	s_ashr_i32 s26, s2, 31
	s_lshr_b32 s26, s26, 29
	s_add_i32 s26, s2, s26
	s_ashr_i32 s27, s26, 3
	s_and_b32 s26, s26, -8
	s_sub_i32 s26, s2, s26
	s_cmp_lt_i32 s26, 0
	s_movk_i32 s28, 0xb1
	s_cselect_b32 s28, s28, 0xb0
	s_mul_i32 s26, s26, s28
	s_add_i32 s26, s26, s27
	s_mul_hi_i32 s27, s26, 0x2e8ba2e9
	s_lshr_b32 s28, s27, 31
	s_ashr_i32 s27, s27, 5
	s_add_i32 s27, s27, s28
	s_mul_i32 s28, s27, 0xb0
	s_lshl_b32 s27, s27, 3
	s_sub_i32 s26, s26, s28
	s_sub_i32 s28, 64, s27
	s_min_i32 s28, s28, 8
	s_abs_i32 s28, s28
	v_cvt_f32_u32_e32 v104, s28
	s_sub_i32 s30, 0, s28
	s_ashr_i32 s29, s26, 31
	s_abs_i32 s26, s26
	v_rcp_iflag_f32_e32 v104, v104
	s_nop 0
	v_mul_f32_e32 v104, 0x4f7ffffe, v104
	v_cvt_u32_f32_e32 v104, v104
	s_nop 0
	v_readfirstlane_b32 s31, v104
	s_mul_i32 s30, s30, s31
	s_mul_hi_u32 s30, s31, s30
	s_add_i32 s31, s31, s30
	s_mul_hi_u32 s30, s26, s31
	s_mul_i32 s30, s30, s28
	s_sub_i32 s26, s26, s30
	s_sub_i32 s30, s26, s28
	s_cmp_ge_u32 s26, s28
	s_cselect_b32 s26, s30, s26
	s_sub_i32 s30, s26, s28
	s_cmp_ge_u32 s26, s28
	s_cselect_b32 s26, s30, s26
	s_xor_b32 s26, s26, s29
	s_sub_i32 s26, s26, s29
	s_add_i32 s26, s26, s27
	s_ashr_i32 s27, s26, 31
	s_lshl_b64 s[26:27], s[26:27], 14
	v_lshl_add_u64 v[116:117], v[2:3], 0, s[26:27]
	global_load_dwordx4 v[104:107], v[116:117], off offset:48
	global_load_dwordx4 v[108:111], v[116:117], off offset:32
	global_load_dwordx4 v[112:115], v[116:117], off offset:16
	s_nop 0
	global_load_dwordx4 v[116:119], v[116:117], off
	s_or_b64 exec, exec, s[24:25]

;     __device__ bool next(int i, Unit& u) const { Unit b; if (!so.next(i >> 2, b)) return false; const int sub = i & 3; u.pm = b.pm; u.pn = sub * 4 + b.pn; u.acol = sub * 512; u.ord = i; return true; }
; __device__ __forceinline__ float row_rstd(const float* rowsq, size_t row) {
;     const f32x4* q = (const f32x4*)(rowsq + row * 16); const f32x4 a = q[0], b = q[1], c = q[2], d = q[3];
;     const float s = ((a[0] + a[1]) + (a[2] + a[3])) + ((b[0] + b[1]) + (b[2] + b[3])) + ((c[0] + c[1]) + (c[2] + c[3])) + ((d[0] + d[1]) + (d[2] + d[3]));
;     return rsqrtf(s * (1.f / DM) + EPS);
; }
; template <class Sched> __device__ __forceinline__ void rstd_prologue(const Sched& S, const float* rowsq, LAS float* rst) {
;     ...
;     for (int i = 0; i < 12 && S.next(i, u); ++i) if (t_ < 256) rst[i * 256 + t_] = pg8::row_rstd(rowsq, (size_t)u.pm * 256 + t_);
.Lmy_rsc_0_s0:
	s_or_b64 exec, exec, s[24:25]
.LBB0_2309:
	s_or_b64 exec, exec, s[24:25]
	s_add_u32 s2, s2, s94
	s_addc_u32 s3, s3, s34
	v_cmp_gt_i64_e32 vcc, s[2:3], v[184:185]
	s_cbranch_vccnz .LBB0_2327
	s_and_saveexec_b64 s[24:25], s[36:37]
	s_cbranch_execz .LBB0_2312
	s_ashr_i32 s26, s2, 31
	s_lshr_b32 s26, s26, 29
	s_add_i32 s26, s2, s26
	s_ashr_i32 s27, s26, 3
	s_and_b32 s26, s26, -8
	s_sub_i32 s26, s2, s26
	s_cmp_lt_i32 s26, 0
	s_movk_i32 s28, 0xb1
	s_cselect_b32 s28, s28, 0xb0
	s_mul_i32 s26, s26, s28
	s_add_i32 s26, s26, s27
	s_mul_hi_i32 s27, s26, 0x2e8ba2e9
	s_lshr_b32 s28, s27, 31
	s_ashr_i32 s27, s27, 5
	s_add_i32 s27, s27, s28
	s_mul_i32 s28, s27, 0xb0
	s_lshl_b32 s27, s27, 3
	s_sub_i32 s26, s26, s28
	s_sub_i32 s28, 64, s27
	s_min_i32 s28, s28, 8
	s_abs_i32 s28, s28
	v_cvt_f32_u32_e32 v4, s28
	s_sub_i32 s30, 0, s28
	s_ashr_i32 s29, s26, 31
	s_abs_i32 s26, s26
	v_rcp_iflag_f32_e32 v4, v4
	s_nop 0
	v_mul_f32_e32 v4, 0x4f7ffffe, v4
	v_cvt_u32_f32_e32 v4, v4
	s_nop 0
	v_readfirstlane_b32 s31, v4
	s_mul_i32 s30, s30, s31
	s_mul_hi_u32 s30, s31, s30
	s_add_i32 s31, s31, s30
	s_mul_hi_u32 s30, s26, s31
	s_mul_i32 s30, s30, s28
	s_sub_i32 s26, s26, s30
	s_sub_i32 s30, s26, s28
	s_cmp_ge_u32 s26, s28
	s_cselect_b32 s26, s30, s26
	s_sub_i32 s30, s26, s28
	s_cmp_ge_u32 s26, s28
	s_cselect_b32 s26, s30, s26
	s_xor_b32 s26, s26, s29
	s_sub_i32 s26, s26, s29
	s_add_i32 s26, s26, s27
	s_ashr_i32 s27, s26, 31
	s_lshl_b64 s[26:27], s[26:27], 14
	v_lshl_add_u64 v[16:17], v[2:3], 0, s[26:27]
	global_load_dwordx4 v[4:7], v[16:17], off offset:48
	global_load_dwordx4 v[8:11], v[16:17], off offset:32
	global_load_dwordx4 v[12:15], v[16:17], off offset:16
	s_nop 0
	global_load_dwordx4 v[16:19], v[16:17], off
	s_mov_b32 s26, 0x800000
	s_waitcnt vmcnt(2)
	v_add_f32_e32 v8, v8, v9
	v_add_f32_e32 v10, v10, v11
	s_waitcnt vmcnt(0)
	v_mov_b32_e32 v20, v17
	v_mov_b32_e32 v21, v18
	v_mov_b32_e32 v17, v19
	v_mov_b32_e32 v18, v13
	v_mov_b32_e32 v19, v14
	v_mov_b32_e32 v13, v15
	v_pk_add_f32 v[16:17], v[20:21], v[16:17]
	v_pk_add_f32 v[12:13], v[18:19], v[12:13]
	v_pk_add_f32 v[16:17], v[16:17], v[16:17] op_sel:[0,1] op_sel_hi:[1,0]
	v_pk_add_f32 v[12:13], v[12:13], v[12:13] op_sel:[0,1] op_sel_hi:[1,0]
	v_mov_b32_e32 v17, v4
	v_mov_b32_e32 v13, v5
	v_mov_b32_e32 v9, v6
	v_mov_b32_e32 v11, v7
	v_pk_add_f32 v[4:5], v[16:17], v[12:13]
	v_pk_add_f32 v[6:7], v[8:9], v[10:11]
	s_nop 0
	v_pk_add_f32 v[4:5], v[4:5], v[6:7]
	s_nop 0
	v_add_f32_e32 v4, v4, v5
	v_fmamk_f32 v4, v4, 0x3a800000, v218
	v_cmp_gt_f32_e32 vcc, s26, v4
	v_mul_f32_e32 v5, 0x4b800000, v4
	s_nop 0
	v_cndmask_b32_e32 v4, v4, v5, vcc
	v_rsq_f32_e32 v4, v4
	s_nop 0
	v_mul_f32_e32 v5, 0x45800000, v4
	v_cndmask_b32_e32 v4, v4, v5, vcc
	ds_write_b32 v0, v4 offset:6144
